# GEMM K-loops: priority raise moved ahead of the barrier, already-satisfied lgkmcnt wait after it and the mid-block setprio flip removed
# baseline (speedup 1.0000x reference)
; #define PG8_STAGE(bufoff, gbase, voff) do { _Pragma("unroll") for (int _i = 0; _i < 2; ++_i) \
;         __builtin_amdgcn_global_load_lds((const unsigned*)((const char*)(gbase) + (voff)[_i]), (PG8_LAS unsigned*)(lds + (bufoff) + ldsw + _i * 8192), 16, 0, 0); } while (0)
; #define PG8_LDA(dst, b, h) do { _Pragma("unroll") for (int m = 0; m < 4; ++m) _Pragma("unroll") for (int k = 0; k < 2; ++k) dst[m][k] = *(const PG8_LAS bf16x8*)(lds + PG8_SA(b, h) + aoff + m * 2048 + k * 1024); } while (0)
; #define PG8_LDB(dst, b, h) do { _Pragma("unroll") for (int n = 0; n < 2; ++n) _Pragma("unroll") for (int k = 0; k < 2; ++k) dst[n][k] = *(const PG8_LAS bf16x8*)(lds + PG8_SB(b, h) + boff + n * 2048 + k * 1024); } while (0)
; #define PG8_MMA(ai, bj, At, Bt) do { __builtin_amdgcn_s_setprio(1); _Pragma("unroll") for (int m = 0; m < 4; ++m) _Pragma("unroll") for (int n = 0; n < 2; ++n) _Pragma("unroll") for (int k = 0; k < 2; ++k) \
;         acc[ai][bj][m][n] = __builtin_amdgcn_mfma_f32_16x16x32_bf16(Bt[n][k], At[m][k], acc[ai][bj][m][n], 0, 0, 0); __builtin_amdgcn_s_setprio(0); } while (0)
; #define PG8_WAIT_V(n) asm volatile("s_waitcnt vmcnt(" #n ")" ::: "memory")
; #define PG8_WAIT_L(n) asm volatile("s_waitcnt lgkmcnt(" #n ")" ::: "memory")
; #define PG8_BAR __builtin_amdgcn_s_barrier()
; #define PG8_SCHED __builtin_amdgcn_sched_barrier(0)
; template <class Epi, class Sched, bool ALIGN_EPI = false, bool SP2 = false>
; __device__ __forceinline__ void gemm_phase(PG8_LAS unsigned char* lds, const Gemm g, const Sched& S, const Epi& E) {
;     ...
;             PG8_LDB(B0, 0, 0); PG8_LDB(B1, 0, 1); PG8_SCHED; PG8_LDA(At, 0, 0); PG8_STAGE(PG8_SA(1, 1), a1 + hstep, voffA);
;             PG8_WAIT_V(8); PG8_WAIT_L(0); PG8_BAR; PG8_MMA(0, 0, At, B0); PG8_MMA(0, 1, At, B1); PG8_BAR; PG8_SCHED;
;             PG8_LDA(At, 0, 1); PG8_STAGE(PG8_SB(0, 0), b2, voffB); PG8_STAGE(PG8_SB(0, 1), b2 + hstep, voffB); PG8_STAGE(PG8_SA(0, 0), a2, voffA);
;             PG8_WAIT_V(8); PG8_WAIT_L(0); PG8_BAR; PG8_MMA(1, 0, At, B0); PG8_MMA(1, 1, At, B1); PG8_BAR; PG8_SCHED;
.LBB0_67:
	ds_read_b128 v[128:131], v159
	ds_read_b128 v[152:155], v159 offset:1024
	ds_read_b128 v[162:165], v159 offset:2048
	ds_read_b128 v[166:169], v159 offset:3072
	ds_read_b128 v[170:173], v160
	ds_read_b128 v[174:177], v160 offset:1024
	ds_read_b128 v[178:181], v160 offset:2048
	ds_read_b128 v[182:185], v160 offset:3072
	s_add_i32 m0, s1, 0xc000
	ds_read_b128 v[186:189], v161
	ds_read_b128 v[190:193], v161 offset:1024
	ds_read_b128 v[194:197], v161 offset:2048
	ds_read_b128 v[200:203], v161 offset:3072
	ds_read_b128 v[204:207], v161 offset:4096
	ds_read_b128 v[208:211], v161 offset:5120
	ds_read_b128 v[212:215], v161 offset:6144
	ds_read_b128 v[216:219], v161 offset:7168
	global_load_lds_dwordx4 v144, s[74:75]
	s_add_i32 m0, s1, 0xe000
	s_nop 0
	global_load_lds_dwordx4 v146, s[74:75]
	s_add_u32 s76, s74, 0xfff80080
	s_addc_u32 s77, s75, -1
	s_cmp_eq_u32 s88, 28
	s_cselect_b32 s79, s5, s77
	s_cselect_b32 s78, s14, s76
	s_cselect_b32 s77, s24, s69
	s_cselect_b32 s76, s25, s67
	s_waitcnt vmcnt(8)
	s_waitcnt lgkmcnt(0)
	s_setprio 1
	s_barrier
	v_mfma_f32_16x16x32_bf16 v[124:127], v[128:131], v[186:189], v[124:127]
	v_mfma_f32_16x16x32_bf16 v[120:123], v[162:165], v[186:189], v[120:123]
	v_mfma_f32_16x16x32_bf16 v[108:111], v[128:131], v[194:197], v[108:111]
	v_mfma_f32_16x16x32_bf16 v[104:107], v[162:165], v[194:197], v[104:107]
	v_mfma_f32_16x16x32_bf16 v[92:95], v[128:131], v[204:207], v[92:95]
	v_mfma_f32_16x16x32_bf16 v[88:91], v[162:165], v[204:207], v[88:91]
	v_mfma_f32_16x16x32_bf16 v[76:79], v[128:131], v[212:215], v[76:79]
	v_mfma_f32_16x16x32_bf16 v[72:75], v[162:165], v[212:215], v[72:75]
	v_mfma_f32_16x16x32_bf16 v[124:127], v[152:155], v[190:193], v[124:127]
	v_mfma_f32_16x16x32_bf16 v[120:123], v[166:169], v[190:193], v[120:123]
	v_mfma_f32_16x16x32_bf16 v[108:111], v[152:155], v[200:203], v[108:111]
	v_mfma_f32_16x16x32_bf16 v[104:107], v[166:169], v[200:203], v[104:107]
	v_mfma_f32_16x16x32_bf16 v[92:95], v[152:155], v[208:211], v[92:95]
	v_mfma_f32_16x16x32_bf16 v[88:91], v[166:169], v[208:211], v[88:91]
	v_mfma_f32_16x16x32_bf16 v[76:79], v[152:155], v[216:219], v[76:79]
	v_mfma_f32_16x16x32_bf16 v[72:75], v[166:169], v[216:219], v[72:75]
	v_mfma_f32_16x16x32_bf16 v[116:119], v[170:173], v[186:189], v[116:119]
	v_mfma_f32_16x16x32_bf16 v[112:115], v[178:181], v[186:189], v[112:115]
	v_mfma_f32_16x16x32_bf16 v[100:103], v[170:173], v[194:197], v[100:103]
	v_mfma_f32_16x16x32_bf16 v[96:99], v[178:181], v[194:197], v[96:99]
	v_mfma_f32_16x16x32_bf16 v[84:87], v[170:173], v[204:207], v[84:87]
	v_mfma_f32_16x16x32_bf16 v[80:83], v[178:181], v[204:207], v[80:83]
	v_mfma_f32_16x16x32_bf16 v[68:71], v[170:173], v[212:215], v[68:71]
	v_mfma_f32_16x16x32_bf16 v[64:67], v[178:181], v[212:215], v[64:67]
	v_mfma_f32_16x16x32_bf16 v[116:119], v[174:177], v[190:193], v[116:119]
	v_mfma_f32_16x16x32_bf16 v[112:115], v[182:185], v[190:193], v[112:115]
	v_mfma_f32_16x16x32_bf16 v[100:103], v[174:177], v[200:203], v[100:103]
	v_mfma_f32_16x16x32_bf16 v[96:99], v[182:185], v[200:203], v[96:99]
	v_mfma_f32_16x16x32_bf16 v[84:87], v[174:177], v[208:211], v[84:87]
	v_mfma_f32_16x16x32_bf16 v[80:83], v[182:185], v[208:211], v[80:83]
	v_mfma_f32_16x16x32_bf16 v[68:71], v[174:177], v[216:219], v[68:71]
	v_mfma_f32_16x16x32_bf16 v[64:67], v[182:185], v[216:219], v[64:67]
	s_setprio 0
	s_barrier
	s_add_i32 s89, s85, s0
	s_mov_b32 m0, s89
	ds_read_b128 v[186:189], v161 offset:16384
	ds_read_b128 v[190:193], v161 offset:17408
	ds_read_b128 v[194:197], v161 offset:18432
	ds_read_b128 v[200:203], v161 offset:19456
	ds_read_b128 v[204:207], v161 offset:20480
	ds_read_b128 v[208:211], v161 offset:21504
	ds_read_b128 v[212:215], v161 offset:22528
	ds_read_b128 v[216:219], v161 offset:23552
	global_load_lds_dwordx4 v134, s[76:77]
	s_add_i32 m0, s89, 0x2000
	s_add_u32 s96, s76, 0x80000
	s_addc_u32 s97, s77, 0
	s_add_i32 s89, s86, s0
	global_load_lds_dwordx4 v138, s[76:77]
	s_mov_b32 m0, s89
	s_nop 0
	global_load_lds_dwordx4 v134, s[96:97]
	s_add_i32 m0, s89, 0x2000
	s_nop 0
	global_load_lds_dwordx4 v138, s[96:97]
	s_mov_b32 m0, s1
	s_nop 0
	global_load_lds_dwordx4 v132, s[78:79]
	s_mov_b32 m0, s11
	s_nop 0
	global_load_lds_dwordx4 v136, s[78:79]
	s_waitcnt vmcnt(8)
	s_waitcnt lgkmcnt(0)
	s_setprio 1
	s_barrier
	v_mfma_f32_16x16x32_bf16 v[60:63], v[128:131], v[186:189], v[60:63]
	v_mfma_f32_16x16x32_bf16 v[56:59], v[162:165], v[186:189], v[56:59]
	v_mfma_f32_16x16x32_bf16 v[44:47], v[128:131], v[194:197], v[44:47]
	v_mfma_f32_16x16x32_bf16 v[40:43], v[162:165], v[194:197], v[40:43]
	v_mfma_f32_16x16x32_bf16 v[28:31], v[128:131], v[204:207], v[28:31]
	v_mfma_f32_16x16x32_bf16 v[24:27], v[162:165], v[204:207], v[24:27]
	v_mfma_f32_16x16x32_bf16 v[12:15], v[128:131], v[212:215], v[12:15]
	v_mfma_f32_16x16x32_bf16 v[8:11], v[162:165], v[212:215], v[8:11]
	v_mfma_f32_16x16x32_bf16 v[60:63], v[152:155], v[190:193], v[60:63]
	v_mfma_f32_16x16x32_bf16 v[56:59], v[166:169], v[190:193], v[56:59]
	v_mfma_f32_16x16x32_bf16 v[44:47], v[152:155], v[200:203], v[44:47]
	v_mfma_f32_16x16x32_bf16 v[40:43], v[166:169], v[200:203], v[40:43]
	v_mfma_f32_16x16x32_bf16 v[28:31], v[152:155], v[208:211], v[28:31]
	v_mfma_f32_16x16x32_bf16 v[24:27], v[166:169], v[208:211], v[24:27]
	v_mfma_f32_16x16x32_bf16 v[12:15], v[152:155], v[216:219], v[12:15]
	v_mfma_f32_16x16x32_bf16 v[8:11], v[166:169], v[216:219], v[8:11]
	v_mfma_f32_16x16x32_bf16 v[52:55], v[170:173], v[186:189], v[52:55]
	v_mfma_f32_16x16x32_bf16 v[48:51], v[178:181], v[186:189], v[48:51]
	v_mfma_f32_16x16x32_bf16 v[36:39], v[170:173], v[194:197], v[36:39]
	v_mfma_f32_16x16x32_bf16 v[32:35], v[178:181], v[194:197], v[32:35]
	v_mfma_f32_16x16x32_bf16 v[20:23], v[170:173], v[204:207], v[20:23]
	v_mfma_f32_16x16x32_bf16 v[16:19], v[178:181], v[204:207], v[16:19]
	v_mfma_f32_16x16x32_bf16 v[4:7], v[170:173], v[212:215], v[4:7]
	v_mfma_f32_16x16x32_bf16 v[0:3], v[178:181], v[212:215], v[0:3]
	v_mfma_f32_16x16x32_bf16 v[52:55], v[174:177], v[190:193], v[52:55]
	v_mfma_f32_16x16x32_bf16 v[48:51], v[182:185], v[190:193], v[48:51]
	v_mfma_f32_16x16x32_bf16 v[36:39], v[174:177], v[200:203], v[36:39]
	v_mfma_f32_16x16x32_bf16 v[32:35], v[182:185], v[200:203], v[32:35]
	v_mfma_f32_16x16x32_bf16 v[20:23], v[174:177], v[208:211], v[20:23]
	v_mfma_f32_16x16x32_bf16 v[16:19], v[182:185], v[208:211], v[16:19]
	v_mfma_f32_16x16x32_bf16 v[4:7], v[174:177], v[216:219], v[4:7]
	v_mfma_f32_16x16x32_bf16 v[0:3], v[182:185], v[216:219], v[0:3]
	s_setprio 0
	s_barrier
; #define PG8_STAGE(bufoff, gbase, voff) do { _Pragma("unroll") for (int _i = 0; _i < 2; ++_i) \
;         __builtin_amdgcn_global_load_lds((const unsigned*)((const char*)(gbase) + (voff)[_i]), (PG8_LAS unsigned*)(lds + (bufoff) + ldsw + _i * 8192), 16, 0, 0); } while (0)
; #define PG8_LDA(dst, b, h) do { _Pragma("unroll") for (int m = 0; m < 4; ++m) _Pragma("unroll") for (int k = 0; k < 2; ++k) dst[m][k] = *(const PG8_LAS bf16x8*)(lds + PG8_SA(b, h) + aoff + m * 2048 + k * 1024); } while (0)
; #define PG8_LDB(dst, b, h) do { _Pragma("unroll") for (int n = 0; n < 2; ++n) _Pragma("unroll") for (int k = 0; k < 2; ++k) dst[n][k] = *(const PG8_LAS bf16x8*)(lds + PG8_SB(b, h) + boff + n * 2048 + k * 1024); } while (0)
; #define PG8_MMA(ai, bj, At, Bt) do { __builtin_amdgcn_s_setprio(1); _Pragma("unroll") for (int m = 0; m < 4; ++m) _Pragma("unroll") for (int n = 0; n < 2; ++n) _Pragma("unroll") for (int k = 0; k < 2; ++k) \
;         acc[ai][bj][m][n] = __builtin_amdgcn_mfma_f32_16x16x32_bf16(Bt[n][k], At[m][k], acc[ai][bj][m][n], 0, 0, 0); __builtin_amdgcn_s_setprio(0); } while (0)
; #define PG8_WAIT_V(n) asm volatile("s_waitcnt vmcnt(" #n ")" ::: "memory")
; #define PG8_WAIT_L(n) asm volatile("s_waitcnt lgkmcnt(" #n ")" ::: "memory")
; #define PG8_BAR __builtin_amdgcn_s_barrier()
; #define PG8_SCHED __builtin_amdgcn_sched_barrier(0)
; template <class Epi, class Sched, bool ALIGN_EPI = false, bool SP2 = false>
; __device__ __forceinline__ void gemm_phase(PG8_LAS unsigned char* lds, const Gemm g, const Sched& S, const Epi& E) {
;     ...
;             PG8_LDB(B0, 1, 0); PG8_LDB(B1, 1, 1); PG8_SCHED; PG8_LDA(At, 1, 0); PG8_STAGE(PG8_SA(0, 1), a2 + hstep, voffA);
;             PG8_WAIT_V(8); PG8_WAIT_L(0); PG8_BAR; PG8_MMA(0, 0, At, B0); PG8_MMA(0, 1, At, B1); PG8_BAR; PG8_SCHED;
;             PG8_LDA(At, 1, 1); PG8_STAGE(PG8_SB(1, 0), b3, voffB); PG8_STAGE(PG8_SB(1, 1), b3 + hstep, voffB); PG8_STAGE(PG8_SA(1, 0), a3, voffA);
;             PG8_WAIT_V(8); PG8_WAIT_L(0); PG8_BAR; PG8_MMA(1, 0, At, B0); PG8_MMA(1, 1, At, B1); PG8_BAR; PG8_SCHED;
;     ...
;         if constexpr (ALIGN_EPI) { if (wr == 0) PG8_BAR; }
	ds_read_b128 v[128:131], v198
	ds_read_b128 v[152:155], v198 offset:1024
	ds_read_b128 v[162:165], v198 offset:2048
	ds_read_b128 v[166:169], v198 offset:3072
	ds_read_b128 v[170:173], v199
	ds_read_b128 v[174:177], v199 offset:1024
	ds_read_b128 v[178:181], v199 offset:2048
	ds_read_b128 v[182:185], v199 offset:3072
	ds_read_b128 v[186:189], v161 offset:32768
	ds_read_b128 v[190:193], v161 offset:33792
	ds_read_b128 v[194:197], v161 offset:34816
	ds_read_b128 v[200:203], v161 offset:35840
	ds_read_b128 v[204:207], v161 offset:36864
	ds_read_b128 v[208:211], v161 offset:37888
	ds_read_b128 v[212:215], v161 offset:38912
	ds_read_b128 v[216:219], v161 offset:39936
	s_add_u32 s98, s78, 0x80000
	s_addc_u32 s99, s79, 0
	s_mov_b32 m0, s33
	s_add_u32 s100, s78, 0x80
	s_addc_u32 s101, s79, 0
	global_load_lds_dwordx4 v132, s[98:99]
	s_mov_b32 m0, s35
	s_nop 0
	global_load_lds_dwordx4 v136, s[98:99]
	s_add_i32 s89, 0, 0x18000
	s_add_i32 s94, 0, 0x1c000
	s_waitcnt vmcnt(8)
	s_waitcnt lgkmcnt(0)
	s_setprio 1
	s_barrier
	v_mfma_f32_16x16x32_bf16 v[124:127], v[128:131], v[186:189], v[124:127]
	v_mfma_f32_16x16x32_bf16 v[120:123], v[162:165], v[186:189], v[120:123]
	v_mfma_f32_16x16x32_bf16 v[108:111], v[128:131], v[194:197], v[108:111]
	v_mfma_f32_16x16x32_bf16 v[104:107], v[162:165], v[194:197], v[104:107]
	v_mfma_f32_16x16x32_bf16 v[92:95], v[128:131], v[204:207], v[92:95]
	v_mfma_f32_16x16x32_bf16 v[88:91], v[162:165], v[204:207], v[88:91]
	v_mfma_f32_16x16x32_bf16 v[76:79], v[128:131], v[212:215], v[76:79]
	v_mfma_f32_16x16x32_bf16 v[72:75], v[162:165], v[212:215], v[72:75]
	v_mfma_f32_16x16x32_bf16 v[124:127], v[152:155], v[190:193], v[124:127]
	v_mfma_f32_16x16x32_bf16 v[120:123], v[166:169], v[190:193], v[120:123]
	v_mfma_f32_16x16x32_bf16 v[108:111], v[152:155], v[200:203], v[108:111]
	v_mfma_f32_16x16x32_bf16 v[104:107], v[166:169], v[200:203], v[104:107]
	v_mfma_f32_16x16x32_bf16 v[92:95], v[152:155], v[208:211], v[92:95]
	v_mfma_f32_16x16x32_bf16 v[88:91], v[166:169], v[208:211], v[88:91]
	v_mfma_f32_16x16x32_bf16 v[76:79], v[152:155], v[216:219], v[76:79]
	v_mfma_f32_16x16x32_bf16 v[72:75], v[166:169], v[216:219], v[72:75]
	v_mfma_f32_16x16x32_bf16 v[116:119], v[170:173], v[186:189], v[116:119]
	v_mfma_f32_16x16x32_bf16 v[112:115], v[178:181], v[186:189], v[112:115]
	v_mfma_f32_16x16x32_bf16 v[100:103], v[170:173], v[194:197], v[100:103]
	v_mfma_f32_16x16x32_bf16 v[96:99], v[178:181], v[194:197], v[96:99]
	v_mfma_f32_16x16x32_bf16 v[84:87], v[170:173], v[204:207], v[84:87]
	v_mfma_f32_16x16x32_bf16 v[80:83], v[178:181], v[204:207], v[80:83]
	v_mfma_f32_16x16x32_bf16 v[68:71], v[170:173], v[212:215], v[68:71]
	v_mfma_f32_16x16x32_bf16 v[64:67], v[178:181], v[212:215], v[64:67]
	v_mfma_f32_16x16x32_bf16 v[116:119], v[174:177], v[190:193], v[116:119]
	v_mfma_f32_16x16x32_bf16 v[112:115], v[182:185], v[190:193], v[112:115]
	v_mfma_f32_16x16x32_bf16 v[100:103], v[174:177], v[200:203], v[100:103]
	v_mfma_f32_16x16x32_bf16 v[96:99], v[182:185], v[200:203], v[96:99]
	v_mfma_f32_16x16x32_bf16 v[84:87], v[174:177], v[208:211], v[84:87]
	v_mfma_f32_16x16x32_bf16 v[80:83], v[182:185], v[208:211], v[80:83]
	v_mfma_f32_16x16x32_bf16 v[68:71], v[174:177], v[216:219], v[68:71]
	v_mfma_f32_16x16x32_bf16 v[64:67], v[182:185], v[216:219], v[64:67]
	s_setprio 0
	s_barrier
	s_add_u32 s98, s76, 0x80
	s_addc_u32 s99, s77, 0
	s_add_i32 s78, s89, s0
	s_mov_b32 m0, s78
	ds_read_b128 v[186:189], v161 offset:49152
	ds_read_b128 v[190:193], v161 offset:50176
	ds_read_b128 v[194:197], v161 offset:51200
	ds_read_b128 v[200:203], v161 offset:52224
	ds_read_b128 v[204:207], v161 offset:53248
	ds_read_b128 v[208:211], v161 offset:54272
	ds_read_b128 v[212:215], v161 offset:55296
	ds_read_b128 v[216:219], v161 offset:56320
	global_load_lds_dwordx4 v134, s[98:99]
	s_add_i32 m0, s78, 0x2000
	s_add_u32 s76, s76, 0x80080
	s_addc_u32 s77, s77, 0
	s_add_i32 s78, s94, s0
	global_load_lds_dwordx4 v138, s[98:99]
	s_mov_b32 m0, s78
	s_nop 0
	global_load_lds_dwordx4 v134, s[76:77]
	s_add_i32 m0, s78, 0x2000
	s_nop 0
	global_load_lds_dwordx4 v138, s[76:77]
	s_mov_b32 m0, s80
	s_nop 0
	global_load_lds_dwordx4 v132, s[100:101]
	s_mov_b32 m0, s81
	s_nop 0
	global_load_lds_dwordx4 v136, s[100:101]
	s_waitcnt vmcnt(8)
	s_waitcnt lgkmcnt(0)
	s_setprio 1
	s_barrier
	v_mfma_f32_16x16x32_bf16 v[60:63], v[128:131], v[186:189], v[60:63]
	v_mfma_f32_16x16x32_bf16 v[56:59], v[162:165], v[186:189], v[56:59]
	v_mfma_f32_16x16x32_bf16 v[44:47], v[128:131], v[194:197], v[44:47]
	v_mfma_f32_16x16x32_bf16 v[40:43], v[162:165], v[194:197], v[40:43]
	v_mfma_f32_16x16x32_bf16 v[28:31], v[128:131], v[204:207], v[28:31]
	v_mfma_f32_16x16x32_bf16 v[24:27], v[162:165], v[204:207], v[24:27]
	v_mfma_f32_16x16x32_bf16 v[12:15], v[128:131], v[212:215], v[12:15]
	v_mfma_f32_16x16x32_bf16 v[8:11], v[162:165], v[212:215], v[8:11]
	v_mfma_f32_16x16x32_bf16 v[60:63], v[152:155], v[190:193], v[60:63]
	v_mfma_f32_16x16x32_bf16 v[56:59], v[166:169], v[190:193], v[56:59]
	v_mfma_f32_16x16x32_bf16 v[44:47], v[152:155], v[200:203], v[44:47]
	v_mfma_f32_16x16x32_bf16 v[40:43], v[166:169], v[200:203], v[40:43]
	v_mfma_f32_16x16x32_bf16 v[28:31], v[152:155], v[208:211], v[28:31]
	v_mfma_f32_16x16x32_bf16 v[24:27], v[166:169], v[208:211], v[24:27]
	v_mfma_f32_16x16x32_bf16 v[12:15], v[152:155], v[216:219], v[12:15]
	v_mfma_f32_16x16x32_bf16 v[8:11], v[166:169], v[216:219], v[8:11]
	v_mfma_f32_16x16x32_bf16 v[52:55], v[170:173], v[186:189], v[52:55]
	v_mfma_f32_16x16x32_bf16 v[48:51], v[178:181], v[186:189], v[48:51]
	v_mfma_f32_16x16x32_bf16 v[36:39], v[170:173], v[194:197], v[36:39]
	v_mfma_f32_16x16x32_bf16 v[32:35], v[178:181], v[194:197], v[32:35]
	v_mfma_f32_16x16x32_bf16 v[20:23], v[170:173], v[204:207], v[20:23]
	v_mfma_f32_16x16x32_bf16 v[16:19], v[178:181], v[204:207], v[16:19]
	v_mfma_f32_16x16x32_bf16 v[4:7], v[170:173], v[212:215], v[4:7]
	v_mfma_f32_16x16x32_bf16 v[0:3], v[178:181], v[212:215], v[0:3]
	v_mfma_f32_16x16x32_bf16 v[52:55], v[174:177], v[190:193], v[52:55]
	v_mfma_f32_16x16x32_bf16 v[48:51], v[182:185], v[190:193], v[48:51]
	v_mfma_f32_16x16x32_bf16 v[36:39], v[174:177], v[200:203], v[36:39]
	v_mfma_f32_16x16x32_bf16 v[32:35], v[182:185], v[200:203], v[32:35]
	v_mfma_f32_16x16x32_bf16 v[20:23], v[174:177], v[208:211], v[20:23]
	v_mfma_f32_16x16x32_bf16 v[16:19], v[182:185], v[208:211], v[16:19]
	v_mfma_f32_16x16x32_bf16 v[4:7], v[174:177], v[216:219], v[4:7]
	v_mfma_f32_16x16x32_bf16 v[0:3], v[182:185], v[216:219], v[0:3]
	s_setprio 0
	s_barrier
	s_add_i32 s88, s88, 2
	s_add_u32 s74, s74, 0x100
	s_addc_u32 s75, s75, 0
	s_add_u32 s67, s67, 0x100
	s_addc_u32 s69, s69, 0
	s_cmp_gt_u32 s88, 29
	s_cbranch_scc0 .LBB0_67
	s_and_b64 vcc, exec, s[60:61]
	s_cbranch_vccz .LBB0_70
	s_barrier

; #define PG8_STAGE(bufoff, gbase, voff) do { _Pragma("unroll") for (int _i = 0; _i < 2; ++_i) \
;         __builtin_amdgcn_global_load_lds((const unsigned*)((const char*)(gbase) + (voff)[_i]), (PG8_LAS unsigned*)(lds + (bufoff) + ldsw + _i * 8192), 16, 0, 0); } while (0)
; #define PG8_LDA(dst, b, h) do { _Pragma("unroll") for (int m = 0; m < 4; ++m) _Pragma("unroll") for (int k = 0; k < 2; ++k) dst[m][k] = *(const PG8_LAS bf16x8*)(lds + PG8_SA(b, h) + aoff + m * 2048 + k * 1024); } while (0)
; #define PG8_LDB(dst, b, h) do { _Pragma("unroll") for (int n = 0; n < 2; ++n) _Pragma("unroll") for (int k = 0; k < 2; ++k) dst[n][k] = *(const PG8_LAS bf16x8*)(lds + PG8_SB(b, h) + boff + n * 2048 + k * 1024); } while (0)
; #define PG8_MMA(ai, bj, At, Bt) do { __builtin_amdgcn_s_setprio(1); _Pragma("unroll") for (int m = 0; m < 4; ++m) _Pragma("unroll") for (int n = 0; n < 2; ++n) _Pragma("unroll") for (int k = 0; k < 2; ++k) \
;         acc[ai][bj][m][n] = __builtin_amdgcn_mfma_f32_16x16x32_bf16(Bt[n][k], At[m][k], acc[ai][bj][m][n], 0, 0, 0); __builtin_amdgcn_s_setprio(0); } while (0)
; #define PG8_WAIT_V(n) asm volatile("s_waitcnt vmcnt(" #n ")" ::: "memory")
; #define PG8_WAIT_L(n) asm volatile("s_waitcnt lgkmcnt(" #n ")" ::: "memory")
; #define PG8_BAR __builtin_amdgcn_s_barrier()
; #define PG8_SCHED __builtin_amdgcn_sched_barrier(0)
; template <class Epi, class Sched, bool ALIGN_EPI = false, bool SP2 = false>
; __device__ __forceinline__ void gemm_phase(PG8_LAS unsigned char* lds, const Gemm g, const Sched& S, const Epi& E) {
;     ...
;             PG8_LDB(B0, 0, 0); PG8_LDB(B1, 0, 1); PG8_SCHED; PG8_LDA(At, 0, 0); PG8_STAGE(PG8_SA(1, 1), a1 + hstep, voffA);
;             PG8_WAIT_V(8); PG8_WAIT_L(0); PG8_BAR; PG8_MMA(0, 0, At, B0); PG8_MMA(0, 1, At, B1); PG8_BAR; PG8_SCHED;
;             PG8_LDA(At, 0, 1); PG8_STAGE(PG8_SB(0, 0), b2, voffB); PG8_STAGE(PG8_SB(0, 1), b2 + hstep, voffB); PG8_STAGE(PG8_SA(0, 0), a2, voffA);
;             PG8_WAIT_V(8); PG8_WAIT_L(0); PG8_BAR; PG8_MMA(1, 0, At, B0); PG8_MMA(1, 1, At, B1); PG8_BAR; PG8_SCHED;
.LBB0_245:
	ds_read_b128 v[144:147], v153
	ds_read_b128 v[156:159], v153 offset:1024
	ds_read_b128 v[160:163], v153 offset:2048
	ds_read_b128 v[164:167], v153 offset:3072
	ds_read_b128 v[168:171], v154
	ds_read_b128 v[172:175], v154 offset:1024
	ds_read_b128 v[176:179], v154 offset:2048
	ds_read_b128 v[180:183], v154 offset:3072
	s_add_i32 m0, s33, 0xc000
	ds_read_b128 v[184:187], v155
	ds_read_b128 v[188:191], v155 offset:1024
	ds_read_b128 v[192:195], v155 offset:2048
	ds_read_b128 v[200:203], v155 offset:3072
	ds_read_b128 v[204:207], v155 offset:4096
	ds_read_b128 v[208:211], v155 offset:5120
	ds_read_b128 v[212:215], v155 offset:6144
	ds_read_b128 v[216:219], v155 offset:7168
	global_load_lds_dwordx4 v136, s[70:71]
	s_add_i32 m0, s33, 0xe000
	s_nop 0
	global_load_lds_dwordx4 v138, s[70:71]
	s_add_u32 s72, s70, 0xfff80080
	s_addc_u32 s73, s71, -1
	s_cmp_eq_u32 s87, 28
	s_cselect_b32 s75, s25, s73
	s_cselect_b32 s74, s63, s72
	s_cselect_b32 s73, s61, s86
	s_cselect_b32 s72, s84, s85
	s_waitcnt vmcnt(8)
	s_waitcnt lgkmcnt(0)
	s_setprio 1
	s_barrier
	v_mfma_f32_16x16x32_bf16 v[124:127], v[144:147], v[184:187], v[124:127]
	v_mfma_f32_16x16x32_bf16 v[120:123], v[160:163], v[184:187], v[120:123]
	v_mfma_f32_16x16x32_bf16 v[108:111], v[144:147], v[192:195], v[108:111]
	v_mfma_f32_16x16x32_bf16 v[104:107], v[160:163], v[192:195], v[104:107]
	v_mfma_f32_16x16x32_bf16 v[92:95], v[144:147], v[204:207], v[92:95]
	v_mfma_f32_16x16x32_bf16 v[88:91], v[160:163], v[204:207], v[88:91]
	v_mfma_f32_16x16x32_bf16 v[76:79], v[144:147], v[212:215], v[76:79]
	v_mfma_f32_16x16x32_bf16 v[72:75], v[160:163], v[212:215], v[72:75]
	v_mfma_f32_16x16x32_bf16 v[124:127], v[156:159], v[188:191], v[124:127]
	v_mfma_f32_16x16x32_bf16 v[120:123], v[164:167], v[188:191], v[120:123]
	v_mfma_f32_16x16x32_bf16 v[108:111], v[156:159], v[200:203], v[108:111]
	v_mfma_f32_16x16x32_bf16 v[104:107], v[164:167], v[200:203], v[104:107]
	v_mfma_f32_16x16x32_bf16 v[92:95], v[156:159], v[208:211], v[92:95]
	v_mfma_f32_16x16x32_bf16 v[88:91], v[164:167], v[208:211], v[88:91]
	v_mfma_f32_16x16x32_bf16 v[76:79], v[156:159], v[216:219], v[76:79]
	v_mfma_f32_16x16x32_bf16 v[72:75], v[164:167], v[216:219], v[72:75]
	v_mfma_f32_16x16x32_bf16 v[116:119], v[168:171], v[184:187], v[116:119]
	v_mfma_f32_16x16x32_bf16 v[112:115], v[176:179], v[184:187], v[112:115]
	v_mfma_f32_16x16x32_bf16 v[100:103], v[168:171], v[192:195], v[100:103]
	v_mfma_f32_16x16x32_bf16 v[96:99], v[176:179], v[192:195], v[96:99]
	v_mfma_f32_16x16x32_bf16 v[84:87], v[168:171], v[204:207], v[84:87]
	v_mfma_f32_16x16x32_bf16 v[80:83], v[176:179], v[204:207], v[80:83]
	v_mfma_f32_16x16x32_bf16 v[68:71], v[168:171], v[212:215], v[68:71]
	v_mfma_f32_16x16x32_bf16 v[64:67], v[176:179], v[212:215], v[64:67]
	v_mfma_f32_16x16x32_bf16 v[116:119], v[172:175], v[188:191], v[116:119]
	v_mfma_f32_16x16x32_bf16 v[112:115], v[180:183], v[188:191], v[112:115]
	v_mfma_f32_16x16x32_bf16 v[100:103], v[172:175], v[200:203], v[100:103]
	v_mfma_f32_16x16x32_bf16 v[96:99], v[180:183], v[200:203], v[96:99]
	v_mfma_f32_16x16x32_bf16 v[84:87], v[172:175], v[208:211], v[84:87]
	v_mfma_f32_16x16x32_bf16 v[80:83], v[180:183], v[208:211], v[80:83]
	v_mfma_f32_16x16x32_bf16 v[68:71], v[172:175], v[216:219], v[68:71]
	v_mfma_f32_16x16x32_bf16 v[64:67], v[180:183], v[216:219], v[64:67]
	s_setprio 0
	s_barrier
	s_add_i32 s88, s82, s1
	s_mov_b32 m0, s88
	ds_read_b128 v[184:187], v155 offset:16384
	ds_read_b128 v[188:191], v155 offset:17408
	ds_read_b128 v[192:195], v155 offset:18432
	ds_read_b128 v[200:203], v155 offset:19456
	ds_read_b128 v[204:207], v155 offset:20480
	ds_read_b128 v[208:211], v155 offset:21504
	ds_read_b128 v[212:215], v155 offset:22528
	ds_read_b128 v[216:219], v155 offset:23552
	global_load_lds_dwordx4 v130, s[72:73]
	s_add_i32 m0, s88, 0x2000
	s_add_u32 s88, s72, 0x80000
	s_addc_u32 s89, s73, 0
	s_add_i32 s94, s83, s1
	global_load_lds_dwordx4 v134, s[72:73]
	s_mov_b32 m0, s94
	s_nop 0
	global_load_lds_dwordx4 v130, s[88:89]
	s_add_i32 m0, s94, 0x2000
	s_nop 0
	global_load_lds_dwordx4 v134, s[88:89]
	s_mov_b32 m0, s33
	s_nop 0
	global_load_lds_dwordx4 v128, s[74:75]
	s_mov_b32 m0, s35
	s_nop 0
	global_load_lds_dwordx4 v132, s[74:75]
	s_waitcnt vmcnt(8)
	s_waitcnt lgkmcnt(0)
	s_setprio 1
	s_barrier
	v_mfma_f32_16x16x32_bf16 v[60:63], v[144:147], v[184:187], v[60:63]
	v_mfma_f32_16x16x32_bf16 v[56:59], v[160:163], v[184:187], v[56:59]
	v_mfma_f32_16x16x32_bf16 v[44:47], v[144:147], v[192:195], v[44:47]
	v_mfma_f32_16x16x32_bf16 v[40:43], v[160:163], v[192:195], v[40:43]
	v_mfma_f32_16x16x32_bf16 v[28:31], v[144:147], v[204:207], v[28:31]
	v_mfma_f32_16x16x32_bf16 v[24:27], v[160:163], v[204:207], v[24:27]
	v_mfma_f32_16x16x32_bf16 v[12:15], v[144:147], v[212:215], v[12:15]
	v_mfma_f32_16x16x32_bf16 v[8:11], v[160:163], v[212:215], v[8:11]
	v_mfma_f32_16x16x32_bf16 v[60:63], v[156:159], v[188:191], v[60:63]
	v_mfma_f32_16x16x32_bf16 v[56:59], v[164:167], v[188:191], v[56:59]
	v_mfma_f32_16x16x32_bf16 v[44:47], v[156:159], v[200:203], v[44:47]
	v_mfma_f32_16x16x32_bf16 v[40:43], v[164:167], v[200:203], v[40:43]
	v_mfma_f32_16x16x32_bf16 v[28:31], v[156:159], v[208:211], v[28:31]
	v_mfma_f32_16x16x32_bf16 v[24:27], v[164:167], v[208:211], v[24:27]
	v_mfma_f32_16x16x32_bf16 v[12:15], v[156:159], v[216:219], v[12:15]
	v_mfma_f32_16x16x32_bf16 v[8:11], v[164:167], v[216:219], v[8:11]
	v_mfma_f32_16x16x32_bf16 v[52:55], v[168:171], v[184:187], v[52:55]
	v_mfma_f32_16x16x32_bf16 v[48:51], v[176:179], v[184:187], v[48:51]
	v_mfma_f32_16x16x32_bf16 v[36:39], v[168:171], v[192:195], v[36:39]
	v_mfma_f32_16x16x32_bf16 v[32:35], v[176:179], v[192:195], v[32:35]
	v_mfma_f32_16x16x32_bf16 v[20:23], v[168:171], v[204:207], v[20:23]
	v_mfma_f32_16x16x32_bf16 v[16:19], v[176:179], v[204:207], v[16:19]
	v_mfma_f32_16x16x32_bf16 v[4:7], v[168:171], v[212:215], v[4:7]
	v_mfma_f32_16x16x32_bf16 v[0:3], v[176:179], v[212:215], v[0:3]
	v_mfma_f32_16x16x32_bf16 v[52:55], v[172:175], v[188:191], v[52:55]
	v_mfma_f32_16x16x32_bf16 v[48:51], v[180:183], v[188:191], v[48:51]
	v_mfma_f32_16x16x32_bf16 v[36:39], v[172:175], v[200:203], v[36:39]
	v_mfma_f32_16x16x32_bf16 v[32:35], v[180:183], v[200:203], v[32:35]
	v_mfma_f32_16x16x32_bf16 v[20:23], v[172:175], v[208:211], v[20:23]
	v_mfma_f32_16x16x32_bf16 v[16:19], v[180:183], v[208:211], v[16:19]
	v_mfma_f32_16x16x32_bf16 v[4:7], v[172:175], v[216:219], v[4:7]
	v_mfma_f32_16x16x32_bf16 v[0:3], v[180:183], v[216:219], v[0:3]
	s_setprio 0
	s_barrier
; #define PG8_STAGE(bufoff, gbase, voff) do { _Pragma("unroll") for (int _i = 0; _i < 2; ++_i) \
;         __builtin_amdgcn_global_load_lds((const unsigned*)((const char*)(gbase) + (voff)[_i]), (PG8_LAS unsigned*)(lds + (bufoff) + ldsw + _i * 8192), 16, 0, 0); } while (0)
; #define PG8_LDA(dst, b, h) do { _Pragma("unroll") for (int m = 0; m < 4; ++m) _Pragma("unroll") for (int k = 0; k < 2; ++k) dst[m][k] = *(const PG8_LAS bf16x8*)(lds + PG8_SA(b, h) + aoff + m * 2048 + k * 1024); } while (0)
; #define PG8_LDB(dst, b, h) do { _Pragma("unroll") for (int n = 0; n < 2; ++n) _Pragma("unroll") for (int k = 0; k < 2; ++k) dst[n][k] = *(const PG8_LAS bf16x8*)(lds + PG8_SB(b, h) + boff + n * 2048 + k * 1024); } while (0)
; #define PG8_MMA(ai, bj, At, Bt) do { __builtin_amdgcn_s_setprio(1); _Pragma("unroll") for (int m = 0; m < 4; ++m) _Pragma("unroll") for (int n = 0; n < 2; ++n) _Pragma("unroll") for (int k = 0; k < 2; ++k) \
;         acc[ai][bj][m][n] = __builtin_amdgcn_mfma_f32_16x16x32_bf16(Bt[n][k], At[m][k], acc[ai][bj][m][n], 0, 0, 0); __builtin_amdgcn_s_setprio(0); } while (0)
; #define PG8_WAIT_V(n) asm volatile("s_waitcnt vmcnt(" #n ")" ::: "memory")
; #define PG8_WAIT_L(n) asm volatile("s_waitcnt lgkmcnt(" #n ")" ::: "memory")
; #define PG8_BAR __builtin_amdgcn_s_barrier()
; #define PG8_SCHED __builtin_amdgcn_sched_barrier(0)
; template <class Epi, class Sched, bool ALIGN_EPI = false, bool SP2 = false>
; __device__ __forceinline__ void gemm_phase(PG8_LAS unsigned char* lds, const Gemm g, const Sched& S, const Epi& E) {
;     ...
;             PG8_LDB(B0, 1, 0); PG8_LDB(B1, 1, 1); PG8_SCHED; PG8_LDA(At, 1, 0); PG8_STAGE(PG8_SA(0, 1), a2 + hstep, voffA);
;             PG8_WAIT_V(8); PG8_WAIT_L(0); PG8_BAR; PG8_MMA(0, 0, At, B0); PG8_MMA(0, 1, At, B1); PG8_BAR; PG8_SCHED;
;             PG8_LDA(At, 1, 1); PG8_STAGE(PG8_SB(1, 0), b3, voffB); PG8_STAGE(PG8_SB(1, 1), b3 + hstep, voffB); PG8_STAGE(PG8_SA(1, 0), a3, voffA);
;             PG8_WAIT_V(8); PG8_WAIT_L(0); PG8_BAR; PG8_MMA(1, 0, At, B0); PG8_MMA(1, 1, At, B1); PG8_BAR; PG8_SCHED;
	ds_read_b128 v[144:147], v196
	ds_read_b128 v[156:159], v196 offset:1024
	ds_read_b128 v[160:163], v196 offset:2048
	ds_read_b128 v[164:167], v196 offset:3072
	ds_read_b128 v[168:171], v197
	ds_read_b128 v[172:175], v197 offset:1024
	ds_read_b128 v[176:179], v197 offset:2048
	ds_read_b128 v[180:183], v197 offset:3072
	ds_read_b128 v[184:187], v155 offset:32768
	ds_read_b128 v[188:191], v155 offset:33792
	ds_read_b128 v[192:195], v155 offset:34816
	ds_read_b128 v[200:203], v155 offset:35840
	ds_read_b128 v[204:207], v155 offset:36864
	ds_read_b128 v[208:211], v155 offset:37888
	ds_read_b128 v[212:215], v155 offset:38912
	ds_read_b128 v[216:219], v155 offset:39936
	s_add_u32 s98, s74, 0x80000
	s_addc_u32 s99, s75, 0
	s_mov_b32 m0, s69
	s_add_u32 s100, s74, 0x80
	s_addc_u32 s101, s75, 0
	global_load_lds_dwordx4 v128, s[98:99]
	s_mov_b32 m0, s76
	s_nop 0
	global_load_lds_dwordx4 v132, s[98:99]
	s_add_i32 s88, 0, 0x18000
	s_add_i32 s89, 0, 0x1c000
	s_waitcnt vmcnt(8)
	s_waitcnt lgkmcnt(0)
	s_setprio 1
	s_barrier
	v_mfma_f32_16x16x32_bf16 v[124:127], v[144:147], v[184:187], v[124:127]
	v_mfma_f32_16x16x32_bf16 v[120:123], v[160:163], v[184:187], v[120:123]
	v_mfma_f32_16x16x32_bf16 v[108:111], v[144:147], v[192:195], v[108:111]
	v_mfma_f32_16x16x32_bf16 v[104:107], v[160:163], v[192:195], v[104:107]
	v_mfma_f32_16x16x32_bf16 v[92:95], v[144:147], v[204:207], v[92:95]
	v_mfma_f32_16x16x32_bf16 v[88:91], v[160:163], v[204:207], v[88:91]
	v_mfma_f32_16x16x32_bf16 v[76:79], v[144:147], v[212:215], v[76:79]
	v_mfma_f32_16x16x32_bf16 v[72:75], v[160:163], v[212:215], v[72:75]
	v_mfma_f32_16x16x32_bf16 v[124:127], v[156:159], v[188:191], v[124:127]
	v_mfma_f32_16x16x32_bf16 v[120:123], v[164:167], v[188:191], v[120:123]
	v_mfma_f32_16x16x32_bf16 v[108:111], v[156:159], v[200:203], v[108:111]
	v_mfma_f32_16x16x32_bf16 v[104:107], v[164:167], v[200:203], v[104:107]
	v_mfma_f32_16x16x32_bf16 v[92:95], v[156:159], v[208:211], v[92:95]
	v_mfma_f32_16x16x32_bf16 v[88:91], v[164:167], v[208:211], v[88:91]
	v_mfma_f32_16x16x32_bf16 v[76:79], v[156:159], v[216:219], v[76:79]
	v_mfma_f32_16x16x32_bf16 v[72:75], v[164:167], v[216:219], v[72:75]
	v_mfma_f32_16x16x32_bf16 v[116:119], v[168:171], v[184:187], v[116:119]
	v_mfma_f32_16x16x32_bf16 v[112:115], v[176:179], v[184:187], v[112:115]
	v_mfma_f32_16x16x32_bf16 v[100:103], v[168:171], v[192:195], v[100:103]
	v_mfma_f32_16x16x32_bf16 v[96:99], v[176:179], v[192:195], v[96:99]
	v_mfma_f32_16x16x32_bf16 v[84:87], v[168:171], v[204:207], v[84:87]
	v_mfma_f32_16x16x32_bf16 v[80:83], v[176:179], v[204:207], v[80:83]
	v_mfma_f32_16x16x32_bf16 v[68:71], v[168:171], v[212:215], v[68:71]
	v_mfma_f32_16x16x32_bf16 v[64:67], v[176:179], v[212:215], v[64:67]
	v_mfma_f32_16x16x32_bf16 v[116:119], v[172:175], v[188:191], v[116:119]
	v_mfma_f32_16x16x32_bf16 v[112:115], v[180:183], v[188:191], v[112:115]
	v_mfma_f32_16x16x32_bf16 v[100:103], v[172:175], v[200:203], v[100:103]
	v_mfma_f32_16x16x32_bf16 v[96:99], v[180:183], v[200:203], v[96:99]
	v_mfma_f32_16x16x32_bf16 v[84:87], v[172:175], v[208:211], v[84:87]
	v_mfma_f32_16x16x32_bf16 v[80:83], v[180:183], v[208:211], v[80:83]
	v_mfma_f32_16x16x32_bf16 v[68:71], v[172:175], v[216:219], v[68:71]
	v_mfma_f32_16x16x32_bf16 v[64:67], v[180:183], v[216:219], v[64:67]
	s_setprio 0
	s_barrier
	s_add_u32 s98, s72, 0x80
	s_addc_u32 s99, s73, 0
	s_add_i32 s74, s88, s1
	s_mov_b32 m0, s74
	ds_read_b128 v[184:187], v155 offset:49152
	ds_read_b128 v[188:191], v155 offset:50176
	ds_read_b128 v[192:195], v155 offset:51200
	ds_read_b128 v[200:203], v155 offset:52224
	ds_read_b128 v[204:207], v155 offset:53248
	ds_read_b128 v[208:211], v155 offset:54272
	ds_read_b128 v[212:215], v155 offset:55296
	ds_read_b128 v[216:219], v155 offset:56320
	global_load_lds_dwordx4 v130, s[98:99]
	s_add_i32 m0, s74, 0x2000
	s_add_u32 s72, s72, 0x80080
	s_addc_u32 s73, s73, 0
	s_add_i32 s74, s89, s1
	global_load_lds_dwordx4 v134, s[98:99]
	s_mov_b32 m0, s74
	s_nop 0
	global_load_lds_dwordx4 v130, s[72:73]
	s_add_i32 m0, s74, 0x2000
	s_nop 0
	global_load_lds_dwordx4 v134, s[72:73]
	s_mov_b32 m0, s78
	s_nop 0
	global_load_lds_dwordx4 v128, s[100:101]
	s_mov_b32 m0, s79
	s_nop 0
	global_load_lds_dwordx4 v132, s[100:101]
	s_waitcnt vmcnt(8)
	s_waitcnt lgkmcnt(0)
	s_setprio 1
	s_barrier
	v_mfma_f32_16x16x32_bf16 v[60:63], v[144:147], v[184:187], v[60:63]
	v_mfma_f32_16x16x32_bf16 v[56:59], v[160:163], v[184:187], v[56:59]
	v_mfma_f32_16x16x32_bf16 v[44:47], v[144:147], v[192:195], v[44:47]
	v_mfma_f32_16x16x32_bf16 v[40:43], v[160:163], v[192:195], v[40:43]
	v_mfma_f32_16x16x32_bf16 v[28:31], v[144:147], v[204:207], v[28:31]
	v_mfma_f32_16x16x32_bf16 v[24:27], v[160:163], v[204:207], v[24:27]
	v_mfma_f32_16x16x32_bf16 v[12:15], v[144:147], v[212:215], v[12:15]
	v_mfma_f32_16x16x32_bf16 v[8:11], v[160:163], v[212:215], v[8:11]
	v_mfma_f32_16x16x32_bf16 v[60:63], v[156:159], v[188:191], v[60:63]
	v_mfma_f32_16x16x32_bf16 v[56:59], v[164:167], v[188:191], v[56:59]
	v_mfma_f32_16x16x32_bf16 v[44:47], v[156:159], v[200:203], v[44:47]
	v_mfma_f32_16x16x32_bf16 v[40:43], v[164:167], v[200:203], v[40:43]
	v_mfma_f32_16x16x32_bf16 v[28:31], v[156:159], v[208:211], v[28:31]
	v_mfma_f32_16x16x32_bf16 v[24:27], v[164:167], v[208:211], v[24:27]
	v_mfma_f32_16x16x32_bf16 v[12:15], v[156:159], v[216:219], v[12:15]
	v_mfma_f32_16x16x32_bf16 v[8:11], v[164:167], v[216:219], v[8:11]
	v_mfma_f32_16x16x32_bf16 v[52:55], v[168:171], v[184:187], v[52:55]
	v_mfma_f32_16x16x32_bf16 v[48:51], v[176:179], v[184:187], v[48:51]
	v_mfma_f32_16x16x32_bf16 v[36:39], v[168:171], v[192:195], v[36:39]
	v_mfma_f32_16x16x32_bf16 v[32:35], v[176:179], v[192:195], v[32:35]
	v_mfma_f32_16x16x32_bf16 v[20:23], v[168:171], v[204:207], v[20:23]
	v_mfma_f32_16x16x32_bf16 v[16:19], v[176:179], v[204:207], v[16:19]
	v_mfma_f32_16x16x32_bf16 v[4:7], v[168:171], v[212:215], v[4:7]
	v_mfma_f32_16x16x32_bf16 v[0:3], v[176:179], v[212:215], v[0:3]
	v_mfma_f32_16x16x32_bf16 v[52:55], v[172:175], v[188:191], v[52:55]
	v_mfma_f32_16x16x32_bf16 v[48:51], v[180:183], v[188:191], v[48:51]
	v_mfma_f32_16x16x32_bf16 v[36:39], v[172:175], v[200:203], v[36:39]
	v_mfma_f32_16x16x32_bf16 v[32:35], v[180:183], v[200:203], v[32:35]
	v_mfma_f32_16x16x32_bf16 v[20:23], v[172:175], v[208:211], v[20:23]
	v_mfma_f32_16x16x32_bf16 v[16:19], v[180:183], v[208:211], v[16:19]
	v_mfma_f32_16x16x32_bf16 v[4:7], v[172:175], v[216:219], v[4:7]
	v_mfma_f32_16x16x32_bf16 v[0:3], v[180:183], v[216:219], v[0:3]
	s_setprio 0
	s_barrier
	s_add_i32 s87, s87, 2
	s_add_u32 s70, s70, 0x100
	s_addc_u32 s71, s71, 0
	s_add_u32 s85, s85, 0x100
	s_addc_u32 s86, s86, 0
	s_cmp_gt_u32 s87, 29
	s_cbranch_scc0 .LBB0_245
	s_and_b64 vcc, exec, s[14:15]
	s_cbranch_vccz .LBB0_248
	s_barrier

; #define PG8_STAGE(bufoff, gbase, voff) do { _Pragma("unroll") for (int _i = 0; _i < 2; ++_i) \
;         __builtin_amdgcn_global_load_lds((const unsigned*)((const char*)(gbase) + (voff)[_i]), (PG8_LAS unsigned*)(lds + (bufoff) + ldsw + _i * 8192), 16, 0, 0); } while (0)
; #define PG8_LDA(dst, b, h) do { _Pragma("unroll") for (int m = 0; m < 4; ++m) _Pragma("unroll") for (int k = 0; k < 2; ++k) dst[m][k] = *(const PG8_LAS bf16x8*)(lds + PG8_SA(b, h) + aoff + m * 2048 + k * 1024); } while (0)
; #define PG8_LDB(dst, b, h) do { _Pragma("unroll") for (int n = 0; n < 2; ++n) _Pragma("unroll") for (int k = 0; k < 2; ++k) dst[n][k] = *(const PG8_LAS bf16x8*)(lds + PG8_SB(b, h) + boff + n * 2048 + k * 1024); } while (0)
; #define PG8_MMA(ai, bj, At, Bt) do { __builtin_amdgcn_s_setprio(1); _Pragma("unroll") for (int m = 0; m < 4; ++m) _Pragma("unroll") for (int n = 0; n < 2; ++n) _Pragma("unroll") for (int k = 0; k < 2; ++k) \
;         acc[ai][bj][m][n] = __builtin_amdgcn_mfma_f32_16x16x32_bf16(Bt[n][k], At[m][k], acc[ai][bj][m][n], 0, 0, 0); __builtin_amdgcn_s_setprio(0); } while (0)
; #define PG8_WAIT_V(n) asm volatile("s_waitcnt vmcnt(" #n ")" ::: "memory")
; #define PG8_WAIT_L(n) asm volatile("s_waitcnt lgkmcnt(" #n ")" ::: "memory")
; #define PG8_BAR __builtin_amdgcn_s_barrier()
; #define PG8_SCHED __builtin_amdgcn_sched_barrier(0)
; template <class Epi, class Sched, bool ALIGN_EPI = false, bool SP2 = false>
; __device__ __forceinline__ void gemm_phase(PG8_LAS unsigned char* lds, const Gemm g, const Sched& S, const Epi& E) {
;     ...
;             PG8_LDB(B0, 0, 0); PG8_LDB(B1, 0, 1); PG8_SCHED; PG8_LDA(At, 0, 0); PG8_STAGE(PG8_SA(1, 1), a1 + hstep, voffA);
;             PG8_WAIT_V(8); PG8_WAIT_L(0); PG8_BAR; PG8_MMA(0, 0, At, B0); PG8_MMA(0, 1, At, B1); PG8_BAR; PG8_SCHED;
;             PG8_LDA(At, 0, 1); PG8_STAGE(PG8_SB(0, 0), b2, voffB); PG8_STAGE(PG8_SB(0, 1), b2 + hstep, voffB); PG8_STAGE(PG8_SA(0, 0), a2, voffA);
;             PG8_WAIT_V(8); PG8_WAIT_L(0); PG8_BAR; PG8_MMA(1, 0, At, B0); PG8_MMA(1, 1, At, B1); PG8_BAR; PG8_SCHED;
.LBB0_376:
	ds_read_b128 v[152:155], v149
	ds_read_b128 v[156:159], v149 offset:1024
	ds_read_b128 v[160:163], v149 offset:2048
	ds_read_b128 v[164:167], v149 offset:3072
	ds_read_b128 v[168:171], v150
	ds_read_b128 v[172:175], v150 offset:1024
	ds_read_b128 v[176:179], v150 offset:2048
	ds_read_b128 v[180:183], v150 offset:3072
	s_add_i32 m0, s33, 0xc000
	ds_read_b128 v[184:187], v151
	ds_read_b128 v[188:191], v151 offset:1024
	ds_read_b128 v[192:195], v151 offset:2048
	ds_read_b128 v[200:203], v151 offset:3072
	ds_read_b128 v[204:207], v151 offset:4096
	ds_read_b128 v[208:211], v151 offset:5120
	ds_read_b128 v[212:215], v151 offset:6144
	ds_read_b128 v[216:219], v151 offset:7168
	global_load_lds_dwordx4 v136, s[68:69]
	s_add_i32 m0, s33, 0xe000
	s_nop 0
	global_load_lds_dwordx4 v138, s[68:69]
	s_add_u32 s70, s68, 0xfff80080
	s_addc_u32 s71, s69, -1
	s_cmp_eq_u32 s88, 28
	s_cselect_b32 s73, s25, s71
	s_cselect_b32 s72, s61, s70
	s_cselect_b32 s71, s49, s87
	s_cselect_b32 s70, s85, s86
	s_waitcnt vmcnt(8)
	s_waitcnt lgkmcnt(0)
	s_setprio 1
	s_barrier
	v_mfma_f32_16x16x32_bf16 v[124:127], v[152:155], v[184:187], v[124:127]
	v_mfma_f32_16x16x32_bf16 v[120:123], v[160:163], v[184:187], v[120:123]
	v_mfma_f32_16x16x32_bf16 v[108:111], v[152:155], v[192:195], v[108:111]
	v_mfma_f32_16x16x32_bf16 v[104:107], v[160:163], v[192:195], v[104:107]
	v_mfma_f32_16x16x32_bf16 v[92:95], v[152:155], v[204:207], v[92:95]
	v_mfma_f32_16x16x32_bf16 v[88:91], v[160:163], v[204:207], v[88:91]
	v_mfma_f32_16x16x32_bf16 v[76:79], v[152:155], v[212:215], v[76:79]
	v_mfma_f32_16x16x32_bf16 v[72:75], v[160:163], v[212:215], v[72:75]
	v_mfma_f32_16x16x32_bf16 v[124:127], v[156:159], v[188:191], v[124:127]
	v_mfma_f32_16x16x32_bf16 v[120:123], v[164:167], v[188:191], v[120:123]
	v_mfma_f32_16x16x32_bf16 v[108:111], v[156:159], v[200:203], v[108:111]
	v_mfma_f32_16x16x32_bf16 v[104:107], v[164:167], v[200:203], v[104:107]
	v_mfma_f32_16x16x32_bf16 v[92:95], v[156:159], v[208:211], v[92:95]
	v_mfma_f32_16x16x32_bf16 v[88:91], v[164:167], v[208:211], v[88:91]
	v_mfma_f32_16x16x32_bf16 v[76:79], v[156:159], v[216:219], v[76:79]
	v_mfma_f32_16x16x32_bf16 v[72:75], v[164:167], v[216:219], v[72:75]
	v_mfma_f32_16x16x32_bf16 v[116:119], v[168:171], v[184:187], v[116:119]
	v_mfma_f32_16x16x32_bf16 v[112:115], v[176:179], v[184:187], v[112:115]
	v_mfma_f32_16x16x32_bf16 v[100:103], v[168:171], v[192:195], v[100:103]
	v_mfma_f32_16x16x32_bf16 v[96:99], v[176:179], v[192:195], v[96:99]
	v_mfma_f32_16x16x32_bf16 v[84:87], v[168:171], v[204:207], v[84:87]
	v_mfma_f32_16x16x32_bf16 v[80:83], v[176:179], v[204:207], v[80:83]
	v_mfma_f32_16x16x32_bf16 v[68:71], v[168:171], v[212:215], v[68:71]
	v_mfma_f32_16x16x32_bf16 v[64:67], v[176:179], v[212:215], v[64:67]
	v_mfma_f32_16x16x32_bf16 v[116:119], v[172:175], v[188:191], v[116:119]
	v_mfma_f32_16x16x32_bf16 v[112:115], v[180:183], v[188:191], v[112:115]
	v_mfma_f32_16x16x32_bf16 v[100:103], v[172:175], v[200:203], v[100:103]
	v_mfma_f32_16x16x32_bf16 v[96:99], v[180:183], v[200:203], v[96:99]
	v_mfma_f32_16x16x32_bf16 v[84:87], v[172:175], v[208:211], v[84:87]
	v_mfma_f32_16x16x32_bf16 v[80:83], v[180:183], v[208:211], v[80:83]
	v_mfma_f32_16x16x32_bf16 v[68:71], v[172:175], v[216:219], v[68:71]
	v_mfma_f32_16x16x32_bf16 v[64:67], v[180:183], v[216:219], v[64:67]
	s_setprio 0
	s_barrier
	s_add_i32 s89, s80, s1
	s_mov_b32 m0, s89
	ds_read_b128 v[184:187], v151 offset:16384
	ds_read_b128 v[188:191], v151 offset:17408
	ds_read_b128 v[192:195], v151 offset:18432
	ds_read_b128 v[200:203], v151 offset:19456
	ds_read_b128 v[204:207], v151 offset:20480
	ds_read_b128 v[208:211], v151 offset:21504
	ds_read_b128 v[212:215], v151 offset:22528
	ds_read_b128 v[216:219], v151 offset:23552
	global_load_lds_dwordx4 v130, s[70:71]
	s_add_i32 m0, s89, 0x2000
	s_add_u32 s96, s70, 0x80000
	s_addc_u32 s97, s71, 0
	s_add_i32 s89, s81, s1
	global_load_lds_dwordx4 v134, s[70:71]
	s_mov_b32 m0, s89
	s_nop 0
	global_load_lds_dwordx4 v130, s[96:97]
	s_add_i32 m0, s89, 0x2000
	s_nop 0
	global_load_lds_dwordx4 v134, s[96:97]
	s_mov_b32 m0, s33
	s_nop 0
	global_load_lds_dwordx4 v128, s[72:73]
	s_mov_b32 m0, s35
	s_nop 0
	global_load_lds_dwordx4 v132, s[72:73]
	s_waitcnt vmcnt(8)
	s_waitcnt lgkmcnt(0)
	s_setprio 1
	s_barrier
	v_mfma_f32_16x16x32_bf16 v[60:63], v[152:155], v[184:187], v[60:63]
	v_mfma_f32_16x16x32_bf16 v[56:59], v[160:163], v[184:187], v[56:59]
	v_mfma_f32_16x16x32_bf16 v[44:47], v[152:155], v[192:195], v[44:47]
	v_mfma_f32_16x16x32_bf16 v[40:43], v[160:163], v[192:195], v[40:43]
	v_mfma_f32_16x16x32_bf16 v[28:31], v[152:155], v[204:207], v[28:31]
	v_mfma_f32_16x16x32_bf16 v[24:27], v[160:163], v[204:207], v[24:27]
	v_mfma_f32_16x16x32_bf16 v[12:15], v[152:155], v[212:215], v[12:15]
	v_mfma_f32_16x16x32_bf16 v[8:11], v[160:163], v[212:215], v[8:11]
	v_mfma_f32_16x16x32_bf16 v[60:63], v[156:159], v[188:191], v[60:63]
	v_mfma_f32_16x16x32_bf16 v[56:59], v[164:167], v[188:191], v[56:59]
	v_mfma_f32_16x16x32_bf16 v[44:47], v[156:159], v[200:203], v[44:47]
	v_mfma_f32_16x16x32_bf16 v[40:43], v[164:167], v[200:203], v[40:43]
	v_mfma_f32_16x16x32_bf16 v[28:31], v[156:159], v[208:211], v[28:31]
	v_mfma_f32_16x16x32_bf16 v[24:27], v[164:167], v[208:211], v[24:27]
	v_mfma_f32_16x16x32_bf16 v[12:15], v[156:159], v[216:219], v[12:15]
	v_mfma_f32_16x16x32_bf16 v[8:11], v[164:167], v[216:219], v[8:11]
	v_mfma_f32_16x16x32_bf16 v[52:55], v[168:171], v[184:187], v[52:55]
	v_mfma_f32_16x16x32_bf16 v[48:51], v[176:179], v[184:187], v[48:51]
	v_mfma_f32_16x16x32_bf16 v[36:39], v[168:171], v[192:195], v[36:39]
	v_mfma_f32_16x16x32_bf16 v[32:35], v[176:179], v[192:195], v[32:35]
	v_mfma_f32_16x16x32_bf16 v[20:23], v[168:171], v[204:207], v[20:23]
	v_mfma_f32_16x16x32_bf16 v[16:19], v[176:179], v[204:207], v[16:19]
	v_mfma_f32_16x16x32_bf16 v[4:7], v[168:171], v[212:215], v[4:7]
	v_mfma_f32_16x16x32_bf16 v[0:3], v[176:179], v[212:215], v[0:3]
	v_mfma_f32_16x16x32_bf16 v[52:55], v[172:175], v[188:191], v[52:55]
	v_mfma_f32_16x16x32_bf16 v[48:51], v[180:183], v[188:191], v[48:51]
	v_mfma_f32_16x16x32_bf16 v[36:39], v[172:175], v[200:203], v[36:39]
	v_mfma_f32_16x16x32_bf16 v[32:35], v[180:183], v[200:203], v[32:35]
	v_mfma_f32_16x16x32_bf16 v[20:23], v[172:175], v[208:211], v[20:23]
	v_mfma_f32_16x16x32_bf16 v[16:19], v[180:183], v[208:211], v[16:19]
	v_mfma_f32_16x16x32_bf16 v[4:7], v[172:175], v[216:219], v[4:7]
	v_mfma_f32_16x16x32_bf16 v[0:3], v[180:183], v[216:219], v[0:3]
	s_setprio 0
	s_barrier
; #define PG8_STAGE(bufoff, gbase, voff) do { _Pragma("unroll") for (int _i = 0; _i < 2; ++_i) \
;         __builtin_amdgcn_global_load_lds((const unsigned*)((const char*)(gbase) + (voff)[_i]), (PG8_LAS unsigned*)(lds + (bufoff) + ldsw + _i * 8192), 16, 0, 0); } while (0)
; #define PG8_LDA(dst, b, h) do { _Pragma("unroll") for (int m = 0; m < 4; ++m) _Pragma("unroll") for (int k = 0; k < 2; ++k) dst[m][k] = *(const PG8_LAS bf16x8*)(lds + PG8_SA(b, h) + aoff + m * 2048 + k * 1024); } while (0)
; #define PG8_LDB(dst, b, h) do { _Pragma("unroll") for (int n = 0; n < 2; ++n) _Pragma("unroll") for (int k = 0; k < 2; ++k) dst[n][k] = *(const PG8_LAS bf16x8*)(lds + PG8_SB(b, h) + boff + n * 2048 + k * 1024); } while (0)
; #define PG8_MMA(ai, bj, At, Bt) do { __builtin_amdgcn_s_setprio(1); _Pragma("unroll") for (int m = 0; m < 4; ++m) _Pragma("unroll") for (int n = 0; n < 2; ++n) _Pragma("unroll") for (int k = 0; k < 2; ++k) \
;         acc[ai][bj][m][n] = __builtin_amdgcn_mfma_f32_16x16x32_bf16(Bt[n][k], At[m][k], acc[ai][bj][m][n], 0, 0, 0); __builtin_amdgcn_s_setprio(0); } while (0)
; #define PG8_WAIT_V(n) asm volatile("s_waitcnt vmcnt(" #n ")" ::: "memory")
; #define PG8_WAIT_L(n) asm volatile("s_waitcnt lgkmcnt(" #n ")" ::: "memory")
; #define PG8_BAR __builtin_amdgcn_s_barrier()
; #define PG8_SCHED __builtin_amdgcn_sched_barrier(0)
; template <class Epi, class Sched, bool ALIGN_EPI = false, bool SP2 = false>
; __device__ __forceinline__ void gemm_phase(PG8_LAS unsigned char* lds, const Gemm g, const Sched& S, const Epi& E) {
;     ...
;             PG8_LDB(B0, 1, 0); PG8_LDB(B1, 1, 1); PG8_SCHED; PG8_LDA(At, 1, 0); PG8_STAGE(PG8_SA(0, 1), a2 + hstep, voffA);
;             PG8_WAIT_V(8); PG8_WAIT_L(0); PG8_BAR; PG8_MMA(0, 0, At, B0); PG8_MMA(0, 1, At, B1); PG8_BAR; PG8_SCHED;
;             PG8_LDA(At, 1, 1); PG8_STAGE(PG8_SB(1, 0), b3, voffB); PG8_STAGE(PG8_SB(1, 1), b3 + hstep, voffB); PG8_STAGE(PG8_SA(1, 0), a3, voffA);
;             PG8_WAIT_V(8); PG8_WAIT_L(0); PG8_BAR; PG8_MMA(1, 0, At, B0); PG8_MMA(1, 1, At, B1); PG8_BAR; PG8_SCHED;
	ds_read_b128 v[152:155], v196
	ds_read_b128 v[156:159], v196 offset:1024
	ds_read_b128 v[160:163], v196 offset:2048
	ds_read_b128 v[164:167], v196 offset:3072
	ds_read_b128 v[168:171], v197
	ds_read_b128 v[172:175], v197 offset:1024
	ds_read_b128 v[176:179], v197 offset:2048
	ds_read_b128 v[180:183], v197 offset:3072
	ds_read_b128 v[184:187], v151 offset:32768
	ds_read_b128 v[188:191], v151 offset:33792
	ds_read_b128 v[192:195], v151 offset:34816
	ds_read_b128 v[200:203], v151 offset:35840
	ds_read_b128 v[204:207], v151 offset:36864
	ds_read_b128 v[208:211], v151 offset:37888
	ds_read_b128 v[212:215], v151 offset:38912
	ds_read_b128 v[216:219], v151 offset:39936
	s_add_u32 s98, s72, 0x80000
	s_addc_u32 s99, s73, 0
	s_mov_b32 m0, s67
	s_add_u32 s100, s72, 0x80
	s_addc_u32 s101, s73, 0
	global_load_lds_dwordx4 v128, s[98:99]
	s_mov_b32 m0, s74
	s_nop 0
	global_load_lds_dwordx4 v132, s[98:99]
	s_add_i32 s89, 0, 0x18000
	s_add_i32 s94, 0, 0x1c000
	s_waitcnt vmcnt(8)
	s_waitcnt lgkmcnt(0)
	s_setprio 1
	s_barrier
	v_mfma_f32_16x16x32_bf16 v[124:127], v[152:155], v[184:187], v[124:127]
	v_mfma_f32_16x16x32_bf16 v[120:123], v[160:163], v[184:187], v[120:123]
	v_mfma_f32_16x16x32_bf16 v[108:111], v[152:155], v[192:195], v[108:111]
	v_mfma_f32_16x16x32_bf16 v[104:107], v[160:163], v[192:195], v[104:107]
	v_mfma_f32_16x16x32_bf16 v[92:95], v[152:155], v[204:207], v[92:95]
	v_mfma_f32_16x16x32_bf16 v[88:91], v[160:163], v[204:207], v[88:91]
	v_mfma_f32_16x16x32_bf16 v[76:79], v[152:155], v[212:215], v[76:79]
	v_mfma_f32_16x16x32_bf16 v[72:75], v[160:163], v[212:215], v[72:75]
	v_mfma_f32_16x16x32_bf16 v[124:127], v[156:159], v[188:191], v[124:127]
	v_mfma_f32_16x16x32_bf16 v[120:123], v[164:167], v[188:191], v[120:123]
	v_mfma_f32_16x16x32_bf16 v[108:111], v[156:159], v[200:203], v[108:111]
	v_mfma_f32_16x16x32_bf16 v[104:107], v[164:167], v[200:203], v[104:107]
	v_mfma_f32_16x16x32_bf16 v[92:95], v[156:159], v[208:211], v[92:95]
	v_mfma_f32_16x16x32_bf16 v[88:91], v[164:167], v[208:211], v[88:91]
	v_mfma_f32_16x16x32_bf16 v[76:79], v[156:159], v[216:219], v[76:79]
	v_mfma_f32_16x16x32_bf16 v[72:75], v[164:167], v[216:219], v[72:75]
	v_mfma_f32_16x16x32_bf16 v[116:119], v[168:171], v[184:187], v[116:119]
	v_mfma_f32_16x16x32_bf16 v[112:115], v[176:179], v[184:187], v[112:115]
	v_mfma_f32_16x16x32_bf16 v[100:103], v[168:171], v[192:195], v[100:103]
	v_mfma_f32_16x16x32_bf16 v[96:99], v[176:179], v[192:195], v[96:99]
	v_mfma_f32_16x16x32_bf16 v[84:87], v[168:171], v[204:207], v[84:87]
	v_mfma_f32_16x16x32_bf16 v[80:83], v[176:179], v[204:207], v[80:83]
	v_mfma_f32_16x16x32_bf16 v[68:71], v[168:171], v[212:215], v[68:71]
	v_mfma_f32_16x16x32_bf16 v[64:67], v[176:179], v[212:215], v[64:67]
	v_mfma_f32_16x16x32_bf16 v[116:119], v[172:175], v[188:191], v[116:119]
	v_mfma_f32_16x16x32_bf16 v[112:115], v[180:183], v[188:191], v[112:115]
	v_mfma_f32_16x16x32_bf16 v[100:103], v[172:175], v[200:203], v[100:103]
	v_mfma_f32_16x16x32_bf16 v[96:99], v[180:183], v[200:203], v[96:99]
	v_mfma_f32_16x16x32_bf16 v[84:87], v[172:175], v[208:211], v[84:87]
	v_mfma_f32_16x16x32_bf16 v[80:83], v[180:183], v[208:211], v[80:83]
	v_mfma_f32_16x16x32_bf16 v[68:71], v[172:175], v[216:219], v[68:71]
	v_mfma_f32_16x16x32_bf16 v[64:67], v[180:183], v[216:219], v[64:67]
	s_setprio 0
	s_barrier
	s_add_u32 s98, s70, 0x80
	s_addc_u32 s99, s71, 0
	s_add_i32 s72, s89, s1
	s_mov_b32 m0, s72
	ds_read_b128 v[184:187], v151 offset:49152
	ds_read_b128 v[188:191], v151 offset:50176
	ds_read_b128 v[192:195], v151 offset:51200
	ds_read_b128 v[200:203], v151 offset:52224
	ds_read_b128 v[204:207], v151 offset:53248
	ds_read_b128 v[208:211], v151 offset:54272
	ds_read_b128 v[212:215], v151 offset:55296
	ds_read_b128 v[216:219], v151 offset:56320
	global_load_lds_dwordx4 v130, s[98:99]
	s_add_i32 m0, s72, 0x2000
	s_add_u32 s70, s70, 0x80080
	s_addc_u32 s71, s71, 0
	s_add_i32 s72, s94, s1
	global_load_lds_dwordx4 v134, s[98:99]
	s_mov_b32 m0, s72
	s_nop 0
	global_load_lds_dwordx4 v130, s[70:71]
	s_add_i32 m0, s72, 0x2000
	s_nop 0
	global_load_lds_dwordx4 v134, s[70:71]
	s_mov_b32 m0, s76
	s_nop 0
	global_load_lds_dwordx4 v128, s[100:101]
	s_mov_b32 m0, s77
	s_nop 0
	global_load_lds_dwordx4 v132, s[100:101]
	s_waitcnt vmcnt(8)
	s_waitcnt lgkmcnt(0)
	s_setprio 1
	s_barrier
	v_mfma_f32_16x16x32_bf16 v[60:63], v[152:155], v[184:187], v[60:63]
	v_mfma_f32_16x16x32_bf16 v[56:59], v[160:163], v[184:187], v[56:59]
	v_mfma_f32_16x16x32_bf16 v[44:47], v[152:155], v[192:195], v[44:47]
	v_mfma_f32_16x16x32_bf16 v[40:43], v[160:163], v[192:195], v[40:43]
	v_mfma_f32_16x16x32_bf16 v[28:31], v[152:155], v[204:207], v[28:31]
	v_mfma_f32_16x16x32_bf16 v[24:27], v[160:163], v[204:207], v[24:27]
	v_mfma_f32_16x16x32_bf16 v[12:15], v[152:155], v[212:215], v[12:15]
	v_mfma_f32_16x16x32_bf16 v[8:11], v[160:163], v[212:215], v[8:11]
	v_mfma_f32_16x16x32_bf16 v[60:63], v[156:159], v[188:191], v[60:63]
	v_mfma_f32_16x16x32_bf16 v[56:59], v[164:167], v[188:191], v[56:59]
	v_mfma_f32_16x16x32_bf16 v[44:47], v[156:159], v[200:203], v[44:47]
	v_mfma_f32_16x16x32_bf16 v[40:43], v[164:167], v[200:203], v[40:43]
	v_mfma_f32_16x16x32_bf16 v[28:31], v[156:159], v[208:211], v[28:31]
	v_mfma_f32_16x16x32_bf16 v[24:27], v[164:167], v[208:211], v[24:27]
	v_mfma_f32_16x16x32_bf16 v[12:15], v[156:159], v[216:219], v[12:15]
	v_mfma_f32_16x16x32_bf16 v[8:11], v[164:167], v[216:219], v[8:11]
	v_mfma_f32_16x16x32_bf16 v[52:55], v[168:171], v[184:187], v[52:55]
	v_mfma_f32_16x16x32_bf16 v[48:51], v[176:179], v[184:187], v[48:51]
	v_mfma_f32_16x16x32_bf16 v[36:39], v[168:171], v[192:195], v[36:39]
	v_mfma_f32_16x16x32_bf16 v[32:35], v[176:179], v[192:195], v[32:35]
	v_mfma_f32_16x16x32_bf16 v[20:23], v[168:171], v[204:207], v[20:23]
	v_mfma_f32_16x16x32_bf16 v[16:19], v[176:179], v[204:207], v[16:19]
	v_mfma_f32_16x16x32_bf16 v[4:7], v[168:171], v[212:215], v[4:7]
	v_mfma_f32_16x16x32_bf16 v[0:3], v[176:179], v[212:215], v[0:3]
	v_mfma_f32_16x16x32_bf16 v[52:55], v[172:175], v[188:191], v[52:55]
	v_mfma_f32_16x16x32_bf16 v[48:51], v[180:183], v[188:191], v[48:51]
	v_mfma_f32_16x16x32_bf16 v[36:39], v[172:175], v[200:203], v[36:39]
	v_mfma_f32_16x16x32_bf16 v[32:35], v[180:183], v[200:203], v[32:35]
	v_mfma_f32_16x16x32_bf16 v[20:23], v[172:175], v[208:211], v[20:23]
	v_mfma_f32_16x16x32_bf16 v[16:19], v[180:183], v[208:211], v[16:19]
	v_mfma_f32_16x16x32_bf16 v[4:7], v[172:175], v[216:219], v[4:7]
	v_mfma_f32_16x16x32_bf16 v[0:3], v[180:183], v[216:219], v[0:3]
	s_setprio 0
	s_barrier
	s_add_i32 s88, s88, 2
	s_add_u32 s68, s68, 0x100
	s_addc_u32 s69, s69, 0
	s_add_u32 s86, s86, 0x100
	s_addc_u32 s87, s87, 0
	s_cmp_gt_u32 s88, 29
	s_cbranch_scc0 .LBB0_376
	s_and_b64 vcc, exec, s[14:15]
	s_cbranch_vccz .LBB0_379
	s_barrier

; #define PG8_STAGE(bufoff, gbase, voff) do { _Pragma("unroll") for (int _i = 0; _i < 2; ++_i) \
;         __builtin_amdgcn_global_load_lds((const unsigned*)((const char*)(gbase) + (voff)[_i]), (PG8_LAS unsigned*)(lds + (bufoff) + ldsw + _i * 8192), 16, 0, 0); } while (0)
; #define PG8_LDA(dst, b, h) do { _Pragma("unroll") for (int m = 0; m < 4; ++m) _Pragma("unroll") for (int k = 0; k < 2; ++k) dst[m][k] = *(const PG8_LAS bf16x8*)(lds + PG8_SA(b, h) + aoff + m * 2048 + k * 1024); } while (0)
; #define PG8_LDB(dst, b, h) do { _Pragma("unroll") for (int n = 0; n < 2; ++n) _Pragma("unroll") for (int k = 0; k < 2; ++k) dst[n][k] = *(const PG8_LAS bf16x8*)(lds + PG8_SB(b, h) + boff + n * 2048 + k * 1024); } while (0)
; #define PG8_MMA(ai, bj, At, Bt) do { __builtin_amdgcn_s_setprio(1); _Pragma("unroll") for (int m = 0; m < 4; ++m) _Pragma("unroll") for (int n = 0; n < 2; ++n) _Pragma("unroll") for (int k = 0; k < 2; ++k) \
;         acc[ai][bj][m][n] = __builtin_amdgcn_mfma_f32_16x16x32_bf16(Bt[n][k], At[m][k], acc[ai][bj][m][n], 0, 0, 0); __builtin_amdgcn_s_setprio(0); } while (0)
; #define PG8_WAIT_V(n) asm volatile("s_waitcnt vmcnt(" #n ")" ::: "memory")
; #define PG8_WAIT_L(n) asm volatile("s_waitcnt lgkmcnt(" #n ")" ::: "memory")
; #define PG8_BAR __builtin_amdgcn_s_barrier()
; #define PG8_SCHED __builtin_amdgcn_sched_barrier(0)
; template <class Epi, class Sched, bool ALIGN_EPI = false, bool SP2 = false>
; __device__ __forceinline__ void gemm_phase(PG8_LAS unsigned char* lds, const Gemm g, const Sched& S, const Epi& E) {
;     ...
;             PG8_LDB(B0, 0, 0); PG8_LDB(B1, 0, 1); PG8_SCHED; PG8_LDA(At, 0, 0); PG8_STAGE(PG8_SA(1, 1), a1 + hstep, voffA);
;             PG8_WAIT_V(8); PG8_WAIT_L(0); PG8_BAR; PG8_MMA(0, 0, At, B0); PG8_MMA(0, 1, At, B1); PG8_BAR; PG8_SCHED;
;             PG8_LDA(At, 0, 1); PG8_STAGE(PG8_SB(0, 0), b2, voffB); PG8_STAGE(PG8_SB(0, 1), b2 + hstep, voffB); PG8_STAGE(PG8_SA(0, 0), a2, voffA);
;             PG8_WAIT_V(8); PG8_WAIT_L(0); PG8_BAR; PG8_MMA(1, 0, At, B0); PG8_MMA(1, 1, At, B1); PG8_BAR; PG8_SCHED;
.LBB0_452:
	ds_read_b128 v[128:131], v202
	ds_read_b128 v[132:135], v202 offset:1024
	ds_read_b128 v[136:139], v202 offset:2048
	ds_read_b128 v[140:143], v202 offset:3072
	ds_read_b128 v[144:147], v203
	ds_read_b128 v[148:151], v203 offset:1024
	ds_read_b128 v[152:155], v203 offset:2048
	ds_read_b128 v[156:159], v203 offset:3072
	s_add_i32 m0, s33, 0xc000
	ds_read_b128 v[160:163], v204
	ds_read_b128 v[164:167], v204 offset:1024
	ds_read_b128 v[184:187], v204 offset:2048
	ds_read_b128 v[188:191], v204 offset:3072
	ds_read_b128 v[192:195], v204 offset:4096
	ds_read_b128 v[206:209], v204 offset:5120
	ds_read_b128 v[210:213], v204 offset:6144
	ds_read_b128 v[214:217], v204 offset:7168
	global_load_lds_dwordx4 v176, s[70:71]
	s_add_i32 m0, s33, 0xe000
	s_nop 0
	global_load_lds_dwordx4 v178, s[70:71]
	s_add_u32 s72, s70, 0xffe00080
	s_addc_u32 s73, s71, -1
	s_cmpk_eq_i32 s87, 0x7c
	s_cselect_b32 s75, s25, s73
	s_cselect_b32 s74, s63, s72
	s_cselect_b32 s73, s61, s86
	s_cselect_b32 s72, s84, s85
	s_waitcnt vmcnt(8)
	s_waitcnt lgkmcnt(0)
	s_setprio 1
	s_barrier
	v_mfma_f32_16x16x32_bf16 v[124:127], v[128:131], v[160:163], v[124:127]
	v_mfma_f32_16x16x32_bf16 v[120:123], v[136:139], v[160:163], v[120:123]
	v_mfma_f32_16x16x32_bf16 v[116:119], v[128:131], v[184:187], v[116:119]
	v_mfma_f32_16x16x32_bf16 v[108:111], v[136:139], v[184:187], v[108:111]
	v_mfma_f32_16x16x32_bf16 v[92:95], v[128:131], v[192:195], v[92:95]
	v_mfma_f32_16x16x32_bf16 v[88:91], v[136:139], v[192:195], v[88:91]
	v_mfma_f32_16x16x32_bf16 v[76:79], v[128:131], v[210:213], v[76:79]
	v_mfma_f32_16x16x32_bf16 v[72:75], v[136:139], v[210:213], v[72:75]
	v_mfma_f32_16x16x32_bf16 v[124:127], v[132:135], v[164:167], v[124:127]
	v_mfma_f32_16x16x32_bf16 v[120:123], v[140:143], v[164:167], v[120:123]
	v_mfma_f32_16x16x32_bf16 v[116:119], v[132:135], v[188:191], v[116:119]
	v_mfma_f32_16x16x32_bf16 v[108:111], v[140:143], v[188:191], v[108:111]
	v_mfma_f32_16x16x32_bf16 v[92:95], v[132:135], v[206:209], v[92:95]
	v_mfma_f32_16x16x32_bf16 v[88:91], v[140:143], v[206:209], v[88:91]
	v_mfma_f32_16x16x32_bf16 v[76:79], v[132:135], v[214:217], v[76:79]
	v_mfma_f32_16x16x32_bf16 v[72:75], v[140:143], v[214:217], v[72:75]
	v_mfma_f32_16x16x32_bf16 v[112:115], v[144:147], v[160:163], v[112:115]
	v_mfma_f32_16x16x32_bf16 v[104:107], v[152:155], v[160:163], v[104:107]
	v_mfma_f32_16x16x32_bf16 v[100:103], v[144:147], v[184:187], v[100:103]
	v_mfma_f32_16x16x32_bf16 v[96:99], v[152:155], v[184:187], v[96:99]
	v_mfma_f32_16x16x32_bf16 v[84:87], v[144:147], v[192:195], v[84:87]
	v_mfma_f32_16x16x32_bf16 v[80:83], v[152:155], v[192:195], v[80:83]
	v_mfma_f32_16x16x32_bf16 v[68:71], v[144:147], v[210:213], v[68:71]
	v_mfma_f32_16x16x32_bf16 v[64:67], v[152:155], v[210:213], v[64:67]
	v_mfma_f32_16x16x32_bf16 v[112:115], v[148:151], v[164:167], v[112:115]
	v_mfma_f32_16x16x32_bf16 v[104:107], v[156:159], v[164:167], v[104:107]
	v_mfma_f32_16x16x32_bf16 v[100:103], v[148:151], v[188:191], v[100:103]
	v_mfma_f32_16x16x32_bf16 v[96:99], v[156:159], v[188:191], v[96:99]
	v_mfma_f32_16x16x32_bf16 v[84:87], v[148:151], v[206:209], v[84:87]
	v_mfma_f32_16x16x32_bf16 v[80:83], v[156:159], v[206:209], v[80:83]
	v_mfma_f32_16x16x32_bf16 v[68:71], v[148:151], v[214:217], v[68:71]
	v_mfma_f32_16x16x32_bf16 v[64:67], v[156:159], v[214:217], v[64:67]
	s_setprio 0
	s_barrier
	s_add_i32 s88, s82, s1
	s_mov_b32 m0, s88
	ds_read_b128 v[160:163], v204 offset:16384
	ds_read_b128 v[164:167], v204 offset:17408
	ds_read_b128 v[184:187], v204 offset:18432
	ds_read_b128 v[188:191], v204 offset:19456
	ds_read_b128 v[192:195], v204 offset:20480
	ds_read_b128 v[206:209], v204 offset:21504
	ds_read_b128 v[210:213], v204 offset:22528
	ds_read_b128 v[214:217], v204 offset:23552
	global_load_lds_dwordx4 v170, s[72:73]
	s_add_i32 m0, s88, 0x2000
	s_add_u32 s88, s72, 0x200000
	s_addc_u32 s89, s73, 0
	s_add_i32 s94, s83, s1
	global_load_lds_dwordx4 v174, s[72:73]
	s_mov_b32 m0, s94
	s_nop 0
	global_load_lds_dwordx4 v170, s[88:89]
	s_add_i32 m0, s94, 0x2000
	s_nop 0
	global_load_lds_dwordx4 v174, s[88:89]
	s_mov_b32 m0, s33
	s_nop 0
	global_load_lds_dwordx4 v168, s[74:75]
	s_mov_b32 m0, s35
	s_nop 0
	global_load_lds_dwordx4 v172, s[74:75]
	s_waitcnt vmcnt(8)
	s_waitcnt lgkmcnt(0)
	s_setprio 1
	s_barrier
	v_mfma_f32_16x16x32_bf16 v[60:63], v[128:131], v[160:163], v[60:63]
	v_mfma_f32_16x16x32_bf16 v[56:59], v[136:139], v[160:163], v[56:59]
	v_mfma_f32_16x16x32_bf16 v[44:47], v[128:131], v[184:187], v[44:47]
	v_mfma_f32_16x16x32_bf16 v[40:43], v[136:139], v[184:187], v[40:43]
	v_mfma_f32_16x16x32_bf16 v[28:31], v[128:131], v[192:195], v[28:31]
	v_mfma_f32_16x16x32_bf16 v[24:27], v[136:139], v[192:195], v[24:27]
	v_mfma_f32_16x16x32_bf16 v[12:15], v[128:131], v[210:213], v[12:15]
	v_mfma_f32_16x16x32_bf16 v[8:11], v[136:139], v[210:213], v[8:11]
	v_mfma_f32_16x16x32_bf16 v[60:63], v[132:135], v[164:167], v[60:63]
	v_mfma_f32_16x16x32_bf16 v[56:59], v[140:143], v[164:167], v[56:59]
	v_mfma_f32_16x16x32_bf16 v[44:47], v[132:135], v[188:191], v[44:47]
	v_mfma_f32_16x16x32_bf16 v[40:43], v[140:143], v[188:191], v[40:43]
	v_mfma_f32_16x16x32_bf16 v[28:31], v[132:135], v[206:209], v[28:31]
	v_mfma_f32_16x16x32_bf16 v[24:27], v[140:143], v[206:209], v[24:27]
	v_mfma_f32_16x16x32_bf16 v[12:15], v[132:135], v[214:217], v[12:15]
	v_mfma_f32_16x16x32_bf16 v[8:11], v[140:143], v[214:217], v[8:11]
	v_mfma_f32_16x16x32_bf16 v[52:55], v[144:147], v[160:163], v[52:55]
	v_mfma_f32_16x16x32_bf16 v[48:51], v[152:155], v[160:163], v[48:51]
	v_mfma_f32_16x16x32_bf16 v[36:39], v[144:147], v[184:187], v[36:39]
	v_mfma_f32_16x16x32_bf16 v[32:35], v[152:155], v[184:187], v[32:35]
	v_mfma_f32_16x16x32_bf16 v[20:23], v[144:147], v[192:195], v[20:23]
	v_mfma_f32_16x16x32_bf16 v[16:19], v[152:155], v[192:195], v[16:19]
	v_mfma_f32_16x16x32_bf16 v[4:7], v[144:147], v[210:213], v[4:7]
	v_mfma_f32_16x16x32_bf16 v[0:3], v[152:155], v[210:213], v[0:3]
	v_mfma_f32_16x16x32_bf16 v[52:55], v[148:151], v[164:167], v[52:55]
	v_mfma_f32_16x16x32_bf16 v[48:51], v[156:159], v[164:167], v[48:51]
	v_mfma_f32_16x16x32_bf16 v[36:39], v[148:151], v[188:191], v[36:39]
	v_mfma_f32_16x16x32_bf16 v[32:35], v[156:159], v[188:191], v[32:35]
	v_mfma_f32_16x16x32_bf16 v[20:23], v[148:151], v[206:209], v[20:23]
	v_mfma_f32_16x16x32_bf16 v[16:19], v[156:159], v[206:209], v[16:19]
	v_mfma_f32_16x16x32_bf16 v[4:7], v[148:151], v[214:217], v[4:7]
	v_mfma_f32_16x16x32_bf16 v[0:3], v[156:159], v[214:217], v[0:3]
	s_setprio 0
	s_barrier
; #define PG8_STAGE(bufoff, gbase, voff) do { _Pragma("unroll") for (int _i = 0; _i < 2; ++_i) \
;         __builtin_amdgcn_global_load_lds((const unsigned*)((const char*)(gbase) + (voff)[_i]), (PG8_LAS unsigned*)(lds + (bufoff) + ldsw + _i * 8192), 16, 0, 0); } while (0)
; #define PG8_LDA(dst, b, h) do { _Pragma("unroll") for (int m = 0; m < 4; ++m) _Pragma("unroll") for (int k = 0; k < 2; ++k) dst[m][k] = *(const PG8_LAS bf16x8*)(lds + PG8_SA(b, h) + aoff + m * 2048 + k * 1024); } while (0)
; #define PG8_LDB(dst, b, h) do { _Pragma("unroll") for (int n = 0; n < 2; ++n) _Pragma("unroll") for (int k = 0; k < 2; ++k) dst[n][k] = *(const PG8_LAS bf16x8*)(lds + PG8_SB(b, h) + boff + n * 2048 + k * 1024); } while (0)
; #define PG8_MMA(ai, bj, At, Bt) do { __builtin_amdgcn_s_setprio(1); _Pragma("unroll") for (int m = 0; m < 4; ++m) _Pragma("unroll") for (int n = 0; n < 2; ++n) _Pragma("unroll") for (int k = 0; k < 2; ++k) \
;         acc[ai][bj][m][n] = __builtin_amdgcn_mfma_f32_16x16x32_bf16(Bt[n][k], At[m][k], acc[ai][bj][m][n], 0, 0, 0); __builtin_amdgcn_s_setprio(0); } while (0)
; #define PG8_WAIT_V(n) asm volatile("s_waitcnt vmcnt(" #n ")" ::: "memory")
; #define PG8_WAIT_L(n) asm volatile("s_waitcnt lgkmcnt(" #n ")" ::: "memory")
; #define PG8_BAR __builtin_amdgcn_s_barrier()
; #define PG8_SCHED __builtin_amdgcn_sched_barrier(0)
; template <class Epi, class Sched, bool ALIGN_EPI = false, bool SP2 = false>
; __device__ __forceinline__ void gemm_phase(PG8_LAS unsigned char* lds, const Gemm g, const Sched& S, const Epi& E) {
;     ...
;             PG8_LDB(B0, 1, 0); PG8_LDB(B1, 1, 1); PG8_SCHED; PG8_LDA(At, 1, 0); PG8_STAGE(PG8_SA(0, 1), a2 + hstep, voffA);
;             PG8_WAIT_V(8); PG8_WAIT_L(0); PG8_BAR; PG8_MMA(0, 0, At, B0); PG8_MMA(0, 1, At, B1); PG8_BAR; PG8_SCHED;
;             PG8_LDA(At, 1, 1); PG8_STAGE(PG8_SB(1, 0), b3, voffB); PG8_STAGE(PG8_SB(1, 1), b3 + hstep, voffB); PG8_STAGE(PG8_SA(1, 0), a3, voffA);
;             PG8_WAIT_V(8); PG8_WAIT_L(0); PG8_BAR; PG8_MMA(1, 0, At, B0); PG8_MMA(1, 1, At, B1); PG8_BAR; PG8_SCHED;
	ds_read_b128 v[128:131], v218
	ds_read_b128 v[132:135], v218 offset:1024
	ds_read_b128 v[136:139], v218 offset:2048
	ds_read_b128 v[140:143], v218 offset:3072
	ds_read_b128 v[144:147], v219
	ds_read_b128 v[148:151], v219 offset:1024
	ds_read_b128 v[152:155], v219 offset:2048
	ds_read_b128 v[156:159], v219 offset:3072
	ds_read_b128 v[160:163], v204 offset:32768
	ds_read_b128 v[164:167], v204 offset:33792
	ds_read_b128 v[184:187], v204 offset:34816
	ds_read_b128 v[188:191], v204 offset:35840
	ds_read_b128 v[192:195], v204 offset:36864
	ds_read_b128 v[206:209], v204 offset:37888
	ds_read_b128 v[210:213], v204 offset:38912
	ds_read_b128 v[214:217], v204 offset:39936
	s_add_u32 s98, s74, 0x200000
	s_addc_u32 s99, s75, 0
	s_mov_b32 m0, s69
	s_add_u32 s100, s74, 0x80
	s_addc_u32 s101, s75, 0
	global_load_lds_dwordx4 v168, s[98:99]
	s_mov_b32 m0, s76
	s_nop 0
	global_load_lds_dwordx4 v172, s[98:99]
	s_add_i32 s88, 0, 0x18000
	s_add_i32 s89, 0, 0x1c000
	s_waitcnt vmcnt(8)
	s_waitcnt lgkmcnt(0)
	s_setprio 1
	s_barrier
	v_mfma_f32_16x16x32_bf16 v[124:127], v[128:131], v[160:163], v[124:127]
	v_mfma_f32_16x16x32_bf16 v[120:123], v[136:139], v[160:163], v[120:123]
	v_mfma_f32_16x16x32_bf16 v[116:119], v[128:131], v[184:187], v[116:119]
	v_mfma_f32_16x16x32_bf16 v[108:111], v[136:139], v[184:187], v[108:111]
	v_mfma_f32_16x16x32_bf16 v[92:95], v[128:131], v[192:195], v[92:95]
	v_mfma_f32_16x16x32_bf16 v[88:91], v[136:139], v[192:195], v[88:91]
	v_mfma_f32_16x16x32_bf16 v[76:79], v[128:131], v[210:213], v[76:79]
	v_mfma_f32_16x16x32_bf16 v[72:75], v[136:139], v[210:213], v[72:75]
	v_mfma_f32_16x16x32_bf16 v[124:127], v[132:135], v[164:167], v[124:127]
	v_mfma_f32_16x16x32_bf16 v[120:123], v[140:143], v[164:167], v[120:123]
	v_mfma_f32_16x16x32_bf16 v[116:119], v[132:135], v[188:191], v[116:119]
	v_mfma_f32_16x16x32_bf16 v[108:111], v[140:143], v[188:191], v[108:111]
	v_mfma_f32_16x16x32_bf16 v[92:95], v[132:135], v[206:209], v[92:95]
	v_mfma_f32_16x16x32_bf16 v[88:91], v[140:143], v[206:209], v[88:91]
	v_mfma_f32_16x16x32_bf16 v[76:79], v[132:135], v[214:217], v[76:79]
	v_mfma_f32_16x16x32_bf16 v[72:75], v[140:143], v[214:217], v[72:75]
	v_mfma_f32_16x16x32_bf16 v[112:115], v[144:147], v[160:163], v[112:115]
	v_mfma_f32_16x16x32_bf16 v[104:107], v[152:155], v[160:163], v[104:107]
	v_mfma_f32_16x16x32_bf16 v[100:103], v[144:147], v[184:187], v[100:103]
	v_mfma_f32_16x16x32_bf16 v[96:99], v[152:155], v[184:187], v[96:99]
	v_mfma_f32_16x16x32_bf16 v[84:87], v[144:147], v[192:195], v[84:87]
	v_mfma_f32_16x16x32_bf16 v[80:83], v[152:155], v[192:195], v[80:83]
	v_mfma_f32_16x16x32_bf16 v[68:71], v[144:147], v[210:213], v[68:71]
	v_mfma_f32_16x16x32_bf16 v[64:67], v[152:155], v[210:213], v[64:67]
	v_mfma_f32_16x16x32_bf16 v[112:115], v[148:151], v[164:167], v[112:115]
	v_mfma_f32_16x16x32_bf16 v[104:107], v[156:159], v[164:167], v[104:107]
	v_mfma_f32_16x16x32_bf16 v[100:103], v[148:151], v[188:191], v[100:103]
	v_mfma_f32_16x16x32_bf16 v[96:99], v[156:159], v[188:191], v[96:99]
	v_mfma_f32_16x16x32_bf16 v[84:87], v[148:151], v[206:209], v[84:87]
	v_mfma_f32_16x16x32_bf16 v[80:83], v[156:159], v[206:209], v[80:83]
	v_mfma_f32_16x16x32_bf16 v[68:71], v[148:151], v[214:217], v[68:71]
	v_mfma_f32_16x16x32_bf16 v[64:67], v[156:159], v[214:217], v[64:67]
	s_setprio 0
	s_barrier
	s_add_u32 s98, s72, 0x80
	s_addc_u32 s99, s73, 0
	s_add_i32 s74, s88, s1
	s_mov_b32 m0, s74
	ds_read_b128 v[160:163], v204 offset:49152
	ds_read_b128 v[164:167], v204 offset:50176
	ds_read_b128 v[184:187], v204 offset:51200
	ds_read_b128 v[188:191], v204 offset:52224
	ds_read_b128 v[192:195], v204 offset:53248
	ds_read_b128 v[206:209], v204 offset:54272
	ds_read_b128 v[210:213], v204 offset:55296
	ds_read_b128 v[214:217], v204 offset:56320
	global_load_lds_dwordx4 v170, s[98:99]
	s_add_i32 m0, s74, 0x2000
	s_add_u32 s72, s72, 0x200080
	s_addc_u32 s73, s73, 0
	s_add_i32 s74, s89, s1
	global_load_lds_dwordx4 v174, s[98:99]
	s_mov_b32 m0, s74
	s_nop 0
	global_load_lds_dwordx4 v170, s[72:73]
	s_add_i32 m0, s74, 0x2000
	s_nop 0
	global_load_lds_dwordx4 v174, s[72:73]
	s_mov_b32 m0, s78
	s_nop 0
	global_load_lds_dwordx4 v168, s[100:101]
	s_mov_b32 m0, s79
	s_nop 0
	global_load_lds_dwordx4 v172, s[100:101]
	s_waitcnt vmcnt(8)
	s_waitcnt lgkmcnt(0)
	s_setprio 1
	s_barrier
	v_mfma_f32_16x16x32_bf16 v[60:63], v[128:131], v[160:163], v[60:63]
	v_mfma_f32_16x16x32_bf16 v[56:59], v[136:139], v[160:163], v[56:59]
	v_mfma_f32_16x16x32_bf16 v[44:47], v[128:131], v[184:187], v[44:47]
	v_mfma_f32_16x16x32_bf16 v[40:43], v[136:139], v[184:187], v[40:43]
	v_mfma_f32_16x16x32_bf16 v[28:31], v[128:131], v[192:195], v[28:31]
	v_mfma_f32_16x16x32_bf16 v[24:27], v[136:139], v[192:195], v[24:27]
	v_mfma_f32_16x16x32_bf16 v[12:15], v[128:131], v[210:213], v[12:15]
	v_mfma_f32_16x16x32_bf16 v[8:11], v[136:139], v[210:213], v[8:11]
	v_mfma_f32_16x16x32_bf16 v[60:63], v[132:135], v[164:167], v[60:63]
	v_mfma_f32_16x16x32_bf16 v[56:59], v[140:143], v[164:167], v[56:59]
	v_mfma_f32_16x16x32_bf16 v[44:47], v[132:135], v[188:191], v[44:47]
	v_mfma_f32_16x16x32_bf16 v[40:43], v[140:143], v[188:191], v[40:43]
	v_mfma_f32_16x16x32_bf16 v[28:31], v[132:135], v[206:209], v[28:31]
	v_mfma_f32_16x16x32_bf16 v[24:27], v[140:143], v[206:209], v[24:27]
	v_mfma_f32_16x16x32_bf16 v[12:15], v[132:135], v[214:217], v[12:15]
	v_mfma_f32_16x16x32_bf16 v[8:11], v[140:143], v[214:217], v[8:11]
	v_mfma_f32_16x16x32_bf16 v[52:55], v[144:147], v[160:163], v[52:55]
	v_mfma_f32_16x16x32_bf16 v[48:51], v[152:155], v[160:163], v[48:51]
	v_mfma_f32_16x16x32_bf16 v[36:39], v[144:147], v[184:187], v[36:39]
	v_mfma_f32_16x16x32_bf16 v[32:35], v[152:155], v[184:187], v[32:35]
	v_mfma_f32_16x16x32_bf16 v[20:23], v[144:147], v[192:195], v[20:23]
	v_mfma_f32_16x16x32_bf16 v[16:19], v[152:155], v[192:195], v[16:19]
	v_mfma_f32_16x16x32_bf16 v[4:7], v[144:147], v[210:213], v[4:7]
	v_mfma_f32_16x16x32_bf16 v[0:3], v[152:155], v[210:213], v[0:3]
	v_mfma_f32_16x16x32_bf16 v[52:55], v[148:151], v[164:167], v[52:55]
	v_mfma_f32_16x16x32_bf16 v[48:51], v[156:159], v[164:167], v[48:51]
	v_mfma_f32_16x16x32_bf16 v[36:39], v[148:151], v[188:191], v[36:39]
	v_mfma_f32_16x16x32_bf16 v[32:35], v[156:159], v[188:191], v[32:35]
	v_mfma_f32_16x16x32_bf16 v[20:23], v[148:151], v[206:209], v[20:23]
	v_mfma_f32_16x16x32_bf16 v[16:19], v[156:159], v[206:209], v[16:19]
	v_mfma_f32_16x16x32_bf16 v[4:7], v[148:151], v[214:217], v[4:7]
	v_mfma_f32_16x16x32_bf16 v[0:3], v[156:159], v[214:217], v[0:3]
	s_setprio 0
	s_barrier
	s_add_i32 s87, s87, 2
	s_add_u32 s70, s70, 0x100
	s_addc_u32 s71, s71, 0
	s_add_u32 s85, s85, 0x100
	s_addc_u32 s86, s86, 0
	s_cmpk_gt_u32 s87, 0x7d
	s_cbranch_scc0 .LBB0_452
	s_and_b64 vcc, exec, s[36:37]
	s_cbranch_vccz .LBB0_455
	s_barrier

; #define PG8_STAGE(bufoff, gbase, voff) do { _Pragma("unroll") for (int _i = 0; _i < 2; ++_i) \
;         __builtin_amdgcn_global_load_lds((const unsigned*)((const char*)(gbase) + (voff)[_i]), (PG8_LAS unsigned*)(lds + (bufoff) + ldsw + _i * 8192), 16, 0, 0); } while (0)
; #define PG8_LDA(dst, b, h) do { _Pragma("unroll") for (int m = 0; m < 4; ++m) _Pragma("unroll") for (int k = 0; k < 2; ++k) dst[m][k] = *(const PG8_LAS bf16x8*)(lds + PG8_SA(b, h) + aoff + m * 2048 + k * 1024); } while (0)
; #define PG8_LDB(dst, b, h) do { _Pragma("unroll") for (int n = 0; n < 2; ++n) _Pragma("unroll") for (int k = 0; k < 2; ++k) dst[n][k] = *(const PG8_LAS bf16x8*)(lds + PG8_SB(b, h) + boff + n * 2048 + k * 1024); } while (0)
; #define PG8_MMA(ai, bj, At, Bt) do { __builtin_amdgcn_s_setprio(1); _Pragma("unroll") for (int m = 0; m < 4; ++m) _Pragma("unroll") for (int n = 0; n < 2; ++n) _Pragma("unroll") for (int k = 0; k < 2; ++k) \
;         acc[ai][bj][m][n] = __builtin_amdgcn_mfma_f32_16x16x32_bf16(Bt[n][k], At[m][k], acc[ai][bj][m][n], 0, 0, 0); __builtin_amdgcn_s_setprio(0); } while (0)
; #define PG8_WAIT_V(n) asm volatile("s_waitcnt vmcnt(" #n ")" ::: "memory")
; #define PG8_WAIT_L(n) asm volatile("s_waitcnt lgkmcnt(" #n ")" ::: "memory")
; #define PG8_BAR __builtin_amdgcn_s_barrier()
; #define PG8_SCHED __builtin_amdgcn_sched_barrier(0)
; template <class Epi, class Sched, bool ALIGN_EPI = false, bool SP2 = false>
; __device__ __forceinline__ void gemm_phase(PG8_LAS unsigned char* lds, const Gemm g, const Sched& S, const Epi& E) {
;     ...
;             const char* a2 = last ? nA : cA + (size_t)(t + 2) * kstep; const char* b2 = last ? nB : cB + (size_t)(t + 2) * kstep;
;             const char* a3 = a2 + kstep; const char* b3 = b2 + kstep;
;             if (last && has_next) S.a_ready(nxt);
;             if constexpr (SP2) {
;             PG8_LDB(B0, 0, 0); PG8_LDB(B1, 0, 1); PG8_SCHED; PG8_LDA(At, 0, 0); PG8_STAGE(PG8_SA(1, 1), a1 + hstep, voffA);
;             PG8_WAIT_V(8); PG8_WAIT_L(0); PG8_BAR; PG8_MMA(0, 0, At, B0); PG8_MMA(0, 1, At, B1); PG8_BAR; PG8_SCHED;
;             PG8_LDA(At, 0, 1); PG8_STAGE(PG8_SB(0, 0), b2, voffB); PG8_STAGE(PG8_SB(0, 1), b2 + hstep, voffB); PG8_STAGE(PG8_SA(0, 0), a2, voffA);
;             PG8_WAIT_V(8); PG8_WAIT_L(0); PG8_BAR; PG8_MMA(1, 0, At, B0); PG8_MMA(1, 1, At, B1); PG8_BAR; PG8_SCHED;
.LBB0_528:
	ds_read_b128 v[152:155], v149
	ds_read_b128 v[156:159], v149 offset:1024
	ds_read_b128 v[160:163], v149 offset:2048
	ds_read_b128 v[164:167], v149 offset:3072
	ds_read_b128 v[168:171], v150
	ds_read_b128 v[172:175], v150 offset:1024
	ds_read_b128 v[176:179], v150 offset:2048
	ds_read_b128 v[180:183], v150 offset:3072
	s_add_i32 m0, s14, 0xc000
	ds_read_b128 v[184:187], v151
	ds_read_b128 v[188:191], v151 offset:1024
	ds_read_b128 v[192:195], v151 offset:2048
	ds_read_b128 v[200:203], v151 offset:3072
	ds_read_b128 v[204:207], v151 offset:4096
	ds_read_b128 v[208:211], v151 offset:5120
	ds_read_b128 v[212:215], v151 offset:6144
	ds_read_b128 v[216:219], v151 offset:7168
	global_load_lds_dwordx4 v136, s[70:71]
	s_add_i32 m0, s14, 0xe000
	s_nop 0
	global_load_lds_dwordx4 v138, s[70:71]
	s_add_u32 s72, s70, 0xfff80080
	s_addc_u32 s73, s71, -1
	s_cmp_eq_u32 s86, 28
	s_cselect_b32 s75, s25, s73
	s_cselect_b32 s74, s63, s72
	s_cselect_b32 s73, s61, s85
	s_cselect_b32 s72, s83, s84
	s_waitcnt vmcnt(8)
	s_waitcnt lgkmcnt(0)
	s_setprio 1
	s_barrier
	v_mfma_f32_16x16x32_bf16 v[124:127], v[152:155], v[184:187], v[124:127]
	v_mfma_f32_16x16x32_bf16 v[120:123], v[160:163], v[184:187], v[120:123]
	v_mfma_f32_16x16x32_bf16 v[108:111], v[152:155], v[192:195], v[108:111]
	v_mfma_f32_16x16x32_bf16 v[104:107], v[160:163], v[192:195], v[104:107]
	v_mfma_f32_16x16x32_bf16 v[92:95], v[152:155], v[204:207], v[92:95]
	v_mfma_f32_16x16x32_bf16 v[88:91], v[160:163], v[204:207], v[88:91]
	v_mfma_f32_16x16x32_bf16 v[76:79], v[152:155], v[212:215], v[76:79]
	v_mfma_f32_16x16x32_bf16 v[72:75], v[160:163], v[212:215], v[72:75]
	v_mfma_f32_16x16x32_bf16 v[124:127], v[156:159], v[188:191], v[124:127]
	v_mfma_f32_16x16x32_bf16 v[120:123], v[164:167], v[188:191], v[120:123]
	v_mfma_f32_16x16x32_bf16 v[108:111], v[156:159], v[200:203], v[108:111]
	v_mfma_f32_16x16x32_bf16 v[104:107], v[164:167], v[200:203], v[104:107]
	v_mfma_f32_16x16x32_bf16 v[92:95], v[156:159], v[208:211], v[92:95]
	v_mfma_f32_16x16x32_bf16 v[88:91], v[164:167], v[208:211], v[88:91]
	v_mfma_f32_16x16x32_bf16 v[76:79], v[156:159], v[216:219], v[76:79]
	v_mfma_f32_16x16x32_bf16 v[72:75], v[164:167], v[216:219], v[72:75]
	v_mfma_f32_16x16x32_bf16 v[116:119], v[168:171], v[184:187], v[116:119]
	v_mfma_f32_16x16x32_bf16 v[112:115], v[176:179], v[184:187], v[112:115]
	v_mfma_f32_16x16x32_bf16 v[100:103], v[168:171], v[192:195], v[100:103]
	v_mfma_f32_16x16x32_bf16 v[96:99], v[176:179], v[192:195], v[96:99]
	v_mfma_f32_16x16x32_bf16 v[84:87], v[168:171], v[204:207], v[84:87]
	v_mfma_f32_16x16x32_bf16 v[80:83], v[176:179], v[204:207], v[80:83]
	v_mfma_f32_16x16x32_bf16 v[68:71], v[168:171], v[212:215], v[68:71]
	v_mfma_f32_16x16x32_bf16 v[64:67], v[176:179], v[212:215], v[64:67]
	v_mfma_f32_16x16x32_bf16 v[116:119], v[172:175], v[188:191], v[116:119]
	v_mfma_f32_16x16x32_bf16 v[112:115], v[180:183], v[188:191], v[112:115]
	v_mfma_f32_16x16x32_bf16 v[100:103], v[172:175], v[200:203], v[100:103]
	v_mfma_f32_16x16x32_bf16 v[96:99], v[180:183], v[200:203], v[96:99]
	v_mfma_f32_16x16x32_bf16 v[84:87], v[172:175], v[208:211], v[84:87]
	v_mfma_f32_16x16x32_bf16 v[80:83], v[180:183], v[208:211], v[80:83]
	v_mfma_f32_16x16x32_bf16 v[68:71], v[172:175], v[216:219], v[68:71]
	v_mfma_f32_16x16x32_bf16 v[64:67], v[180:183], v[216:219], v[64:67]
	s_setprio 0
	s_barrier
	s_add_i32 s87, s80, s1
	s_mov_b32 m0, s87
	ds_read_b128 v[184:187], v151 offset:16384
	ds_read_b128 v[188:191], v151 offset:17408
	ds_read_b128 v[192:195], v151 offset:18432
	ds_read_b128 v[200:203], v151 offset:19456
	ds_read_b128 v[204:207], v151 offset:20480
	ds_read_b128 v[208:211], v151 offset:21504
	ds_read_b128 v[212:215], v151 offset:22528
	ds_read_b128 v[216:219], v151 offset:23552
	global_load_lds_dwordx4 v130, s[72:73]
	s_add_i32 m0, s87, 0x2000
	s_add_u32 s88, s72, 0x80000
	s_addc_u32 s89, s73, 0
	s_add_i32 s87, s81, s1
	global_load_lds_dwordx4 v134, s[72:73]
	s_mov_b32 m0, s87
	s_nop 0
	global_load_lds_dwordx4 v130, s[88:89]
	s_add_i32 m0, s87, 0x2000
	s_nop 0
	global_load_lds_dwordx4 v134, s[88:89]
	s_mov_b32 m0, s14
	s_nop 0
	global_load_lds_dwordx4 v128, s[74:75]
	s_mov_b32 m0, s15
	s_nop 0
	global_load_lds_dwordx4 v132, s[74:75]
	s_waitcnt vmcnt(8)
	s_waitcnt lgkmcnt(0)
	s_setprio 1
	s_barrier
	v_mfma_f32_16x16x32_bf16 v[60:63], v[152:155], v[184:187], v[60:63]
	v_mfma_f32_16x16x32_bf16 v[56:59], v[160:163], v[184:187], v[56:59]
	v_mfma_f32_16x16x32_bf16 v[44:47], v[152:155], v[192:195], v[44:47]
	v_mfma_f32_16x16x32_bf16 v[40:43], v[160:163], v[192:195], v[40:43]
	v_mfma_f32_16x16x32_bf16 v[28:31], v[152:155], v[204:207], v[28:31]
	v_mfma_f32_16x16x32_bf16 v[24:27], v[160:163], v[204:207], v[24:27]
	v_mfma_f32_16x16x32_bf16 v[12:15], v[152:155], v[212:215], v[12:15]
	v_mfma_f32_16x16x32_bf16 v[8:11], v[160:163], v[212:215], v[8:11]
	v_mfma_f32_16x16x32_bf16 v[60:63], v[156:159], v[188:191], v[60:63]
	v_mfma_f32_16x16x32_bf16 v[56:59], v[164:167], v[188:191], v[56:59]
	v_mfma_f32_16x16x32_bf16 v[44:47], v[156:159], v[200:203], v[44:47]
	v_mfma_f32_16x16x32_bf16 v[40:43], v[164:167], v[200:203], v[40:43]
	v_mfma_f32_16x16x32_bf16 v[28:31], v[156:159], v[208:211], v[28:31]
	v_mfma_f32_16x16x32_bf16 v[24:27], v[164:167], v[208:211], v[24:27]
	v_mfma_f32_16x16x32_bf16 v[12:15], v[156:159], v[216:219], v[12:15]
	v_mfma_f32_16x16x32_bf16 v[8:11], v[164:167], v[216:219], v[8:11]
	v_mfma_f32_16x16x32_bf16 v[52:55], v[168:171], v[184:187], v[52:55]
	v_mfma_f32_16x16x32_bf16 v[48:51], v[176:179], v[184:187], v[48:51]
	v_mfma_f32_16x16x32_bf16 v[36:39], v[168:171], v[192:195], v[36:39]
	v_mfma_f32_16x16x32_bf16 v[32:35], v[176:179], v[192:195], v[32:35]
	v_mfma_f32_16x16x32_bf16 v[20:23], v[168:171], v[204:207], v[20:23]
	v_mfma_f32_16x16x32_bf16 v[16:19], v[176:179], v[204:207], v[16:19]
	v_mfma_f32_16x16x32_bf16 v[4:7], v[168:171], v[212:215], v[4:7]
	v_mfma_f32_16x16x32_bf16 v[0:3], v[176:179], v[212:215], v[0:3]
	v_mfma_f32_16x16x32_bf16 v[52:55], v[172:175], v[188:191], v[52:55]
	v_mfma_f32_16x16x32_bf16 v[48:51], v[180:183], v[188:191], v[48:51]
	v_mfma_f32_16x16x32_bf16 v[36:39], v[172:175], v[200:203], v[36:39]
	v_mfma_f32_16x16x32_bf16 v[32:35], v[180:183], v[200:203], v[32:35]
	v_mfma_f32_16x16x32_bf16 v[20:23], v[172:175], v[208:211], v[20:23]
	v_mfma_f32_16x16x32_bf16 v[16:19], v[180:183], v[208:211], v[16:19]
	v_mfma_f32_16x16x32_bf16 v[4:7], v[172:175], v[216:219], v[4:7]
	v_mfma_f32_16x16x32_bf16 v[0:3], v[180:183], v[216:219], v[0:3]
	s_setprio 0
	s_barrier
; #define PG8_STAGE(bufoff, gbase, voff) do { _Pragma("unroll") for (int _i = 0; _i < 2; ++_i) \
;         __builtin_amdgcn_global_load_lds((const unsigned*)((const char*)(gbase) + (voff)[_i]), (PG8_LAS unsigned*)(lds + (bufoff) + ldsw + _i * 8192), 16, 0, 0); } while (0)
; #define PG8_LDA(dst, b, h) do { _Pragma("unroll") for (int m = 0; m < 4; ++m) _Pragma("unroll") for (int k = 0; k < 2; ++k) dst[m][k] = *(const PG8_LAS bf16x8*)(lds + PG8_SA(b, h) + aoff + m * 2048 + k * 1024); } while (0)
; #define PG8_LDB(dst, b, h) do { _Pragma("unroll") for (int n = 0; n < 2; ++n) _Pragma("unroll") for (int k = 0; k < 2; ++k) dst[n][k] = *(const PG8_LAS bf16x8*)(lds + PG8_SB(b, h) + boff + n * 2048 + k * 1024); } while (0)
; #define PG8_MMA(ai, bj, At, Bt) do { __builtin_amdgcn_s_setprio(1); _Pragma("unroll") for (int m = 0; m < 4; ++m) _Pragma("unroll") for (int n = 0; n < 2; ++n) _Pragma("unroll") for (int k = 0; k < 2; ++k) \
;         acc[ai][bj][m][n] = __builtin_amdgcn_mfma_f32_16x16x32_bf16(Bt[n][k], At[m][k], acc[ai][bj][m][n], 0, 0, 0); __builtin_amdgcn_s_setprio(0); } while (0)
; #define PG8_WAIT_V(n) asm volatile("s_waitcnt vmcnt(" #n ")" ::: "memory")
; #define PG8_WAIT_L(n) asm volatile("s_waitcnt lgkmcnt(" #n ")" ::: "memory")
; #define PG8_BAR __builtin_amdgcn_s_barrier()
; #define PG8_SCHED __builtin_amdgcn_sched_barrier(0)
; template <class Epi, class Sched, bool ALIGN_EPI = false, bool SP2 = false>
; __device__ __forceinline__ void gemm_phase(PG8_LAS unsigned char* lds, const Gemm g, const Sched& S, const Epi& E) {
;     ...
;             PG8_LDB(B0, 1, 0); PG8_LDB(B1, 1, 1); PG8_SCHED; PG8_LDA(At, 1, 0); PG8_STAGE(PG8_SA(0, 1), a2 + hstep, voffA);
;             PG8_WAIT_V(8); PG8_WAIT_L(0); PG8_BAR; PG8_MMA(0, 0, At, B0); PG8_MMA(0, 1, At, B1); PG8_BAR; PG8_SCHED;
;             PG8_LDA(At, 1, 1); PG8_STAGE(PG8_SB(1, 0), b3, voffB); PG8_STAGE(PG8_SB(1, 1), b3 + hstep, voffB); PG8_STAGE(PG8_SA(1, 0), a3, voffA);
;             PG8_WAIT_V(8); PG8_WAIT_L(0); PG8_BAR; PG8_MMA(1, 0, At, B0); PG8_MMA(1, 1, At, B1); PG8_BAR; PG8_SCHED;
;     ...
;         if constexpr (ALIGN_EPI) { if (wr == 0) PG8_BAR; }
	ds_read_b128 v[152:155], v196
	ds_read_b128 v[156:159], v196 offset:1024
	ds_read_b128 v[160:163], v196 offset:2048
	ds_read_b128 v[164:167], v196 offset:3072
	ds_read_b128 v[168:171], v197
	ds_read_b128 v[172:175], v197 offset:1024
	ds_read_b128 v[176:179], v197 offset:2048
	ds_read_b128 v[180:183], v197 offset:3072
	ds_read_b128 v[184:187], v151 offset:32768
	ds_read_b128 v[188:191], v151 offset:33792
	ds_read_b128 v[192:195], v151 offset:34816
	ds_read_b128 v[200:203], v151 offset:35840
	ds_read_b128 v[204:207], v151 offset:36864
	ds_read_b128 v[208:211], v151 offset:37888
	ds_read_b128 v[212:215], v151 offset:38912
	ds_read_b128 v[216:219], v151 offset:39936
	s_add_u32 s98, s74, 0x80000
	s_addc_u32 s99, s75, 0
	s_mov_b32 m0, s33
	s_add_u32 s100, s74, 0x80
	s_addc_u32 s101, s75, 0
	global_load_lds_dwordx4 v128, s[98:99]
	s_mov_b32 m0, s35
	s_nop 0
	global_load_lds_dwordx4 v132, s[98:99]
	s_add_i32 s87, 0, 0x18000
	s_add_i32 s88, 0, 0x1c000
	s_waitcnt vmcnt(8)
	s_waitcnt lgkmcnt(0)
	s_setprio 1
	s_barrier
	v_mfma_f32_16x16x32_bf16 v[124:127], v[152:155], v[184:187], v[124:127]
	v_mfma_f32_16x16x32_bf16 v[120:123], v[160:163], v[184:187], v[120:123]
	v_mfma_f32_16x16x32_bf16 v[108:111], v[152:155], v[192:195], v[108:111]
	v_mfma_f32_16x16x32_bf16 v[104:107], v[160:163], v[192:195], v[104:107]
	v_mfma_f32_16x16x32_bf16 v[92:95], v[152:155], v[204:207], v[92:95]
	v_mfma_f32_16x16x32_bf16 v[88:91], v[160:163], v[204:207], v[88:91]
	v_mfma_f32_16x16x32_bf16 v[76:79], v[152:155], v[212:215], v[76:79]
	v_mfma_f32_16x16x32_bf16 v[72:75], v[160:163], v[212:215], v[72:75]
	v_mfma_f32_16x16x32_bf16 v[124:127], v[156:159], v[188:191], v[124:127]
	v_mfma_f32_16x16x32_bf16 v[120:123], v[164:167], v[188:191], v[120:123]
	v_mfma_f32_16x16x32_bf16 v[108:111], v[156:159], v[200:203], v[108:111]
	v_mfma_f32_16x16x32_bf16 v[104:107], v[164:167], v[200:203], v[104:107]
	v_mfma_f32_16x16x32_bf16 v[92:95], v[156:159], v[208:211], v[92:95]
	v_mfma_f32_16x16x32_bf16 v[88:91], v[164:167], v[208:211], v[88:91]
	v_mfma_f32_16x16x32_bf16 v[76:79], v[156:159], v[216:219], v[76:79]
	v_mfma_f32_16x16x32_bf16 v[72:75], v[164:167], v[216:219], v[72:75]
	v_mfma_f32_16x16x32_bf16 v[116:119], v[168:171], v[184:187], v[116:119]
	v_mfma_f32_16x16x32_bf16 v[112:115], v[176:179], v[184:187], v[112:115]
	v_mfma_f32_16x16x32_bf16 v[100:103], v[168:171], v[192:195], v[100:103]
	v_mfma_f32_16x16x32_bf16 v[96:99], v[176:179], v[192:195], v[96:99]
	v_mfma_f32_16x16x32_bf16 v[84:87], v[168:171], v[204:207], v[84:87]
	v_mfma_f32_16x16x32_bf16 v[80:83], v[176:179], v[204:207], v[80:83]
	v_mfma_f32_16x16x32_bf16 v[68:71], v[168:171], v[212:215], v[68:71]
	v_mfma_f32_16x16x32_bf16 v[64:67], v[176:179], v[212:215], v[64:67]
	v_mfma_f32_16x16x32_bf16 v[116:119], v[172:175], v[188:191], v[116:119]
	v_mfma_f32_16x16x32_bf16 v[112:115], v[180:183], v[188:191], v[112:115]
	v_mfma_f32_16x16x32_bf16 v[100:103], v[172:175], v[200:203], v[100:103]
	v_mfma_f32_16x16x32_bf16 v[96:99], v[180:183], v[200:203], v[96:99]
	v_mfma_f32_16x16x32_bf16 v[84:87], v[172:175], v[208:211], v[84:87]
	v_mfma_f32_16x16x32_bf16 v[80:83], v[180:183], v[208:211], v[80:83]
	v_mfma_f32_16x16x32_bf16 v[68:71], v[172:175], v[216:219], v[68:71]
	v_mfma_f32_16x16x32_bf16 v[64:67], v[180:183], v[216:219], v[64:67]
	s_setprio 0
	s_barrier
	s_add_u32 s98, s72, 0x80
	s_addc_u32 s99, s73, 0
	s_add_i32 s74, s87, s1
	s_mov_b32 m0, s74
	ds_read_b128 v[184:187], v151 offset:49152
	ds_read_b128 v[188:191], v151 offset:50176
	ds_read_b128 v[192:195], v151 offset:51200
	ds_read_b128 v[200:203], v151 offset:52224
	ds_read_b128 v[204:207], v151 offset:53248
	ds_read_b128 v[208:211], v151 offset:54272
	ds_read_b128 v[212:215], v151 offset:55296
	ds_read_b128 v[216:219], v151 offset:56320
	global_load_lds_dwordx4 v130, s[98:99]
	s_add_i32 m0, s74, 0x2000
	s_add_u32 s72, s72, 0x80080
	s_addc_u32 s73, s73, 0
	s_add_i32 s74, s88, s1
	global_load_lds_dwordx4 v134, s[98:99]
	s_mov_b32 m0, s74
	s_nop 0
	global_load_lds_dwordx4 v130, s[72:73]
	s_add_i32 m0, s74, 0x2000
	s_nop 0
	global_load_lds_dwordx4 v134, s[72:73]
	s_mov_b32 m0, s76
	s_nop 0
	global_load_lds_dwordx4 v128, s[100:101]
	s_mov_b32 m0, s77
	s_nop 0
	global_load_lds_dwordx4 v132, s[100:101]
	s_waitcnt vmcnt(8)
	s_waitcnt lgkmcnt(0)
	s_setprio 1
	s_barrier
	v_mfma_f32_16x16x32_bf16 v[60:63], v[152:155], v[184:187], v[60:63]
	v_mfma_f32_16x16x32_bf16 v[56:59], v[160:163], v[184:187], v[56:59]
	v_mfma_f32_16x16x32_bf16 v[44:47], v[152:155], v[192:195], v[44:47]
	v_mfma_f32_16x16x32_bf16 v[40:43], v[160:163], v[192:195], v[40:43]
	v_mfma_f32_16x16x32_bf16 v[28:31], v[152:155], v[204:207], v[28:31]
	v_mfma_f32_16x16x32_bf16 v[24:27], v[160:163], v[204:207], v[24:27]
	v_mfma_f32_16x16x32_bf16 v[12:15], v[152:155], v[212:215], v[12:15]
	v_mfma_f32_16x16x32_bf16 v[8:11], v[160:163], v[212:215], v[8:11]
	v_mfma_f32_16x16x32_bf16 v[60:63], v[156:159], v[188:191], v[60:63]
	v_mfma_f32_16x16x32_bf16 v[56:59], v[164:167], v[188:191], v[56:59]
	v_mfma_f32_16x16x32_bf16 v[44:47], v[156:159], v[200:203], v[44:47]
	v_mfma_f32_16x16x32_bf16 v[40:43], v[164:167], v[200:203], v[40:43]
	v_mfma_f32_16x16x32_bf16 v[28:31], v[156:159], v[208:211], v[28:31]
	v_mfma_f32_16x16x32_bf16 v[24:27], v[164:167], v[208:211], v[24:27]
	v_mfma_f32_16x16x32_bf16 v[12:15], v[156:159], v[216:219], v[12:15]
	v_mfma_f32_16x16x32_bf16 v[8:11], v[164:167], v[216:219], v[8:11]
	v_mfma_f32_16x16x32_bf16 v[52:55], v[168:171], v[184:187], v[52:55]
	v_mfma_f32_16x16x32_bf16 v[48:51], v[176:179], v[184:187], v[48:51]
	v_mfma_f32_16x16x32_bf16 v[36:39], v[168:171], v[192:195], v[36:39]
	v_mfma_f32_16x16x32_bf16 v[32:35], v[176:179], v[192:195], v[32:35]
	v_mfma_f32_16x16x32_bf16 v[20:23], v[168:171], v[204:207], v[20:23]
	v_mfma_f32_16x16x32_bf16 v[16:19], v[176:179], v[204:207], v[16:19]
	v_mfma_f32_16x16x32_bf16 v[4:7], v[168:171], v[212:215], v[4:7]
	v_mfma_f32_16x16x32_bf16 v[0:3], v[176:179], v[212:215], v[0:3]
	v_mfma_f32_16x16x32_bf16 v[52:55], v[172:175], v[188:191], v[52:55]
	v_mfma_f32_16x16x32_bf16 v[48:51], v[180:183], v[188:191], v[48:51]
	v_mfma_f32_16x16x32_bf16 v[36:39], v[172:175], v[200:203], v[36:39]
	v_mfma_f32_16x16x32_bf16 v[32:35], v[180:183], v[200:203], v[32:35]
	v_mfma_f32_16x16x32_bf16 v[20:23], v[172:175], v[208:211], v[20:23]
	v_mfma_f32_16x16x32_bf16 v[16:19], v[180:183], v[208:211], v[16:19]
	v_mfma_f32_16x16x32_bf16 v[4:7], v[172:175], v[216:219], v[4:7]
	v_mfma_f32_16x16x32_bf16 v[0:3], v[180:183], v[216:219], v[0:3]
	s_setprio 0
	s_barrier
	s_add_i32 s86, s86, 2
	s_add_u32 s70, s70, 0x100
	s_addc_u32 s71, s71, 0
	s_add_u32 s84, s84, 0x100
	s_addc_u32 s85, s85, 0
	s_cmp_gt_u32 s86, 29
	s_cbranch_scc0 .LBB0_528
	s_and_b64 vcc, exec, s[44:45]
	s_cbranch_vccz .LBB0_531
	s_barrier

; #define PG8_STAGE(bufoff, gbase, voff) do { _Pragma("unroll") for (int _i = 0; _i < 2; ++_i) \
;         __builtin_amdgcn_global_load_lds((const unsigned*)((const char*)(gbase) + (voff)[_i]), (PG8_LAS unsigned*)(lds + (bufoff) + ldsw + _i * 8192), 16, 0, 0); } while (0)
; #define PG8_LDA(dst, b, h) do { _Pragma("unroll") for (int m = 0; m < 4; ++m) _Pragma("unroll") for (int k = 0; k < 2; ++k) dst[m][k] = *(const PG8_LAS bf16x8*)(lds + PG8_SA(b, h) + aoff + m * 2048 + k * 1024); } while (0)
; #define PG8_LDB(dst, b, h) do { _Pragma("unroll") for (int n = 0; n < 2; ++n) _Pragma("unroll") for (int k = 0; k < 2; ++k) dst[n][k] = *(const PG8_LAS bf16x8*)(lds + PG8_SB(b, h) + boff + n * 2048 + k * 1024); } while (0)
; #define PG8_MMA(ai, bj, At, Bt) do { __builtin_amdgcn_s_setprio(1); _Pragma("unroll") for (int m = 0; m < 4; ++m) _Pragma("unroll") for (int n = 0; n < 2; ++n) _Pragma("unroll") for (int k = 0; k < 2; ++k) \
;         acc[ai][bj][m][n] = __builtin_amdgcn_mfma_f32_16x16x32_bf16(Bt[n][k], At[m][k], acc[ai][bj][m][n], 0, 0, 0); __builtin_amdgcn_s_setprio(0); } while (0)
; #define PG8_WAIT_V(n) asm volatile("s_waitcnt vmcnt(" #n ")" ::: "memory")
; #define PG8_WAIT_L(n) asm volatile("s_waitcnt lgkmcnt(" #n ")" ::: "memory")
; #define PG8_BAR __builtin_amdgcn_s_barrier()
; #define PG8_SCHED __builtin_amdgcn_sched_barrier(0)
; template <class Epi, class Sched, bool ALIGN_EPI = false, bool SP2 = false>
; __device__ __forceinline__ void gemm_phase(PG8_LAS unsigned char* lds, const Gemm g, const Sched& S, const Epi& E) {
;     ...
;             const char* a2 = last ? nA : cA + (size_t)(t + 2) * kstep; const char* b2 = last ? nB : cB + (size_t)(t + 2) * kstep;
;             const char* a3 = a2 + kstep; const char* b3 = b2 + kstep;
;             if (last && has_next) S.a_ready(nxt);
;             if constexpr (SP2) {
;             PG8_LDB(B0, 0, 0); PG8_LDB(B1, 0, 1); PG8_SCHED; PG8_LDA(At, 0, 0); PG8_STAGE(PG8_SA(1, 1), a1 + hstep, voffA);
;             PG8_WAIT_V(8); PG8_WAIT_L(0); PG8_BAR; PG8_MMA(0, 0, At, B0); PG8_MMA(0, 1, At, B1); PG8_BAR; PG8_SCHED;
;             PG8_LDA(At, 0, 1); PG8_STAGE(PG8_SB(0, 0), b2, voffB); PG8_STAGE(PG8_SB(0, 1), b2 + hstep, voffB); PG8_STAGE(PG8_SA(0, 0), a2, voffA);
;             PG8_WAIT_V(8); PG8_WAIT_L(0); PG8_BAR; PG8_MMA(1, 0, At, B0); PG8_MMA(1, 1, At, B1); PG8_BAR; PG8_SCHED;
.LBB0_604:
	ds_read_b128 v[128:131], v202
	ds_read_b128 v[132:135], v202 offset:1024
	ds_read_b128 v[136:139], v202 offset:2048
	ds_read_b128 v[140:143], v202 offset:3072
	ds_read_b128 v[144:147], v203
	ds_read_b128 v[148:151], v203 offset:1024
	ds_read_b128 v[152:155], v203 offset:2048
	ds_read_b128 v[156:159], v203 offset:3072
	s_add_i32 m0, s4, 0xc000
	ds_read_b128 v[160:163], v204
	ds_read_b128 v[164:167], v204 offset:1024
	ds_read_b128 v[184:187], v204 offset:2048
	ds_read_b128 v[188:191], v204 offset:3072
	ds_read_b128 v[192:195], v204 offset:4096
	ds_read_b128 v[206:209], v204 offset:5120
	ds_read_b128 v[210:213], v204 offset:6144
	ds_read_b128 v[214:217], v204 offset:7168
	global_load_lds_dwordx4 v176, s[72:73]
	s_add_i32 m0, s4, 0xe000
	s_nop 0
	global_load_lds_dwordx4 v178, s[72:73]
	s_add_u32 s74, s72, 0xffe00080
	s_addc_u32 s75, s73, -1
	s_cmpk_eq_i32 s85, 0x7c
	s_cselect_b32 s77, s25, s75
	s_cselect_b32 s76, s65, s74
	s_cselect_b32 s75, s63, s84
	s_cselect_b32 s74, s82, s83
	s_waitcnt vmcnt(8)
	s_waitcnt lgkmcnt(0)
	s_setprio 1
	s_barrier
	v_mfma_f32_16x16x32_bf16 v[124:127], v[128:131], v[160:163], v[124:127]
	v_mfma_f32_16x16x32_bf16 v[120:123], v[136:139], v[160:163], v[120:123]
	v_mfma_f32_16x16x32_bf16 v[116:119], v[128:131], v[184:187], v[116:119]
	v_mfma_f32_16x16x32_bf16 v[108:111], v[136:139], v[184:187], v[108:111]
	v_mfma_f32_16x16x32_bf16 v[92:95], v[128:131], v[192:195], v[92:95]
	v_mfma_f32_16x16x32_bf16 v[88:91], v[136:139], v[192:195], v[88:91]
	v_mfma_f32_16x16x32_bf16 v[76:79], v[128:131], v[210:213], v[76:79]
	v_mfma_f32_16x16x32_bf16 v[72:75], v[136:139], v[210:213], v[72:75]
	v_mfma_f32_16x16x32_bf16 v[124:127], v[132:135], v[164:167], v[124:127]
	v_mfma_f32_16x16x32_bf16 v[120:123], v[140:143], v[164:167], v[120:123]
	v_mfma_f32_16x16x32_bf16 v[116:119], v[132:135], v[188:191], v[116:119]
	v_mfma_f32_16x16x32_bf16 v[108:111], v[140:143], v[188:191], v[108:111]
	v_mfma_f32_16x16x32_bf16 v[92:95], v[132:135], v[206:209], v[92:95]
	v_mfma_f32_16x16x32_bf16 v[88:91], v[140:143], v[206:209], v[88:91]
	v_mfma_f32_16x16x32_bf16 v[76:79], v[132:135], v[214:217], v[76:79]
	v_mfma_f32_16x16x32_bf16 v[72:75], v[140:143], v[214:217], v[72:75]
	v_mfma_f32_16x16x32_bf16 v[112:115], v[144:147], v[160:163], v[112:115]
	v_mfma_f32_16x16x32_bf16 v[104:107], v[152:155], v[160:163], v[104:107]
	v_mfma_f32_16x16x32_bf16 v[100:103], v[144:147], v[184:187], v[100:103]
	v_mfma_f32_16x16x32_bf16 v[96:99], v[152:155], v[184:187], v[96:99]
	v_mfma_f32_16x16x32_bf16 v[84:87], v[144:147], v[192:195], v[84:87]
	v_mfma_f32_16x16x32_bf16 v[80:83], v[152:155], v[192:195], v[80:83]
	v_mfma_f32_16x16x32_bf16 v[68:71], v[144:147], v[210:213], v[68:71]
	v_mfma_f32_16x16x32_bf16 v[64:67], v[152:155], v[210:213], v[64:67]
	v_mfma_f32_16x16x32_bf16 v[112:115], v[148:151], v[164:167], v[112:115]
	v_mfma_f32_16x16x32_bf16 v[104:107], v[156:159], v[164:167], v[104:107]
	v_mfma_f32_16x16x32_bf16 v[100:103], v[148:151], v[188:191], v[100:103]
	v_mfma_f32_16x16x32_bf16 v[96:99], v[156:159], v[188:191], v[96:99]
	v_mfma_f32_16x16x32_bf16 v[84:87], v[148:151], v[206:209], v[84:87]
	v_mfma_f32_16x16x32_bf16 v[80:83], v[156:159], v[206:209], v[80:83]
	v_mfma_f32_16x16x32_bf16 v[68:71], v[148:151], v[214:217], v[68:71]
	v_mfma_f32_16x16x32_bf16 v[64:67], v[156:159], v[214:217], v[64:67]
	s_setprio 0
	s_barrier
	s_add_i32 s86, s80, s1
	s_mov_b32 m0, s86
	ds_read_b128 v[160:163], v204 offset:16384
	ds_read_b128 v[164:167], v204 offset:17408
	ds_read_b128 v[184:187], v204 offset:18432
	ds_read_b128 v[188:191], v204 offset:19456
	ds_read_b128 v[192:195], v204 offset:20480
	ds_read_b128 v[206:209], v204 offset:21504
	ds_read_b128 v[210:213], v204 offset:22528
	ds_read_b128 v[214:217], v204 offset:23552
	global_load_lds_dwordx4 v170, s[74:75]
	s_add_i32 m0, s86, 0x2000
	s_add_u32 s86, s74, 0x200000
	s_addc_u32 s87, s75, 0
	s_add_i32 s88, s81, s1
	global_load_lds_dwordx4 v174, s[74:75]
	s_mov_b32 m0, s88
	s_nop 0
	global_load_lds_dwordx4 v170, s[86:87]
	s_add_i32 m0, s88, 0x2000
	s_nop 0
	global_load_lds_dwordx4 v174, s[86:87]
	s_mov_b32 m0, s4
	s_nop 0
	global_load_lds_dwordx4 v168, s[76:77]
	s_mov_b32 m0, s5
	s_nop 0
	global_load_lds_dwordx4 v172, s[76:77]
	s_waitcnt vmcnt(8)
	s_waitcnt lgkmcnt(0)
	s_setprio 1
	s_barrier
	v_mfma_f32_16x16x32_bf16 v[60:63], v[128:131], v[160:163], v[60:63]
	v_mfma_f32_16x16x32_bf16 v[56:59], v[136:139], v[160:163], v[56:59]
	v_mfma_f32_16x16x32_bf16 v[44:47], v[128:131], v[184:187], v[44:47]
	v_mfma_f32_16x16x32_bf16 v[40:43], v[136:139], v[184:187], v[40:43]
	v_mfma_f32_16x16x32_bf16 v[28:31], v[128:131], v[192:195], v[28:31]
	v_mfma_f32_16x16x32_bf16 v[24:27], v[136:139], v[192:195], v[24:27]
	v_mfma_f32_16x16x32_bf16 v[12:15], v[128:131], v[210:213], v[12:15]
	v_mfma_f32_16x16x32_bf16 v[8:11], v[136:139], v[210:213], v[8:11]
	v_mfma_f32_16x16x32_bf16 v[60:63], v[132:135], v[164:167], v[60:63]
	v_mfma_f32_16x16x32_bf16 v[56:59], v[140:143], v[164:167], v[56:59]
	v_mfma_f32_16x16x32_bf16 v[44:47], v[132:135], v[188:191], v[44:47]
	v_mfma_f32_16x16x32_bf16 v[40:43], v[140:143], v[188:191], v[40:43]
	v_mfma_f32_16x16x32_bf16 v[28:31], v[132:135], v[206:209], v[28:31]
	v_mfma_f32_16x16x32_bf16 v[24:27], v[140:143], v[206:209], v[24:27]
	v_mfma_f32_16x16x32_bf16 v[12:15], v[132:135], v[214:217], v[12:15]
	v_mfma_f32_16x16x32_bf16 v[8:11], v[140:143], v[214:217], v[8:11]
	v_mfma_f32_16x16x32_bf16 v[52:55], v[144:147], v[160:163], v[52:55]
	v_mfma_f32_16x16x32_bf16 v[48:51], v[152:155], v[160:163], v[48:51]
	v_mfma_f32_16x16x32_bf16 v[36:39], v[144:147], v[184:187], v[36:39]
	v_mfma_f32_16x16x32_bf16 v[32:35], v[152:155], v[184:187], v[32:35]
	v_mfma_f32_16x16x32_bf16 v[20:23], v[144:147], v[192:195], v[20:23]
	v_mfma_f32_16x16x32_bf16 v[16:19], v[152:155], v[192:195], v[16:19]
	v_mfma_f32_16x16x32_bf16 v[4:7], v[144:147], v[210:213], v[4:7]
	v_mfma_f32_16x16x32_bf16 v[0:3], v[152:155], v[210:213], v[0:3]
	v_mfma_f32_16x16x32_bf16 v[52:55], v[148:151], v[164:167], v[52:55]
	v_mfma_f32_16x16x32_bf16 v[48:51], v[156:159], v[164:167], v[48:51]
	v_mfma_f32_16x16x32_bf16 v[36:39], v[148:151], v[188:191], v[36:39]
	v_mfma_f32_16x16x32_bf16 v[32:35], v[156:159], v[188:191], v[32:35]
	v_mfma_f32_16x16x32_bf16 v[20:23], v[148:151], v[206:209], v[20:23]
	v_mfma_f32_16x16x32_bf16 v[16:19], v[156:159], v[206:209], v[16:19]
	v_mfma_f32_16x16x32_bf16 v[4:7], v[148:151], v[214:217], v[4:7]
	v_mfma_f32_16x16x32_bf16 v[0:3], v[156:159], v[214:217], v[0:3]
	s_setprio 0
	s_barrier
; #define PG8_STAGE(bufoff, gbase, voff) do { _Pragma("unroll") for (int _i = 0; _i < 2; ++_i) \
;         __builtin_amdgcn_global_load_lds((const unsigned*)((const char*)(gbase) + (voff)[_i]), (PG8_LAS unsigned*)(lds + (bufoff) + ldsw + _i * 8192), 16, 0, 0); } while (0)
; #define PG8_LDA(dst, b, h) do { _Pragma("unroll") for (int m = 0; m < 4; ++m) _Pragma("unroll") for (int k = 0; k < 2; ++k) dst[m][k] = *(const PG8_LAS bf16x8*)(lds + PG8_SA(b, h) + aoff + m * 2048 + k * 1024); } while (0)
; #define PG8_LDB(dst, b, h) do { _Pragma("unroll") for (int n = 0; n < 2; ++n) _Pragma("unroll") for (int k = 0; k < 2; ++k) dst[n][k] = *(const PG8_LAS bf16x8*)(lds + PG8_SB(b, h) + boff + n * 2048 + k * 1024); } while (0)
; #define PG8_MMA(ai, bj, At, Bt) do { __builtin_amdgcn_s_setprio(1); _Pragma("unroll") for (int m = 0; m < 4; ++m) _Pragma("unroll") for (int n = 0; n < 2; ++n) _Pragma("unroll") for (int k = 0; k < 2; ++k) \
;         acc[ai][bj][m][n] = __builtin_amdgcn_mfma_f32_16x16x32_bf16(Bt[n][k], At[m][k], acc[ai][bj][m][n], 0, 0, 0); __builtin_amdgcn_s_setprio(0); } while (0)
; #define PG8_WAIT_V(n) asm volatile("s_waitcnt vmcnt(" #n ")" ::: "memory")
; #define PG8_WAIT_L(n) asm volatile("s_waitcnt lgkmcnt(" #n ")" ::: "memory")
; #define PG8_BAR __builtin_amdgcn_s_barrier()
; #define PG8_SCHED __builtin_amdgcn_sched_barrier(0)
; template <class Epi, class Sched, bool ALIGN_EPI = false, bool SP2 = false>
; __device__ __forceinline__ void gemm_phase(PG8_LAS unsigned char* lds, const Gemm g, const Sched& S, const Epi& E) {
;     ...
;             PG8_LDB(B0, 1, 0); PG8_LDB(B1, 1, 1); PG8_SCHED; PG8_LDA(At, 1, 0); PG8_STAGE(PG8_SA(0, 1), a2 + hstep, voffA);
;             PG8_WAIT_V(8); PG8_WAIT_L(0); PG8_BAR; PG8_MMA(0, 0, At, B0); PG8_MMA(0, 1, At, B1); PG8_BAR; PG8_SCHED;
;             PG8_LDA(At, 1, 1); PG8_STAGE(PG8_SB(1, 0), b3, voffB); PG8_STAGE(PG8_SB(1, 1), b3 + hstep, voffB); PG8_STAGE(PG8_SA(1, 0), a3, voffA);
;             PG8_WAIT_V(8); PG8_WAIT_L(0); PG8_BAR; PG8_MMA(1, 0, At, B0); PG8_MMA(1, 1, At, B1); PG8_BAR; PG8_SCHED;
;     ...
;         if constexpr (ALIGN_EPI) { if (wr == 0) PG8_BAR; }
	ds_read_b128 v[128:131], v218
	ds_read_b128 v[132:135], v218 offset:1024
	ds_read_b128 v[136:139], v218 offset:2048
	ds_read_b128 v[140:143], v218 offset:3072
	ds_read_b128 v[144:147], v219
	ds_read_b128 v[148:151], v219 offset:1024
	ds_read_b128 v[152:155], v219 offset:2048
	ds_read_b128 v[156:159], v219 offset:3072
	ds_read_b128 v[160:163], v204 offset:32768
	ds_read_b128 v[164:167], v204 offset:33792
	ds_read_b128 v[184:187], v204 offset:34816
	ds_read_b128 v[188:191], v204 offset:35840
	ds_read_b128 v[192:195], v204 offset:36864
	ds_read_b128 v[206:209], v204 offset:37888
	ds_read_b128 v[210:213], v204 offset:38912
	ds_read_b128 v[214:217], v204 offset:39936
	s_add_u32 s98, s76, 0x200000
	s_addc_u32 s99, s77, 0
	s_mov_b32 m0, s14
	s_add_u32 s100, s76, 0x80
	s_addc_u32 s101, s77, 0
	global_load_lds_dwordx4 v168, s[98:99]
	s_mov_b32 m0, s15
	s_nop 0
	global_load_lds_dwordx4 v172, s[98:99]
	s_add_i32 s86, 0, 0x18000
	s_add_i32 s87, 0, 0x1c000
	s_waitcnt vmcnt(8)
	s_waitcnt lgkmcnt(0)
	s_setprio 1
	s_barrier
	v_mfma_f32_16x16x32_bf16 v[124:127], v[128:131], v[160:163], v[124:127]
	v_mfma_f32_16x16x32_bf16 v[120:123], v[136:139], v[160:163], v[120:123]
	v_mfma_f32_16x16x32_bf16 v[116:119], v[128:131], v[184:187], v[116:119]
	v_mfma_f32_16x16x32_bf16 v[108:111], v[136:139], v[184:187], v[108:111]
	v_mfma_f32_16x16x32_bf16 v[92:95], v[128:131], v[192:195], v[92:95]
	v_mfma_f32_16x16x32_bf16 v[88:91], v[136:139], v[192:195], v[88:91]
	v_mfma_f32_16x16x32_bf16 v[76:79], v[128:131], v[210:213], v[76:79]
	v_mfma_f32_16x16x32_bf16 v[72:75], v[136:139], v[210:213], v[72:75]
	v_mfma_f32_16x16x32_bf16 v[124:127], v[132:135], v[164:167], v[124:127]
	v_mfma_f32_16x16x32_bf16 v[120:123], v[140:143], v[164:167], v[120:123]
	v_mfma_f32_16x16x32_bf16 v[116:119], v[132:135], v[188:191], v[116:119]
	v_mfma_f32_16x16x32_bf16 v[108:111], v[140:143], v[188:191], v[108:111]
	v_mfma_f32_16x16x32_bf16 v[92:95], v[132:135], v[206:209], v[92:95]
	v_mfma_f32_16x16x32_bf16 v[88:91], v[140:143], v[206:209], v[88:91]
	v_mfma_f32_16x16x32_bf16 v[76:79], v[132:135], v[214:217], v[76:79]
	v_mfma_f32_16x16x32_bf16 v[72:75], v[140:143], v[214:217], v[72:75]
	v_mfma_f32_16x16x32_bf16 v[112:115], v[144:147], v[160:163], v[112:115]
	v_mfma_f32_16x16x32_bf16 v[104:107], v[152:155], v[160:163], v[104:107]
	v_mfma_f32_16x16x32_bf16 v[100:103], v[144:147], v[184:187], v[100:103]
	v_mfma_f32_16x16x32_bf16 v[96:99], v[152:155], v[184:187], v[96:99]
	v_mfma_f32_16x16x32_bf16 v[84:87], v[144:147], v[192:195], v[84:87]
	v_mfma_f32_16x16x32_bf16 v[80:83], v[152:155], v[192:195], v[80:83]
	v_mfma_f32_16x16x32_bf16 v[68:71], v[144:147], v[210:213], v[68:71]
	v_mfma_f32_16x16x32_bf16 v[64:67], v[152:155], v[210:213], v[64:67]
	v_mfma_f32_16x16x32_bf16 v[112:115], v[148:151], v[164:167], v[112:115]
	v_mfma_f32_16x16x32_bf16 v[104:107], v[156:159], v[164:167], v[104:107]
	v_mfma_f32_16x16x32_bf16 v[100:103], v[148:151], v[188:191], v[100:103]
	v_mfma_f32_16x16x32_bf16 v[96:99], v[156:159], v[188:191], v[96:99]
	v_mfma_f32_16x16x32_bf16 v[84:87], v[148:151], v[206:209], v[84:87]
	v_mfma_f32_16x16x32_bf16 v[80:83], v[156:159], v[206:209], v[80:83]
	v_mfma_f32_16x16x32_bf16 v[68:71], v[148:151], v[214:217], v[68:71]
	v_mfma_f32_16x16x32_bf16 v[64:67], v[156:159], v[214:217], v[64:67]
	s_setprio 0
	s_barrier
	s_add_u32 s98, s74, 0x80
	s_addc_u32 s99, s75, 0
	s_add_i32 s76, s86, s1
	s_mov_b32 m0, s76
	ds_read_b128 v[160:163], v204 offset:49152
	ds_read_b128 v[164:167], v204 offset:50176
	ds_read_b128 v[184:187], v204 offset:51200
	ds_read_b128 v[188:191], v204 offset:52224
	ds_read_b128 v[192:195], v204 offset:53248
	ds_read_b128 v[206:209], v204 offset:54272
	ds_read_b128 v[210:213], v204 offset:55296
	ds_read_b128 v[214:217], v204 offset:56320
	global_load_lds_dwordx4 v170, s[98:99]
	s_add_i32 m0, s76, 0x2000
	s_add_u32 s74, s74, 0x200080
	s_addc_u32 s75, s75, 0
	s_add_i32 s76, s87, s1
	global_load_lds_dwordx4 v174, s[98:99]
	s_mov_b32 m0, s76
	s_nop 0
	global_load_lds_dwordx4 v170, s[74:75]
	s_add_i32 m0, s76, 0x2000
	s_nop 0
	global_load_lds_dwordx4 v174, s[74:75]
	s_mov_b32 m0, s35
	s_nop 0
	global_load_lds_dwordx4 v168, s[100:101]
	s_mov_b32 m0, s71
	s_nop 0
	global_load_lds_dwordx4 v172, s[100:101]
	s_waitcnt vmcnt(8)
	s_waitcnt lgkmcnt(0)
	s_setprio 1
	s_barrier
	v_mfma_f32_16x16x32_bf16 v[60:63], v[128:131], v[160:163], v[60:63]
	v_mfma_f32_16x16x32_bf16 v[56:59], v[136:139], v[160:163], v[56:59]
	v_mfma_f32_16x16x32_bf16 v[44:47], v[128:131], v[184:187], v[44:47]
	v_mfma_f32_16x16x32_bf16 v[40:43], v[136:139], v[184:187], v[40:43]
	v_mfma_f32_16x16x32_bf16 v[28:31], v[128:131], v[192:195], v[28:31]
	v_mfma_f32_16x16x32_bf16 v[24:27], v[136:139], v[192:195], v[24:27]
	v_mfma_f32_16x16x32_bf16 v[12:15], v[128:131], v[210:213], v[12:15]
	v_mfma_f32_16x16x32_bf16 v[8:11], v[136:139], v[210:213], v[8:11]
	v_mfma_f32_16x16x32_bf16 v[60:63], v[132:135], v[164:167], v[60:63]
	v_mfma_f32_16x16x32_bf16 v[56:59], v[140:143], v[164:167], v[56:59]
	v_mfma_f32_16x16x32_bf16 v[44:47], v[132:135], v[188:191], v[44:47]
	v_mfma_f32_16x16x32_bf16 v[40:43], v[140:143], v[188:191], v[40:43]
	v_mfma_f32_16x16x32_bf16 v[28:31], v[132:135], v[206:209], v[28:31]
	v_mfma_f32_16x16x32_bf16 v[24:27], v[140:143], v[206:209], v[24:27]
	v_mfma_f32_16x16x32_bf16 v[12:15], v[132:135], v[214:217], v[12:15]
	v_mfma_f32_16x16x32_bf16 v[8:11], v[140:143], v[214:217], v[8:11]
	v_mfma_f32_16x16x32_bf16 v[52:55], v[144:147], v[160:163], v[52:55]
	v_mfma_f32_16x16x32_bf16 v[48:51], v[152:155], v[160:163], v[48:51]
	v_mfma_f32_16x16x32_bf16 v[36:39], v[144:147], v[184:187], v[36:39]
	v_mfma_f32_16x16x32_bf16 v[32:35], v[152:155], v[184:187], v[32:35]
	v_mfma_f32_16x16x32_bf16 v[20:23], v[144:147], v[192:195], v[20:23]
	v_mfma_f32_16x16x32_bf16 v[16:19], v[152:155], v[192:195], v[16:19]
	v_mfma_f32_16x16x32_bf16 v[4:7], v[144:147], v[210:213], v[4:7]
	v_mfma_f32_16x16x32_bf16 v[0:3], v[152:155], v[210:213], v[0:3]
	v_mfma_f32_16x16x32_bf16 v[52:55], v[148:151], v[164:167], v[52:55]
	v_mfma_f32_16x16x32_bf16 v[48:51], v[156:159], v[164:167], v[48:51]
	v_mfma_f32_16x16x32_bf16 v[36:39], v[148:151], v[188:191], v[36:39]
	v_mfma_f32_16x16x32_bf16 v[32:35], v[156:159], v[188:191], v[32:35]
	v_mfma_f32_16x16x32_bf16 v[20:23], v[148:151], v[206:209], v[20:23]
	v_mfma_f32_16x16x32_bf16 v[16:19], v[156:159], v[206:209], v[16:19]
	v_mfma_f32_16x16x32_bf16 v[4:7], v[148:151], v[214:217], v[4:7]
	v_mfma_f32_16x16x32_bf16 v[0:3], v[156:159], v[214:217], v[0:3]
	s_setprio 0
	s_barrier
	s_add_i32 s85, s85, 2
	s_add_u32 s72, s72, 0x100
	s_addc_u32 s73, s73, 0
	s_add_u32 s83, s83, 0x100
	s_addc_u32 s84, s84, 0
	s_cmpk_gt_u32 s85, 0x7d
	s_cbranch_scc0 .LBB0_604
	s_and_b64 vcc, exec, s[48:49]
	s_cbranch_vccz .LBB0_607
	s_barrier

; #define PG8_STAGE(bufoff, gbase, voff) do { _Pragma("unroll") for (int _i = 0; _i < 2; ++_i) \
;         __builtin_amdgcn_global_load_lds((const unsigned*)((const char*)(gbase) + (voff)[_i]), (PG8_LAS unsigned*)(lds + (bufoff) + ldsw + _i * 8192), 16, 0, 0); } while (0)
; #define PG8_LDA(dst, b, h) do { _Pragma("unroll") for (int m = 0; m < 4; ++m) _Pragma("unroll") for (int k = 0; k < 2; ++k) dst[m][k] = *(const PG8_LAS bf16x8*)(lds + PG8_SA(b, h) + aoff + m * 2048 + k * 1024); } while (0)
; #define PG8_LDB(dst, b, h) do { _Pragma("unroll") for (int n = 0; n < 2; ++n) _Pragma("unroll") for (int k = 0; k < 2; ++k) dst[n][k] = *(const PG8_LAS bf16x8*)(lds + PG8_SB(b, h) + boff + n * 2048 + k * 1024); } while (0)
; #define PG8_MMA(ai, bj, At, Bt) do { __builtin_amdgcn_s_setprio(1); _Pragma("unroll") for (int m = 0; m < 4; ++m) _Pragma("unroll") for (int n = 0; n < 2; ++n) _Pragma("unroll") for (int k = 0; k < 2; ++k) \
;         acc[ai][bj][m][n] = __builtin_amdgcn_mfma_f32_16x16x32_bf16(Bt[n][k], At[m][k], acc[ai][bj][m][n], 0, 0, 0); __builtin_amdgcn_s_setprio(0); } while (0)
; #define PG8_WAIT_V(n) asm volatile("s_waitcnt vmcnt(" #n ")" ::: "memory")
; #define PG8_WAIT_L(n) asm volatile("s_waitcnt lgkmcnt(" #n ")" ::: "memory")
; #define PG8_BAR __builtin_amdgcn_s_barrier()
; #define PG8_SCHED __builtin_amdgcn_sched_barrier(0)
; template <class Epi, class Sched, bool ALIGN_EPI = false, bool SP2 = false>
; __device__ __forceinline__ void gemm_phase(PG8_LAS unsigned char* lds, const Gemm g, const Sched& S, const Epi& E) {
;     ...
;             const char* a2 = last ? nA : cA + (size_t)(t + 2) * kstep; const char* b2 = last ? nB : cB + (size_t)(t + 2) * kstep;
;             const char* a3 = a2 + kstep; const char* b3 = b2 + kstep;
;             if (last && has_next) S.a_ready(nxt);
;             if constexpr (SP2) {
;             PG8_LDB(B0, 0, 0); PG8_LDB(B1, 0, 1); PG8_SCHED; PG8_LDA(At, 0, 0); PG8_STAGE(PG8_SA(1, 1), a1 + hstep, voffA);
;             PG8_WAIT_V(8); PG8_WAIT_L(0); PG8_BAR; PG8_MMA(0, 0, At, B0); PG8_MMA(0, 1, At, B1); PG8_BAR; PG8_SCHED;
;             PG8_LDA(At, 0, 1); PG8_STAGE(PG8_SB(0, 0), b2, voffB); PG8_STAGE(PG8_SB(0, 1), b2 + hstep, voffB); PG8_STAGE(PG8_SA(0, 0), a2, voffA);
;             PG8_WAIT_V(8); PG8_WAIT_L(0); PG8_BAR; PG8_MMA(1, 0, At, B0); PG8_MMA(1, 1, At, B1); PG8_BAR; PG8_SCHED;
.LBB0_735:
	ds_read_b128 v[156:159], v151
	ds_read_b128 v[160:163], v151 offset:1024
	ds_read_b128 v[164:167], v151 offset:2048
	ds_read_b128 v[168:171], v151 offset:3072
	ds_read_b128 v[172:175], v152
	ds_read_b128 v[176:179], v152 offset:1024
	ds_read_b128 v[180:183], v152 offset:2048
	ds_read_b128 v[184:187], v152 offset:3072
	s_add_i32 m0, s4, 0xc000
	ds_read_b128 v[188:191], v153
	ds_read_b128 v[192:195], v153 offset:1024
	ds_read_b128 v[200:203], v153 offset:2048
	ds_read_b128 v[204:207], v153 offset:3072
	ds_read_b128 v[208:211], v153 offset:4096
	ds_read_b128 v[212:215], v153 offset:5120
	ds_read_b128 v[216:219], v153 offset:6144
	ds_read_b128 v[220:223], v153 offset:7168
	global_load_lds_dwordx4 v138, s[68:69]
	s_add_i32 m0, s4, 0xe000
	s_nop 0
	global_load_lds_dwordx4 v140, s[68:69]
	s_add_u32 s70, s68, 0xfff80080
	s_addc_u32 s71, s69, -1
	s_cmp_eq_u32 s82, 28
	s_cselect_b32 s73, s25, s71
	s_cselect_b32 s72, s61, s70
	s_cselect_b32 s71, s49, s81
	s_cselect_b32 s70, s79, s80
	s_waitcnt vmcnt(8)
	s_waitcnt lgkmcnt(0)
	s_setprio 1
	s_barrier
	v_mfma_f32_16x16x32_bf16 v[124:127], v[156:159], v[188:191], v[124:127]
	v_mfma_f32_16x16x32_bf16 v[120:123], v[164:167], v[188:191], v[120:123]
	v_mfma_f32_16x16x32_bf16 v[108:111], v[156:159], v[200:203], v[108:111]
	v_mfma_f32_16x16x32_bf16 v[104:107], v[164:167], v[200:203], v[104:107]
	v_mfma_f32_16x16x32_bf16 v[96:99], v[156:159], v[208:211], v[96:99]
	v_mfma_f32_16x16x32_bf16 v[88:91], v[164:167], v[208:211], v[88:91]
	v_mfma_f32_16x16x32_bf16 v[80:83], v[156:159], v[216:219], v[80:83]
	v_mfma_f32_16x16x32_bf16 v[72:75], v[164:167], v[216:219], v[72:75]
	v_mfma_f32_16x16x32_bf16 v[124:127], v[160:163], v[192:195], v[124:127]
	v_mfma_f32_16x16x32_bf16 v[120:123], v[168:171], v[192:195], v[120:123]
	v_mfma_f32_16x16x32_bf16 v[108:111], v[160:163], v[204:207], v[108:111]
	v_mfma_f32_16x16x32_bf16 v[104:107], v[168:171], v[204:207], v[104:107]
	v_mfma_f32_16x16x32_bf16 v[96:99], v[160:163], v[212:215], v[96:99]
	v_mfma_f32_16x16x32_bf16 v[88:91], v[168:171], v[212:215], v[88:91]
	v_mfma_f32_16x16x32_bf16 v[80:83], v[160:163], v[220:223], v[80:83]
	v_mfma_f32_16x16x32_bf16 v[72:75], v[168:171], v[220:223], v[72:75]
	v_mfma_f32_16x16x32_bf16 v[116:119], v[172:175], v[188:191], v[116:119]
	v_mfma_f32_16x16x32_bf16 v[112:115], v[180:183], v[188:191], v[112:115]
	v_mfma_f32_16x16x32_bf16 v[100:103], v[172:175], v[200:203], v[100:103]
	v_mfma_f32_16x16x32_bf16 v[92:95], v[180:183], v[200:203], v[92:95]
	v_mfma_f32_16x16x32_bf16 v[84:87], v[172:175], v[208:211], v[84:87]
	v_mfma_f32_16x16x32_bf16 v[76:79], v[180:183], v[208:211], v[76:79]
	v_mfma_f32_16x16x32_bf16 v[68:71], v[172:175], v[216:219], v[68:71]
	v_mfma_f32_16x16x32_bf16 v[64:67], v[180:183], v[216:219], v[64:67]
	v_mfma_f32_16x16x32_bf16 v[116:119], v[176:179], v[192:195], v[116:119]
	v_mfma_f32_16x16x32_bf16 v[112:115], v[184:187], v[192:195], v[112:115]
	v_mfma_f32_16x16x32_bf16 v[100:103], v[176:179], v[204:207], v[100:103]
	v_mfma_f32_16x16x32_bf16 v[92:95], v[184:187], v[204:207], v[92:95]
	v_mfma_f32_16x16x32_bf16 v[84:87], v[176:179], v[212:215], v[84:87]
	v_mfma_f32_16x16x32_bf16 v[76:79], v[184:187], v[212:215], v[76:79]
	v_mfma_f32_16x16x32_bf16 v[68:71], v[176:179], v[220:223], v[68:71]
	v_mfma_f32_16x16x32_bf16 v[64:67], v[184:187], v[220:223], v[64:67]
	s_setprio 0
	s_barrier
	s_add_i32 s83, s77, s1
	s_mov_b32 m0, s83
	ds_read_b128 v[188:191], v153 offset:16384
	ds_read_b128 v[192:195], v153 offset:17408
	ds_read_b128 v[200:203], v153 offset:18432
	ds_read_b128 v[204:207], v153 offset:19456
	ds_read_b128 v[208:211], v153 offset:20480
	ds_read_b128 v[212:215], v153 offset:21504
	ds_read_b128 v[216:219], v153 offset:22528
	ds_read_b128 v[220:223], v153 offset:23552
	global_load_lds_dwordx4 v130, s[70:71]
	s_add_i32 m0, s83, 0x2000
	s_add_u32 s84, s70, 0x80000
	s_addc_u32 s85, s71, 0
	s_add_i32 s83, s78, s1
	global_load_lds_dwordx4 v134, s[70:71]
	s_mov_b32 m0, s83
	s_nop 0
	global_load_lds_dwordx4 v130, s[84:85]
	s_add_i32 m0, s83, 0x2000
	s_nop 0
	global_load_lds_dwordx4 v134, s[84:85]
	s_mov_b32 m0, s4
	s_nop 0
	global_load_lds_dwordx4 v128, s[72:73]
	s_mov_b32 m0, s5
	s_nop 0
	global_load_lds_dwordx4 v132, s[72:73]
	s_waitcnt vmcnt(8)
	s_waitcnt lgkmcnt(0)
	s_setprio 1
	s_barrier
	v_mfma_f32_16x16x32_bf16 v[60:63], v[156:159], v[188:191], v[60:63]
	v_mfma_f32_16x16x32_bf16 v[56:59], v[164:167], v[188:191], v[56:59]
	v_mfma_f32_16x16x32_bf16 v[44:47], v[156:159], v[200:203], v[44:47]
	v_mfma_f32_16x16x32_bf16 v[40:43], v[164:167], v[200:203], v[40:43]
	v_mfma_f32_16x16x32_bf16 v[32:35], v[156:159], v[208:211], v[32:35]
	v_mfma_f32_16x16x32_bf16 v[24:27], v[164:167], v[208:211], v[24:27]
	v_mfma_f32_16x16x32_bf16 v[16:19], v[156:159], v[216:219], v[16:19]
	v_mfma_f32_16x16x32_bf16 v[8:11], v[164:167], v[216:219], v[8:11]
	v_mfma_f32_16x16x32_bf16 v[60:63], v[160:163], v[192:195], v[60:63]
	v_mfma_f32_16x16x32_bf16 v[56:59], v[168:171], v[192:195], v[56:59]
	v_mfma_f32_16x16x32_bf16 v[44:47], v[160:163], v[204:207], v[44:47]
	v_mfma_f32_16x16x32_bf16 v[40:43], v[168:171], v[204:207], v[40:43]
	v_mfma_f32_16x16x32_bf16 v[32:35], v[160:163], v[212:215], v[32:35]
	v_mfma_f32_16x16x32_bf16 v[24:27], v[168:171], v[212:215], v[24:27]
	v_mfma_f32_16x16x32_bf16 v[16:19], v[160:163], v[220:223], v[16:19]
	v_mfma_f32_16x16x32_bf16 v[8:11], v[168:171], v[220:223], v[8:11]
	v_mfma_f32_16x16x32_bf16 v[52:55], v[172:175], v[188:191], v[52:55]
	v_mfma_f32_16x16x32_bf16 v[48:51], v[180:183], v[188:191], v[48:51]
	v_mfma_f32_16x16x32_bf16 v[36:39], v[172:175], v[200:203], v[36:39]
	v_mfma_f32_16x16x32_bf16 v[28:31], v[180:183], v[200:203], v[28:31]
	v_mfma_f32_16x16x32_bf16 v[20:23], v[172:175], v[208:211], v[20:23]
	v_mfma_f32_16x16x32_bf16 v[12:15], v[180:183], v[208:211], v[12:15]
	v_mfma_f32_16x16x32_bf16 v[4:7], v[172:175], v[216:219], v[4:7]
	v_mfma_f32_16x16x32_bf16 v[0:3], v[180:183], v[216:219], v[0:3]
	v_mfma_f32_16x16x32_bf16 v[52:55], v[176:179], v[192:195], v[52:55]
	v_mfma_f32_16x16x32_bf16 v[48:51], v[184:187], v[192:195], v[48:51]
	v_mfma_f32_16x16x32_bf16 v[36:39], v[176:179], v[204:207], v[36:39]
	v_mfma_f32_16x16x32_bf16 v[28:31], v[184:187], v[204:207], v[28:31]
	v_mfma_f32_16x16x32_bf16 v[20:23], v[176:179], v[212:215], v[20:23]
	v_mfma_f32_16x16x32_bf16 v[12:15], v[184:187], v[212:215], v[12:15]
	v_mfma_f32_16x16x32_bf16 v[4:7], v[176:179], v[220:223], v[4:7]
	v_mfma_f32_16x16x32_bf16 v[0:3], v[184:187], v[220:223], v[0:3]
	s_setprio 0
	s_barrier
; #define PG8_STAGE(bufoff, gbase, voff) do { _Pragma("unroll") for (int _i = 0; _i < 2; ++_i) \
;         __builtin_amdgcn_global_load_lds((const unsigned*)((const char*)(gbase) + (voff)[_i]), (PG8_LAS unsigned*)(lds + (bufoff) + ldsw + _i * 8192), 16, 0, 0); } while (0)
; #define PG8_LDA(dst, b, h) do { _Pragma("unroll") for (int m = 0; m < 4; ++m) _Pragma("unroll") for (int k = 0; k < 2; ++k) dst[m][k] = *(const PG8_LAS bf16x8*)(lds + PG8_SA(b, h) + aoff + m * 2048 + k * 1024); } while (0)
; #define PG8_LDB(dst, b, h) do { _Pragma("unroll") for (int n = 0; n < 2; ++n) _Pragma("unroll") for (int k = 0; k < 2; ++k) dst[n][k] = *(const PG8_LAS bf16x8*)(lds + PG8_SB(b, h) + boff + n * 2048 + k * 1024); } while (0)
; #define PG8_MMA(ai, bj, At, Bt) do { __builtin_amdgcn_s_setprio(1); _Pragma("unroll") for (int m = 0; m < 4; ++m) _Pragma("unroll") for (int n = 0; n < 2; ++n) _Pragma("unroll") for (int k = 0; k < 2; ++k) \
;         acc[ai][bj][m][n] = __builtin_amdgcn_mfma_f32_16x16x32_bf16(Bt[n][k], At[m][k], acc[ai][bj][m][n], 0, 0, 0); __builtin_amdgcn_s_setprio(0); } while (0)
; #define PG8_WAIT_V(n) asm volatile("s_waitcnt vmcnt(" #n ")" ::: "memory")
; #define PG8_WAIT_L(n) asm volatile("s_waitcnt lgkmcnt(" #n ")" ::: "memory")
; #define PG8_BAR __builtin_amdgcn_s_barrier()
; #define PG8_SCHED __builtin_amdgcn_sched_barrier(0)
; template <class Epi, class Sched, bool ALIGN_EPI = false, bool SP2 = false>
; __device__ __forceinline__ void gemm_phase(PG8_LAS unsigned char* lds, const Gemm g, const Sched& S, const Epi& E) {
;     ...
;             PG8_LDB(B0, 1, 0); PG8_LDB(B1, 1, 1); PG8_SCHED; PG8_LDA(At, 1, 0); PG8_STAGE(PG8_SA(0, 1), a2 + hstep, voffA);
;             PG8_WAIT_V(8); PG8_WAIT_L(0); PG8_BAR; PG8_MMA(0, 0, At, B0); PG8_MMA(0, 1, At, B1); PG8_BAR; PG8_SCHED;
;             PG8_LDA(At, 1, 1); PG8_STAGE(PG8_SB(1, 0), b3, voffB); PG8_STAGE(PG8_SB(1, 1), b3 + hstep, voffB); PG8_STAGE(PG8_SA(1, 0), a3, voffA);
;             PG8_WAIT_V(8); PG8_WAIT_L(0); PG8_BAR; PG8_MMA(1, 0, At, B0); PG8_MMA(1, 1, At, B1); PG8_BAR; PG8_SCHED;
;     ...
;         if constexpr (ALIGN_EPI) { if (wr == 0) PG8_BAR; }
	ds_read_b128 v[156:159], v196
	ds_read_b128 v[160:163], v196 offset:1024
	ds_read_b128 v[164:167], v196 offset:2048
	ds_read_b128 v[168:171], v196 offset:3072
	ds_read_b128 v[172:175], v197
	ds_read_b128 v[176:179], v197 offset:1024
	ds_read_b128 v[180:183], v197 offset:2048
	ds_read_b128 v[184:187], v197 offset:3072
	ds_read_b128 v[188:191], v153 offset:32768
	ds_read_b128 v[192:195], v153 offset:33792
	ds_read_b128 v[200:203], v153 offset:34816
	ds_read_b128 v[204:207], v153 offset:35840
	ds_read_b128 v[208:211], v153 offset:36864
	ds_read_b128 v[212:215], v153 offset:37888
	ds_read_b128 v[216:219], v153 offset:38912
	ds_read_b128 v[220:223], v153 offset:39936
	s_add_u32 s98, s72, 0x80000
	s_addc_u32 s99, s73, 0
	s_mov_b32 m0, s14
	s_add_u32 s100, s72, 0x80
	s_addc_u32 s101, s73, 0
	global_load_lds_dwordx4 v128, s[98:99]
	s_mov_b32 m0, s15
	s_nop 0
	global_load_lds_dwordx4 v132, s[98:99]
	s_add_i32 s83, 0, 0x18000
	s_add_i32 s84, 0, 0x1c000
	s_waitcnt vmcnt(8)
	s_waitcnt lgkmcnt(0)
	s_setprio 1
	s_barrier
	v_mfma_f32_16x16x32_bf16 v[124:127], v[156:159], v[188:191], v[124:127]
	v_mfma_f32_16x16x32_bf16 v[120:123], v[164:167], v[188:191], v[120:123]
	v_mfma_f32_16x16x32_bf16 v[108:111], v[156:159], v[200:203], v[108:111]
	v_mfma_f32_16x16x32_bf16 v[104:107], v[164:167], v[200:203], v[104:107]
	v_mfma_f32_16x16x32_bf16 v[96:99], v[156:159], v[208:211], v[96:99]
	v_mfma_f32_16x16x32_bf16 v[88:91], v[164:167], v[208:211], v[88:91]
	v_mfma_f32_16x16x32_bf16 v[80:83], v[156:159], v[216:219], v[80:83]
	v_mfma_f32_16x16x32_bf16 v[72:75], v[164:167], v[216:219], v[72:75]
	v_mfma_f32_16x16x32_bf16 v[124:127], v[160:163], v[192:195], v[124:127]
	v_mfma_f32_16x16x32_bf16 v[120:123], v[168:171], v[192:195], v[120:123]
	v_mfma_f32_16x16x32_bf16 v[108:111], v[160:163], v[204:207], v[108:111]
	v_mfma_f32_16x16x32_bf16 v[104:107], v[168:171], v[204:207], v[104:107]
	v_mfma_f32_16x16x32_bf16 v[96:99], v[160:163], v[212:215], v[96:99]
	v_mfma_f32_16x16x32_bf16 v[88:91], v[168:171], v[212:215], v[88:91]
	v_mfma_f32_16x16x32_bf16 v[80:83], v[160:163], v[220:223], v[80:83]
	v_mfma_f32_16x16x32_bf16 v[72:75], v[168:171], v[220:223], v[72:75]
	v_mfma_f32_16x16x32_bf16 v[116:119], v[172:175], v[188:191], v[116:119]
	v_mfma_f32_16x16x32_bf16 v[112:115], v[180:183], v[188:191], v[112:115]
	v_mfma_f32_16x16x32_bf16 v[100:103], v[172:175], v[200:203], v[100:103]
	v_mfma_f32_16x16x32_bf16 v[92:95], v[180:183], v[200:203], v[92:95]
	v_mfma_f32_16x16x32_bf16 v[84:87], v[172:175], v[208:211], v[84:87]
	v_mfma_f32_16x16x32_bf16 v[76:79], v[180:183], v[208:211], v[76:79]
	v_mfma_f32_16x16x32_bf16 v[68:71], v[172:175], v[216:219], v[68:71]
	v_mfma_f32_16x16x32_bf16 v[64:67], v[180:183], v[216:219], v[64:67]
	v_mfma_f32_16x16x32_bf16 v[116:119], v[176:179], v[192:195], v[116:119]
	v_mfma_f32_16x16x32_bf16 v[112:115], v[184:187], v[192:195], v[112:115]
	v_mfma_f32_16x16x32_bf16 v[100:103], v[176:179], v[204:207], v[100:103]
	v_mfma_f32_16x16x32_bf16 v[92:95], v[184:187], v[204:207], v[92:95]
	v_mfma_f32_16x16x32_bf16 v[84:87], v[176:179], v[212:215], v[84:87]
	v_mfma_f32_16x16x32_bf16 v[76:79], v[184:187], v[212:215], v[76:79]
	v_mfma_f32_16x16x32_bf16 v[68:71], v[176:179], v[220:223], v[68:71]
	v_mfma_f32_16x16x32_bf16 v[64:67], v[184:187], v[220:223], v[64:67]
	s_setprio 0
	s_barrier
	s_add_u32 s98, s70, 0x80
	s_addc_u32 s99, s71, 0
	s_add_i32 s72, s83, s1
	s_mov_b32 m0, s72
	ds_read_b128 v[188:191], v153 offset:49152
	ds_read_b128 v[192:195], v153 offset:50176
	ds_read_b128 v[200:203], v153 offset:51200
	ds_read_b128 v[204:207], v153 offset:52224
	ds_read_b128 v[208:211], v153 offset:53248
	ds_read_b128 v[212:215], v153 offset:54272
	ds_read_b128 v[216:219], v153 offset:55296
	ds_read_b128 v[220:223], v153 offset:56320
	global_load_lds_dwordx4 v130, s[98:99]
	s_add_i32 m0, s72, 0x2000
	s_add_u32 s70, s70, 0x80080
	s_addc_u32 s71, s71, 0
	s_add_i32 s72, s84, s1
	global_load_lds_dwordx4 v134, s[98:99]
	s_mov_b32 m0, s72
	s_nop 0
	global_load_lds_dwordx4 v130, s[70:71]
	s_add_i32 m0, s72, 0x2000
	s_nop 0
	global_load_lds_dwordx4 v134, s[70:71]
	s_mov_b32 m0, s67
	s_nop 0
	global_load_lds_dwordx4 v128, s[100:101]
	s_mov_b32 m0, s74
	s_nop 0
	global_load_lds_dwordx4 v132, s[100:101]
	s_waitcnt vmcnt(8)
	s_waitcnt lgkmcnt(0)
	s_setprio 1
	s_barrier
	v_mfma_f32_16x16x32_bf16 v[60:63], v[156:159], v[188:191], v[60:63]
	v_mfma_f32_16x16x32_bf16 v[56:59], v[164:167], v[188:191], v[56:59]
	v_mfma_f32_16x16x32_bf16 v[44:47], v[156:159], v[200:203], v[44:47]
	v_mfma_f32_16x16x32_bf16 v[40:43], v[164:167], v[200:203], v[40:43]
	v_mfma_f32_16x16x32_bf16 v[32:35], v[156:159], v[208:211], v[32:35]
	v_mfma_f32_16x16x32_bf16 v[24:27], v[164:167], v[208:211], v[24:27]
	v_mfma_f32_16x16x32_bf16 v[16:19], v[156:159], v[216:219], v[16:19]
	v_mfma_f32_16x16x32_bf16 v[8:11], v[164:167], v[216:219], v[8:11]
	v_mfma_f32_16x16x32_bf16 v[60:63], v[160:163], v[192:195], v[60:63]
	v_mfma_f32_16x16x32_bf16 v[56:59], v[168:171], v[192:195], v[56:59]
	v_mfma_f32_16x16x32_bf16 v[44:47], v[160:163], v[204:207], v[44:47]
	v_mfma_f32_16x16x32_bf16 v[40:43], v[168:171], v[204:207], v[40:43]
	v_mfma_f32_16x16x32_bf16 v[32:35], v[160:163], v[212:215], v[32:35]
	v_mfma_f32_16x16x32_bf16 v[24:27], v[168:171], v[212:215], v[24:27]
	v_mfma_f32_16x16x32_bf16 v[16:19], v[160:163], v[220:223], v[16:19]
	v_mfma_f32_16x16x32_bf16 v[8:11], v[168:171], v[220:223], v[8:11]
	v_mfma_f32_16x16x32_bf16 v[52:55], v[172:175], v[188:191], v[52:55]
	v_mfma_f32_16x16x32_bf16 v[48:51], v[180:183], v[188:191], v[48:51]
	v_mfma_f32_16x16x32_bf16 v[36:39], v[172:175], v[200:203], v[36:39]
	v_mfma_f32_16x16x32_bf16 v[28:31], v[180:183], v[200:203], v[28:31]
	v_mfma_f32_16x16x32_bf16 v[20:23], v[172:175], v[208:211], v[20:23]
	v_mfma_f32_16x16x32_bf16 v[12:15], v[180:183], v[208:211], v[12:15]
	v_mfma_f32_16x16x32_bf16 v[4:7], v[172:175], v[216:219], v[4:7]
	v_mfma_f32_16x16x32_bf16 v[0:3], v[180:183], v[216:219], v[0:3]
	v_mfma_f32_16x16x32_bf16 v[52:55], v[176:179], v[192:195], v[52:55]
	v_mfma_f32_16x16x32_bf16 v[48:51], v[184:187], v[192:195], v[48:51]
	v_mfma_f32_16x16x32_bf16 v[36:39], v[176:179], v[204:207], v[36:39]
	v_mfma_f32_16x16x32_bf16 v[28:31], v[184:187], v[204:207], v[28:31]
	v_mfma_f32_16x16x32_bf16 v[20:23], v[176:179], v[212:215], v[20:23]
	v_mfma_f32_16x16x32_bf16 v[12:15], v[184:187], v[212:215], v[12:15]
	v_mfma_f32_16x16x32_bf16 v[4:7], v[176:179], v[220:223], v[4:7]
	v_mfma_f32_16x16x32_bf16 v[0:3], v[184:187], v[220:223], v[0:3]
	s_setprio 0
	s_barrier
	s_add_i32 s82, s82, 2
	s_add_u32 s68, s68, 0x100
	s_addc_u32 s69, s69, 0
	s_add_u32 s80, s80, 0x100
	s_addc_u32 s81, s81, 0
	s_cmp_gt_u32 s82, 29
	s_cbranch_scc0 .LBB0_735
	s_and_b64 vcc, exec, s[38:39]
	s_cbranch_vccz .LBB0_738
	s_barrier

; #define PG8_STAGE(bufoff, gbase, voff) do { _Pragma("unroll") for (int _i = 0; _i < 2; ++_i) \
;         __builtin_amdgcn_global_load_lds((const unsigned*)((const char*)(gbase) + (voff)[_i]), (PG8_LAS unsigned*)(lds + (bufoff) + ldsw + _i * 8192), 16, 0, 0); } while (0)
; #define PG8_LDA(dst, b, h) do { _Pragma("unroll") for (int m = 0; m < 4; ++m) _Pragma("unroll") for (int k = 0; k < 2; ++k) dst[m][k] = *(const PG8_LAS bf16x8*)(lds + PG8_SA(b, h) + aoff + m * 2048 + k * 1024); } while (0)
; #define PG8_LDB(dst, b, h) do { _Pragma("unroll") for (int n = 0; n < 2; ++n) _Pragma("unroll") for (int k = 0; k < 2; ++k) dst[n][k] = *(const PG8_LAS bf16x8*)(lds + PG8_SB(b, h) + boff + n * 2048 + k * 1024); } while (0)
; #define PG8_MMA(ai, bj, At, Bt) do { __builtin_amdgcn_s_setprio(1); _Pragma("unroll") for (int m = 0; m < 4; ++m) _Pragma("unroll") for (int n = 0; n < 2; ++n) _Pragma("unroll") for (int k = 0; k < 2; ++k) \
;         acc[ai][bj][m][n] = __builtin_amdgcn_mfma_f32_16x16x32_bf16(Bt[n][k], At[m][k], acc[ai][bj][m][n], 0, 0, 0); __builtin_amdgcn_s_setprio(0); } while (0)
; #define PG8_WAIT_V(n) asm volatile("s_waitcnt vmcnt(" #n ")" ::: "memory")
; #define PG8_WAIT_L(n) asm volatile("s_waitcnt lgkmcnt(" #n ")" ::: "memory")
; #define PG8_BAR __builtin_amdgcn_s_barrier()
; #define PG8_SCHED __builtin_amdgcn_sched_barrier(0)
; template <class Epi, class Sched, bool ALIGN_EPI = false, bool SP2 = false>
; __device__ __forceinline__ void gemm_phase(PG8_LAS unsigned char* lds, const Gemm g, const Sched& S, const Epi& E) {
;     ...
;             const char* a2 = last ? nA : cA + (size_t)(t + 2) * kstep; const char* b2 = last ? nB : cB + (size_t)(t + 2) * kstep;
;             const char* a3 = a2 + kstep; const char* b3 = b2 + kstep;
;             if (last && has_next) S.a_ready(nxt);
;             if constexpr (SP2) {
;             PG8_LDB(B0, 0, 0); PG8_LDB(B1, 0, 1); PG8_SCHED; PG8_LDA(At, 0, 0); PG8_STAGE(PG8_SA(1, 1), a1 + hstep, voffA);
;             PG8_WAIT_V(8); PG8_WAIT_L(0); PG8_BAR; PG8_MMA(0, 0, At, B0); PG8_MMA(0, 1, At, B1); PG8_BAR; PG8_SCHED;
;             PG8_LDA(At, 0, 1); PG8_STAGE(PG8_SB(0, 0), b2, voffB); PG8_STAGE(PG8_SB(0, 1), b2 + hstep, voffB); PG8_STAGE(PG8_SA(0, 0), a2, voffA);
;             PG8_WAIT_V(8); PG8_WAIT_L(0); PG8_BAR; PG8_MMA(1, 0, At, B0); PG8_MMA(1, 1, At, B1); PG8_BAR; PG8_SCHED;
.LBB0_759:
	ds_read_b128 v[152:155], v149
	ds_read_b128 v[156:159], v149 offset:1024
	ds_read_b128 v[160:163], v149 offset:2048
	ds_read_b128 v[164:167], v149 offset:3072
	ds_read_b128 v[168:171], v150
	ds_read_b128 v[172:175], v150 offset:1024
	ds_read_b128 v[176:179], v150 offset:2048
	ds_read_b128 v[180:183], v150 offset:3072
	s_add_i32 m0, s6, 0xc000
	ds_read_b128 v[184:187], v151
	ds_read_b128 v[188:191], v151 offset:1024
	ds_read_b128 v[192:195], v151 offset:2048
	ds_read_b128 v[200:203], v151 offset:3072
	ds_read_b128 v[204:207], v151 offset:4096
	ds_read_b128 v[208:211], v151 offset:5120
	ds_read_b128 v[212:215], v151 offset:6144
	ds_read_b128 v[216:219], v151 offset:7168
	global_load_lds_dwordx4 v138, s[68:69]
	s_add_i32 m0, s6, 0xe000
	s_nop 0
	global_load_lds_dwordx4 v140, s[68:69]
	s_add_u32 s70, s68, 0xfff80080
	s_addc_u32 s71, s69, -1
	s_cmp_eq_u32 s83, 28
	s_cselect_b32 s73, s25, s71
	s_cselect_b32 s72, s61, s70
	s_cselect_b32 s71, s49, s82
	s_cselect_b32 s70, s80, s81
	s_waitcnt vmcnt(8)
	s_waitcnt lgkmcnt(0)
	s_setprio 1
	s_barrier
	v_mfma_f32_16x16x32_bf16 v[124:127], v[152:155], v[184:187], v[124:127]
	v_mfma_f32_16x16x32_bf16 v[120:123], v[160:163], v[184:187], v[120:123]
	v_mfma_f32_16x16x32_bf16 v[112:115], v[152:155], v[192:195], v[112:115]
	v_mfma_f32_16x16x32_bf16 v[104:107], v[160:163], v[192:195], v[104:107]
	v_mfma_f32_16x16x32_bf16 v[100:103], v[152:155], v[204:207], v[100:103]
	v_mfma_f32_16x16x32_bf16 v[92:95], v[160:163], v[204:207], v[92:95]
	v_mfma_f32_16x16x32_bf16 v[84:87], v[152:155], v[212:215], v[84:87]
	v_mfma_f32_16x16x32_bf16 v[76:79], v[160:163], v[212:215], v[76:79]
	v_mfma_f32_16x16x32_bf16 v[124:127], v[156:159], v[188:191], v[124:127]
	v_mfma_f32_16x16x32_bf16 v[120:123], v[164:167], v[188:191], v[120:123]
	v_mfma_f32_16x16x32_bf16 v[112:115], v[156:159], v[200:203], v[112:115]
	v_mfma_f32_16x16x32_bf16 v[104:107], v[164:167], v[200:203], v[104:107]
	v_mfma_f32_16x16x32_bf16 v[100:103], v[156:159], v[208:211], v[100:103]
	v_mfma_f32_16x16x32_bf16 v[92:95], v[164:167], v[208:211], v[92:95]
	v_mfma_f32_16x16x32_bf16 v[84:87], v[156:159], v[216:219], v[84:87]
	v_mfma_f32_16x16x32_bf16 v[76:79], v[164:167], v[216:219], v[76:79]
	v_mfma_f32_16x16x32_bf16 v[116:119], v[168:171], v[184:187], v[116:119]
	v_mfma_f32_16x16x32_bf16 v[108:111], v[176:179], v[184:187], v[108:111]
	v_mfma_f32_16x16x32_bf16 v[96:99], v[168:171], v[192:195], v[96:99]
	v_mfma_f32_16x16x32_bf16 v[88:91], v[176:179], v[192:195], v[88:91]
	v_mfma_f32_16x16x32_bf16 v[80:83], v[168:171], v[204:207], v[80:83]
	v_mfma_f32_16x16x32_bf16 v[72:75], v[176:179], v[204:207], v[72:75]
	v_mfma_f32_16x16x32_bf16 v[68:71], v[168:171], v[212:215], v[68:71]
	v_mfma_f32_16x16x32_bf16 v[64:67], v[176:179], v[212:215], v[64:67]
	v_mfma_f32_16x16x32_bf16 v[116:119], v[172:175], v[188:191], v[116:119]
	v_mfma_f32_16x16x32_bf16 v[108:111], v[180:183], v[188:191], v[108:111]
	v_mfma_f32_16x16x32_bf16 v[96:99], v[172:175], v[200:203], v[96:99]
	v_mfma_f32_16x16x32_bf16 v[88:91], v[180:183], v[200:203], v[88:91]
	v_mfma_f32_16x16x32_bf16 v[80:83], v[172:175], v[208:211], v[80:83]
	v_mfma_f32_16x16x32_bf16 v[72:75], v[180:183], v[208:211], v[72:75]
	v_mfma_f32_16x16x32_bf16 v[68:71], v[172:175], v[216:219], v[68:71]
	v_mfma_f32_16x16x32_bf16 v[64:67], v[180:183], v[216:219], v[64:67]
	s_setprio 0
	s_barrier
	s_add_i32 s84, s78, s5
	s_mov_b32 m0, s84
	ds_read_b128 v[184:187], v151 offset:16384
	ds_read_b128 v[188:191], v151 offset:17408
	ds_read_b128 v[192:195], v151 offset:18432
	ds_read_b128 v[200:203], v151 offset:19456
	ds_read_b128 v[204:207], v151 offset:20480
	ds_read_b128 v[208:211], v151 offset:21504
	ds_read_b128 v[212:215], v151 offset:22528
	ds_read_b128 v[216:219], v151 offset:23552
	global_load_lds_dwordx4 v130, s[70:71]
	s_add_i32 m0, s84, 0x2000
	s_add_u32 s84, s70, 0x80000
	s_addc_u32 s85, s71, 0
	s_add_i32 s86, s79, s5
	global_load_lds_dwordx4 v134, s[70:71]
	s_mov_b32 m0, s86
	s_nop 0
	global_load_lds_dwordx4 v130, s[84:85]
	s_add_i32 m0, s86, 0x2000
	s_nop 0
	global_load_lds_dwordx4 v134, s[84:85]
	s_mov_b32 m0, s6
	s_nop 0
	global_load_lds_dwordx4 v128, s[72:73]
	s_mov_b32 m0, s7
	s_nop 0
	global_load_lds_dwordx4 v132, s[72:73]
	s_waitcnt vmcnt(8)
	s_waitcnt lgkmcnt(0)
	s_setprio 1
	s_barrier
	v_mfma_f32_16x16x32_bf16 v[60:63], v[152:155], v[184:187], v[60:63]
	v_mfma_f32_16x16x32_bf16 v[56:59], v[160:163], v[184:187], v[56:59]
	v_mfma_f32_16x16x32_bf16 v[52:55], v[152:155], v[192:195], v[52:55]
	v_mfma_f32_16x16x32_bf16 v[44:47], v[160:163], v[192:195], v[44:47]
	v_mfma_f32_16x16x32_bf16 v[36:39], v[152:155], v[204:207], v[36:39]
	v_mfma_f32_16x16x32_bf16 v[28:31], v[160:163], v[204:207], v[28:31]
	v_mfma_f32_16x16x32_bf16 v[20:23], v[152:155], v[212:215], v[20:23]
	v_mfma_f32_16x16x32_bf16 v[12:15], v[160:163], v[212:215], v[12:15]
	v_mfma_f32_16x16x32_bf16 v[60:63], v[156:159], v[188:191], v[60:63]
	v_mfma_f32_16x16x32_bf16 v[56:59], v[164:167], v[188:191], v[56:59]
	v_mfma_f32_16x16x32_bf16 v[52:55], v[156:159], v[200:203], v[52:55]
	v_mfma_f32_16x16x32_bf16 v[44:47], v[164:167], v[200:203], v[44:47]
	v_mfma_f32_16x16x32_bf16 v[36:39], v[156:159], v[208:211], v[36:39]
	v_mfma_f32_16x16x32_bf16 v[28:31], v[164:167], v[208:211], v[28:31]
	v_mfma_f32_16x16x32_bf16 v[20:23], v[156:159], v[216:219], v[20:23]
	v_mfma_f32_16x16x32_bf16 v[12:15], v[164:167], v[216:219], v[12:15]
	v_mfma_f32_16x16x32_bf16 v[48:51], v[168:171], v[184:187], v[48:51]
	v_mfma_f32_16x16x32_bf16 v[40:43], v[176:179], v[184:187], v[40:43]
	v_mfma_f32_16x16x32_bf16 v[32:35], v[168:171], v[192:195], v[32:35]
	v_mfma_f32_16x16x32_bf16 v[24:27], v[176:179], v[192:195], v[24:27]
	v_mfma_f32_16x16x32_bf16 v[16:19], v[168:171], v[204:207], v[16:19]
	v_mfma_f32_16x16x32_bf16 v[8:11], v[176:179], v[204:207], v[8:11]
	v_mfma_f32_16x16x32_bf16 v[4:7], v[168:171], v[212:215], v[4:7]
	v_mfma_f32_16x16x32_bf16 v[0:3], v[176:179], v[212:215], v[0:3]
	v_mfma_f32_16x16x32_bf16 v[48:51], v[172:175], v[188:191], v[48:51]
	v_mfma_f32_16x16x32_bf16 v[40:43], v[180:183], v[188:191], v[40:43]
	v_mfma_f32_16x16x32_bf16 v[32:35], v[172:175], v[200:203], v[32:35]
	v_mfma_f32_16x16x32_bf16 v[24:27], v[180:183], v[200:203], v[24:27]
	v_mfma_f32_16x16x32_bf16 v[16:19], v[172:175], v[208:211], v[16:19]
	v_mfma_f32_16x16x32_bf16 v[8:11], v[180:183], v[208:211], v[8:11]
	v_mfma_f32_16x16x32_bf16 v[4:7], v[172:175], v[216:219], v[4:7]
	v_mfma_f32_16x16x32_bf16 v[0:3], v[180:183], v[216:219], v[0:3]
	s_setprio 0
	s_barrier
; #define PG8_STAGE(bufoff, gbase, voff) do { _Pragma("unroll") for (int _i = 0; _i < 2; ++_i) \
;         __builtin_amdgcn_global_load_lds((const unsigned*)((const char*)(gbase) + (voff)[_i]), (PG8_LAS unsigned*)(lds + (bufoff) + ldsw + _i * 8192), 16, 0, 0); } while (0)
; #define PG8_LDA(dst, b, h) do { _Pragma("unroll") for (int m = 0; m < 4; ++m) _Pragma("unroll") for (int k = 0; k < 2; ++k) dst[m][k] = *(const PG8_LAS bf16x8*)(lds + PG8_SA(b, h) + aoff + m * 2048 + k * 1024); } while (0)
; #define PG8_LDB(dst, b, h) do { _Pragma("unroll") for (int n = 0; n < 2; ++n) _Pragma("unroll") for (int k = 0; k < 2; ++k) dst[n][k] = *(const PG8_LAS bf16x8*)(lds + PG8_SB(b, h) + boff + n * 2048 + k * 1024); } while (0)
; #define PG8_MMA(ai, bj, At, Bt) do { __builtin_amdgcn_s_setprio(1); _Pragma("unroll") for (int m = 0; m < 4; ++m) _Pragma("unroll") for (int n = 0; n < 2; ++n) _Pragma("unroll") for (int k = 0; k < 2; ++k) \
;         acc[ai][bj][m][n] = __builtin_amdgcn_mfma_f32_16x16x32_bf16(Bt[n][k], At[m][k], acc[ai][bj][m][n], 0, 0, 0); __builtin_amdgcn_s_setprio(0); } while (0)
; #define PG8_WAIT_V(n) asm volatile("s_waitcnt vmcnt(" #n ")" ::: "memory")
; #define PG8_WAIT_L(n) asm volatile("s_waitcnt lgkmcnt(" #n ")" ::: "memory")
; #define PG8_BAR __builtin_amdgcn_s_barrier()
; #define PG8_SCHED __builtin_amdgcn_sched_barrier(0)
; template <class Epi, class Sched, bool ALIGN_EPI = false, bool SP2 = false>
; __device__ __forceinline__ void gemm_phase(PG8_LAS unsigned char* lds, const Gemm g, const Sched& S, const Epi& E) {
;     ...
;             PG8_LDB(B0, 1, 0); PG8_LDB(B1, 1, 1); PG8_SCHED; PG8_LDA(At, 1, 0); PG8_STAGE(PG8_SA(0, 1), a2 + hstep, voffA);
;             PG8_WAIT_V(8); PG8_WAIT_L(0); PG8_BAR; PG8_MMA(0, 0, At, B0); PG8_MMA(0, 1, At, B1); PG8_BAR; PG8_SCHED;
;             PG8_LDA(At, 1, 1); PG8_STAGE(PG8_SB(1, 0), b3, voffB); PG8_STAGE(PG8_SB(1, 1), b3 + hstep, voffB); PG8_STAGE(PG8_SA(1, 0), a3, voffA);
;             PG8_WAIT_V(8); PG8_WAIT_L(0); PG8_BAR; PG8_MMA(1, 0, At, B0); PG8_MMA(1, 1, At, B1); PG8_BAR; PG8_SCHED;
;     ...
;         if constexpr (ALIGN_EPI) { if (wr == 0) PG8_BAR; }
	ds_read_b128 v[152:155], v198
	ds_read_b128 v[156:159], v198 offset:1024
	ds_read_b128 v[160:163], v198 offset:2048
	ds_read_b128 v[164:167], v198 offset:3072
	ds_read_b128 v[168:171], v199
	ds_read_b128 v[172:175], v199 offset:1024
	ds_read_b128 v[176:179], v199 offset:2048
	ds_read_b128 v[180:183], v199 offset:3072
	ds_read_b128 v[184:187], v151 offset:32768
	ds_read_b128 v[188:191], v151 offset:33792
	ds_read_b128 v[192:195], v151 offset:34816
	ds_read_b128 v[200:203], v151 offset:35840
	ds_read_b128 v[204:207], v151 offset:36864
	ds_read_b128 v[208:211], v151 offset:37888
	ds_read_b128 v[212:215], v151 offset:38912
	ds_read_b128 v[216:219], v151 offset:39936
	s_add_u32 s98, s72, 0x80000
	s_addc_u32 s99, s73, 0
	s_mov_b32 m0, s14
	s_add_u32 s100, s72, 0x80
	s_addc_u32 s101, s73, 0
	global_load_lds_dwordx4 v128, s[98:99]
	s_mov_b32 m0, s15
	s_nop 0
	global_load_lds_dwordx4 v132, s[98:99]
	s_add_i32 s84, 0, 0x18000
	s_add_i32 s85, 0, 0x1c000
	s_waitcnt vmcnt(8)
	s_waitcnt lgkmcnt(0)
	s_setprio 1
	s_barrier
	v_mfma_f32_16x16x32_bf16 v[124:127], v[152:155], v[184:187], v[124:127]
	v_mfma_f32_16x16x32_bf16 v[120:123], v[160:163], v[184:187], v[120:123]
	v_mfma_f32_16x16x32_bf16 v[112:115], v[152:155], v[192:195], v[112:115]
	v_mfma_f32_16x16x32_bf16 v[104:107], v[160:163], v[192:195], v[104:107]
	v_mfma_f32_16x16x32_bf16 v[100:103], v[152:155], v[204:207], v[100:103]
	v_mfma_f32_16x16x32_bf16 v[92:95], v[160:163], v[204:207], v[92:95]
	v_mfma_f32_16x16x32_bf16 v[84:87], v[152:155], v[212:215], v[84:87]
	v_mfma_f32_16x16x32_bf16 v[76:79], v[160:163], v[212:215], v[76:79]
	v_mfma_f32_16x16x32_bf16 v[124:127], v[156:159], v[188:191], v[124:127]
	v_mfma_f32_16x16x32_bf16 v[120:123], v[164:167], v[188:191], v[120:123]
	v_mfma_f32_16x16x32_bf16 v[112:115], v[156:159], v[200:203], v[112:115]
	v_mfma_f32_16x16x32_bf16 v[104:107], v[164:167], v[200:203], v[104:107]
	v_mfma_f32_16x16x32_bf16 v[100:103], v[156:159], v[208:211], v[100:103]
	v_mfma_f32_16x16x32_bf16 v[92:95], v[164:167], v[208:211], v[92:95]
	v_mfma_f32_16x16x32_bf16 v[84:87], v[156:159], v[216:219], v[84:87]
	v_mfma_f32_16x16x32_bf16 v[76:79], v[164:167], v[216:219], v[76:79]
	v_mfma_f32_16x16x32_bf16 v[116:119], v[168:171], v[184:187], v[116:119]
	v_mfma_f32_16x16x32_bf16 v[108:111], v[176:179], v[184:187], v[108:111]
	v_mfma_f32_16x16x32_bf16 v[96:99], v[168:171], v[192:195], v[96:99]
	v_mfma_f32_16x16x32_bf16 v[88:91], v[176:179], v[192:195], v[88:91]
	v_mfma_f32_16x16x32_bf16 v[80:83], v[168:171], v[204:207], v[80:83]
	v_mfma_f32_16x16x32_bf16 v[72:75], v[176:179], v[204:207], v[72:75]
	v_mfma_f32_16x16x32_bf16 v[68:71], v[168:171], v[212:215], v[68:71]
	v_mfma_f32_16x16x32_bf16 v[64:67], v[176:179], v[212:215], v[64:67]
	v_mfma_f32_16x16x32_bf16 v[116:119], v[172:175], v[188:191], v[116:119]
	v_mfma_f32_16x16x32_bf16 v[108:111], v[180:183], v[188:191], v[108:111]
	v_mfma_f32_16x16x32_bf16 v[96:99], v[172:175], v[200:203], v[96:99]
	v_mfma_f32_16x16x32_bf16 v[88:91], v[180:183], v[200:203], v[88:91]
	v_mfma_f32_16x16x32_bf16 v[80:83], v[172:175], v[208:211], v[80:83]
	v_mfma_f32_16x16x32_bf16 v[72:75], v[180:183], v[208:211], v[72:75]
	v_mfma_f32_16x16x32_bf16 v[68:71], v[172:175], v[216:219], v[68:71]
	v_mfma_f32_16x16x32_bf16 v[64:67], v[180:183], v[216:219], v[64:67]
	s_setprio 0
	s_barrier
	s_add_u32 s98, s70, 0x80
	s_addc_u32 s99, s71, 0
	s_add_i32 s72, s84, s5
	s_mov_b32 m0, s72
	ds_read_b128 v[184:187], v151 offset:49152
	ds_read_b128 v[188:191], v151 offset:50176
	ds_read_b128 v[192:195], v151 offset:51200
	ds_read_b128 v[200:203], v151 offset:52224
	ds_read_b128 v[204:207], v151 offset:53248
	ds_read_b128 v[208:211], v151 offset:54272
	ds_read_b128 v[212:215], v151 offset:55296
	ds_read_b128 v[216:219], v151 offset:56320
	global_load_lds_dwordx4 v130, s[98:99]
	s_add_i32 m0, s72, 0x2000
	s_add_u32 s70, s70, 0x80080
	s_addc_u32 s71, s71, 0
	s_add_i32 s72, s85, s5
	global_load_lds_dwordx4 v134, s[98:99]
	s_mov_b32 m0, s72
	s_nop 0
	global_load_lds_dwordx4 v130, s[70:71]
	s_add_i32 m0, s72, 0x2000
	s_nop 0
	global_load_lds_dwordx4 v134, s[70:71]
	s_mov_b32 m0, s74
	s_nop 0
	global_load_lds_dwordx4 v128, s[100:101]
	s_mov_b32 m0, s75
	s_nop 0
	global_load_lds_dwordx4 v132, s[100:101]
	s_waitcnt vmcnt(8)
	s_waitcnt lgkmcnt(0)
	s_setprio 1
	s_barrier
	v_mfma_f32_16x16x32_bf16 v[60:63], v[152:155], v[184:187], v[60:63]
	v_mfma_f32_16x16x32_bf16 v[56:59], v[160:163], v[184:187], v[56:59]
	v_mfma_f32_16x16x32_bf16 v[52:55], v[152:155], v[192:195], v[52:55]
	v_mfma_f32_16x16x32_bf16 v[44:47], v[160:163], v[192:195], v[44:47]
	v_mfma_f32_16x16x32_bf16 v[36:39], v[152:155], v[204:207], v[36:39]
	v_mfma_f32_16x16x32_bf16 v[28:31], v[160:163], v[204:207], v[28:31]
	v_mfma_f32_16x16x32_bf16 v[20:23], v[152:155], v[212:215], v[20:23]
	v_mfma_f32_16x16x32_bf16 v[12:15], v[160:163], v[212:215], v[12:15]
	v_mfma_f32_16x16x32_bf16 v[60:63], v[156:159], v[188:191], v[60:63]
	v_mfma_f32_16x16x32_bf16 v[56:59], v[164:167], v[188:191], v[56:59]
	v_mfma_f32_16x16x32_bf16 v[52:55], v[156:159], v[200:203], v[52:55]
	v_mfma_f32_16x16x32_bf16 v[44:47], v[164:167], v[200:203], v[44:47]
	v_mfma_f32_16x16x32_bf16 v[36:39], v[156:159], v[208:211], v[36:39]
	v_mfma_f32_16x16x32_bf16 v[28:31], v[164:167], v[208:211], v[28:31]
	v_mfma_f32_16x16x32_bf16 v[20:23], v[156:159], v[216:219], v[20:23]
	v_mfma_f32_16x16x32_bf16 v[12:15], v[164:167], v[216:219], v[12:15]
	v_mfma_f32_16x16x32_bf16 v[48:51], v[168:171], v[184:187], v[48:51]
	v_mfma_f32_16x16x32_bf16 v[40:43], v[176:179], v[184:187], v[40:43]
	v_mfma_f32_16x16x32_bf16 v[32:35], v[168:171], v[192:195], v[32:35]
	v_mfma_f32_16x16x32_bf16 v[24:27], v[176:179], v[192:195], v[24:27]
	v_mfma_f32_16x16x32_bf16 v[16:19], v[168:171], v[204:207], v[16:19]
	v_mfma_f32_16x16x32_bf16 v[8:11], v[176:179], v[204:207], v[8:11]
	v_mfma_f32_16x16x32_bf16 v[4:7], v[168:171], v[212:215], v[4:7]
	v_mfma_f32_16x16x32_bf16 v[0:3], v[176:179], v[212:215], v[0:3]
	v_mfma_f32_16x16x32_bf16 v[48:51], v[172:175], v[188:191], v[48:51]
	v_mfma_f32_16x16x32_bf16 v[40:43], v[180:183], v[188:191], v[40:43]
	v_mfma_f32_16x16x32_bf16 v[32:35], v[172:175], v[200:203], v[32:35]
	v_mfma_f32_16x16x32_bf16 v[24:27], v[180:183], v[200:203], v[24:27]
	v_mfma_f32_16x16x32_bf16 v[16:19], v[172:175], v[208:211], v[16:19]
	v_mfma_f32_16x16x32_bf16 v[8:11], v[180:183], v[208:211], v[8:11]
	v_mfma_f32_16x16x32_bf16 v[4:7], v[172:175], v[216:219], v[4:7]
	v_mfma_f32_16x16x32_bf16 v[0:3], v[180:183], v[216:219], v[0:3]
	s_setprio 0
	s_barrier
	s_add_i32 s83, s83, 2
	s_add_u32 s68, s68, 0x100
	s_addc_u32 s69, s69, 0
	s_add_u32 s81, s81, 0x100
	s_addc_u32 s82, s82, 0
	s_cmp_gt_u32 s83, 29
	s_cbranch_scc0 .LBB0_759
	s_and_b64 vcc, exec, s[46:47]
	s_cbranch_vccz .LBB0_762
	s_barrier

; #define PG8_STAGE(bufoff, gbase, voff) do { _Pragma("unroll") for (int _i = 0; _i < 2; ++_i) \
;         __builtin_amdgcn_global_load_lds((const unsigned*)((const char*)(gbase) + (voff)[_i]), (PG8_LAS unsigned*)(lds + (bufoff) + ldsw + _i * 8192), 16, 0, 0); } while (0)
; #define PG8_LDA(dst, b, h) do { _Pragma("unroll") for (int m = 0; m < 4; ++m) _Pragma("unroll") for (int k = 0; k < 2; ++k) dst[m][k] = *(const PG8_LAS bf16x8*)(lds + PG8_SA(b, h) + aoff + m * 2048 + k * 1024); } while (0)
; #define PG8_LDB(dst, b, h) do { _Pragma("unroll") for (int n = 0; n < 2; ++n) _Pragma("unroll") for (int k = 0; k < 2; ++k) dst[n][k] = *(const PG8_LAS bf16x8*)(lds + PG8_SB(b, h) + boff + n * 2048 + k * 1024); } while (0)
; #define PG8_MMA(ai, bj, At, Bt) do { __builtin_amdgcn_s_setprio(1); _Pragma("unroll") for (int m = 0; m < 4; ++m) _Pragma("unroll") for (int n = 0; n < 2; ++n) _Pragma("unroll") for (int k = 0; k < 2; ++k) \
;         acc[ai][bj][m][n] = __builtin_amdgcn_mfma_f32_16x16x32_bf16(Bt[n][k], At[m][k], acc[ai][bj][m][n], 0, 0, 0); __builtin_amdgcn_s_setprio(0); } while (0)
; #define PG8_WAIT_V(n) asm volatile("s_waitcnt vmcnt(" #n ")" ::: "memory")
; #define PG8_WAIT_L(n) asm volatile("s_waitcnt lgkmcnt(" #n ")" ::: "memory")
; #define PG8_BAR __builtin_amdgcn_s_barrier()
; #define PG8_SCHED __builtin_amdgcn_sched_barrier(0)
; template <class Epi, class Sched, bool ALIGN_EPI = false, bool SP2 = false>
; __device__ __forceinline__ void gemm_phase(PG8_LAS unsigned char* lds, const Gemm g, const Sched& S, const Epi& E) {
;     ...
;             const char* a2 = last ? nA : cA + (size_t)(t + 2) * kstep; const char* b2 = last ? nB : cB + (size_t)(t + 2) * kstep;
;             const char* a3 = a2 + kstep; const char* b3 = b2 + kstep;
;             if (last && has_next) S.a_ready(nxt);
;             if constexpr (SP2) {
;             PG8_LDB(B0, 0, 0); PG8_LDB(B1, 0, 1); PG8_SCHED; PG8_LDA(At, 0, 0); PG8_STAGE(PG8_SA(1, 1), a1 + hstep, voffA);
;             PG8_WAIT_V(8); PG8_WAIT_L(0); PG8_BAR; PG8_MMA(0, 0, At, B0); PG8_MMA(0, 1, At, B1); PG8_BAR; PG8_SCHED;
;             PG8_LDA(At, 0, 1); PG8_STAGE(PG8_SB(0, 0), b2, voffB); PG8_STAGE(PG8_SB(0, 1), b2 + hstep, voffB); PG8_STAGE(PG8_SA(0, 0), a2, voffA);
;             PG8_WAIT_V(8); PG8_WAIT_L(0); PG8_BAR; PG8_MMA(1, 0, At, B0); PG8_MMA(1, 1, At, B1); PG8_BAR; PG8_SCHED;
.LBB0_1053:
	ds_read_b128 v[128:131], v202
	ds_read_b128 v[132:135], v202 offset:1024
	ds_read_b128 v[136:139], v202 offset:2048
	ds_read_b128 v[140:143], v202 offset:3072
	ds_read_b128 v[144:147], v203
	ds_read_b128 v[148:151], v203 offset:1024
	ds_read_b128 v[152:155], v203 offset:2048
	ds_read_b128 v[156:159], v203 offset:3072
	s_add_i32 m0, s3, 0xc000
	ds_read_b128 v[160:163], v204
	ds_read_b128 v[164:167], v204 offset:1024
	ds_read_b128 v[184:187], v204 offset:2048
	ds_read_b128 v[188:191], v204 offset:3072
	ds_read_b128 v[192:195], v204 offset:4096
	ds_read_b128 v[206:209], v204 offset:5120
	ds_read_b128 v[210:213], v204 offset:6144
	ds_read_b128 v[214:217], v204 offset:7168
	global_load_lds_dwordx4 v176, s[60:61]
	s_add_i32 m0, s3, 0xe000
	s_nop 0
	global_load_lds_dwordx4 v178, s[60:61]
	s_add_u32 s62, s60, 0xfff80080
	s_addc_u32 s63, s61, -1
	s_cmp_eq_u32 s72, 28
	s_cselect_b32 s65, s25, s63
	s_cselect_b32 s64, s43, s62
	s_cselect_b32 s63, s39, s71
	s_cselect_b32 s62, s69, s70
	s_waitcnt vmcnt(8)
	s_waitcnt lgkmcnt(0)
	s_setprio 1
	s_barrier
	v_mfma_f32_16x16x32_bf16 v[124:127], v[128:131], v[160:163], v[124:127]
	v_mfma_f32_16x16x32_bf16 v[120:123], v[136:139], v[160:163], v[120:123]
	v_mfma_f32_16x16x32_bf16 v[116:119], v[128:131], v[184:187], v[116:119]
	v_mfma_f32_16x16x32_bf16 v[108:111], v[136:139], v[184:187], v[108:111]
	v_mfma_f32_16x16x32_bf16 v[92:95], v[128:131], v[192:195], v[92:95]
	v_mfma_f32_16x16x32_bf16 v[88:91], v[136:139], v[192:195], v[88:91]
	v_mfma_f32_16x16x32_bf16 v[76:79], v[128:131], v[210:213], v[76:79]
	v_mfma_f32_16x16x32_bf16 v[72:75], v[136:139], v[210:213], v[72:75]
	v_mfma_f32_16x16x32_bf16 v[124:127], v[132:135], v[164:167], v[124:127]
	v_mfma_f32_16x16x32_bf16 v[120:123], v[140:143], v[164:167], v[120:123]
	v_mfma_f32_16x16x32_bf16 v[116:119], v[132:135], v[188:191], v[116:119]
	v_mfma_f32_16x16x32_bf16 v[108:111], v[140:143], v[188:191], v[108:111]
	v_mfma_f32_16x16x32_bf16 v[92:95], v[132:135], v[206:209], v[92:95]
	v_mfma_f32_16x16x32_bf16 v[88:91], v[140:143], v[206:209], v[88:91]
	v_mfma_f32_16x16x32_bf16 v[76:79], v[132:135], v[214:217], v[76:79]
	v_mfma_f32_16x16x32_bf16 v[72:75], v[140:143], v[214:217], v[72:75]
	v_mfma_f32_16x16x32_bf16 v[112:115], v[144:147], v[160:163], v[112:115]
	v_mfma_f32_16x16x32_bf16 v[104:107], v[152:155], v[160:163], v[104:107]
	v_mfma_f32_16x16x32_bf16 v[100:103], v[144:147], v[184:187], v[100:103]
	v_mfma_f32_16x16x32_bf16 v[96:99], v[152:155], v[184:187], v[96:99]
	v_mfma_f32_16x16x32_bf16 v[84:87], v[144:147], v[192:195], v[84:87]
	v_mfma_f32_16x16x32_bf16 v[80:83], v[152:155], v[192:195], v[80:83]
	v_mfma_f32_16x16x32_bf16 v[68:71], v[144:147], v[210:213], v[68:71]
	v_mfma_f32_16x16x32_bf16 v[64:67], v[152:155], v[210:213], v[64:67]
	v_mfma_f32_16x16x32_bf16 v[112:115], v[148:151], v[164:167], v[112:115]
	v_mfma_f32_16x16x32_bf16 v[104:107], v[156:159], v[164:167], v[104:107]
	v_mfma_f32_16x16x32_bf16 v[100:103], v[148:151], v[188:191], v[100:103]
	v_mfma_f32_16x16x32_bf16 v[96:99], v[156:159], v[188:191], v[96:99]
	v_mfma_f32_16x16x32_bf16 v[84:87], v[148:151], v[206:209], v[84:87]
	v_mfma_f32_16x16x32_bf16 v[80:83], v[156:159], v[206:209], v[80:83]
	v_mfma_f32_16x16x32_bf16 v[68:71], v[148:151], v[214:217], v[68:71]
	v_mfma_f32_16x16x32_bf16 v[64:67], v[156:159], v[214:217], v[64:67]
	s_setprio 0
	s_barrier
	s_add_i32 s73, s67, s1
	s_mov_b32 m0, s73
	ds_read_b128 v[160:163], v204 offset:16384
	ds_read_b128 v[164:167], v204 offset:17408
	ds_read_b128 v[184:187], v204 offset:18432
	ds_read_b128 v[188:191], v204 offset:19456
	ds_read_b128 v[192:195], v204 offset:20480
	ds_read_b128 v[206:209], v204 offset:21504
	ds_read_b128 v[210:213], v204 offset:22528
	ds_read_b128 v[214:217], v204 offset:23552
	global_load_lds_dwordx4 v170, s[62:63]
	s_add_i32 m0, s73, 0x2000
	s_add_u32 s74, s62, 0x80000
	s_addc_u32 s75, s63, 0
	s_add_i32 s73, s68, s1
	global_load_lds_dwordx4 v174, s[62:63]
	s_mov_b32 m0, s73
	s_nop 0
	global_load_lds_dwordx4 v170, s[74:75]
	s_add_i32 m0, s73, 0x2000
	s_nop 0
	global_load_lds_dwordx4 v174, s[74:75]
	s_mov_b32 m0, s3
	s_nop 0
	global_load_lds_dwordx4 v168, s[64:65]
	s_mov_b32 m0, s4
	s_nop 0
	global_load_lds_dwordx4 v172, s[64:65]
	s_waitcnt vmcnt(8)
	s_waitcnt lgkmcnt(0)
	s_setprio 1
	s_barrier
	v_mfma_f32_16x16x32_bf16 v[60:63], v[128:131], v[160:163], v[60:63]
	v_mfma_f32_16x16x32_bf16 v[56:59], v[136:139], v[160:163], v[56:59]
	v_mfma_f32_16x16x32_bf16 v[44:47], v[128:131], v[184:187], v[44:47]
	v_mfma_f32_16x16x32_bf16 v[40:43], v[136:139], v[184:187], v[40:43]
	v_mfma_f32_16x16x32_bf16 v[28:31], v[128:131], v[192:195], v[28:31]
	v_mfma_f32_16x16x32_bf16 v[24:27], v[136:139], v[192:195], v[24:27]
	v_mfma_f32_16x16x32_bf16 v[12:15], v[128:131], v[210:213], v[12:15]
	v_mfma_f32_16x16x32_bf16 v[8:11], v[136:139], v[210:213], v[8:11]
	v_mfma_f32_16x16x32_bf16 v[60:63], v[132:135], v[164:167], v[60:63]
	v_mfma_f32_16x16x32_bf16 v[56:59], v[140:143], v[164:167], v[56:59]
	v_mfma_f32_16x16x32_bf16 v[44:47], v[132:135], v[188:191], v[44:47]
	v_mfma_f32_16x16x32_bf16 v[40:43], v[140:143], v[188:191], v[40:43]
	v_mfma_f32_16x16x32_bf16 v[28:31], v[132:135], v[206:209], v[28:31]
	v_mfma_f32_16x16x32_bf16 v[24:27], v[140:143], v[206:209], v[24:27]
	v_mfma_f32_16x16x32_bf16 v[12:15], v[132:135], v[214:217], v[12:15]
	v_mfma_f32_16x16x32_bf16 v[8:11], v[140:143], v[214:217], v[8:11]
	v_mfma_f32_16x16x32_bf16 v[52:55], v[144:147], v[160:163], v[52:55]
	v_mfma_f32_16x16x32_bf16 v[48:51], v[152:155], v[160:163], v[48:51]
	v_mfma_f32_16x16x32_bf16 v[36:39], v[144:147], v[184:187], v[36:39]
	v_mfma_f32_16x16x32_bf16 v[32:35], v[152:155], v[184:187], v[32:35]
	v_mfma_f32_16x16x32_bf16 v[20:23], v[144:147], v[192:195], v[20:23]
	v_mfma_f32_16x16x32_bf16 v[16:19], v[152:155], v[192:195], v[16:19]
	v_mfma_f32_16x16x32_bf16 v[4:7], v[144:147], v[210:213], v[4:7]
	v_mfma_f32_16x16x32_bf16 v[0:3], v[152:155], v[210:213], v[0:3]
	v_mfma_f32_16x16x32_bf16 v[52:55], v[148:151], v[164:167], v[52:55]
	v_mfma_f32_16x16x32_bf16 v[48:51], v[156:159], v[164:167], v[48:51]
	v_mfma_f32_16x16x32_bf16 v[36:39], v[148:151], v[188:191], v[36:39]
	v_mfma_f32_16x16x32_bf16 v[32:35], v[156:159], v[188:191], v[32:35]
	v_mfma_f32_16x16x32_bf16 v[20:23], v[148:151], v[206:209], v[20:23]
	v_mfma_f32_16x16x32_bf16 v[16:19], v[156:159], v[206:209], v[16:19]
	v_mfma_f32_16x16x32_bf16 v[4:7], v[148:151], v[214:217], v[4:7]
	v_mfma_f32_16x16x32_bf16 v[0:3], v[156:159], v[214:217], v[0:3]
	s_setprio 0
	s_barrier
; #define PG8_STAGE(bufoff, gbase, voff) do { _Pragma("unroll") for (int _i = 0; _i < 2; ++_i) \
;         __builtin_amdgcn_global_load_lds((const unsigned*)((const char*)(gbase) + (voff)[_i]), (PG8_LAS unsigned*)(lds + (bufoff) + ldsw + _i * 8192), 16, 0, 0); } while (0)
; #define PG8_LDA(dst, b, h) do { _Pragma("unroll") for (int m = 0; m < 4; ++m) _Pragma("unroll") for (int k = 0; k < 2; ++k) dst[m][k] = *(const PG8_LAS bf16x8*)(lds + PG8_SA(b, h) + aoff + m * 2048 + k * 1024); } while (0)
; #define PG8_LDB(dst, b, h) do { _Pragma("unroll") for (int n = 0; n < 2; ++n) _Pragma("unroll") for (int k = 0; k < 2; ++k) dst[n][k] = *(const PG8_LAS bf16x8*)(lds + PG8_SB(b, h) + boff + n * 2048 + k * 1024); } while (0)
; #define PG8_MMA(ai, bj, At, Bt) do { __builtin_amdgcn_s_setprio(1); _Pragma("unroll") for (int m = 0; m < 4; ++m) _Pragma("unroll") for (int n = 0; n < 2; ++n) _Pragma("unroll") for (int k = 0; k < 2; ++k) \
;         acc[ai][bj][m][n] = __builtin_amdgcn_mfma_f32_16x16x32_bf16(Bt[n][k], At[m][k], acc[ai][bj][m][n], 0, 0, 0); __builtin_amdgcn_s_setprio(0); } while (0)
; #define PG8_WAIT_V(n) asm volatile("s_waitcnt vmcnt(" #n ")" ::: "memory")
; #define PG8_WAIT_L(n) asm volatile("s_waitcnt lgkmcnt(" #n ")" ::: "memory")
; #define PG8_BAR __builtin_amdgcn_s_barrier()
; #define PG8_SCHED __builtin_amdgcn_sched_barrier(0)
; template <class Epi, class Sched, bool ALIGN_EPI = false, bool SP2 = false>
; __device__ __forceinline__ void gemm_phase(PG8_LAS unsigned char* lds, const Gemm g, const Sched& S, const Epi& E) {
;     ...
;             PG8_LDB(B0, 1, 0); PG8_LDB(B1, 1, 1); PG8_SCHED; PG8_LDA(At, 1, 0); PG8_STAGE(PG8_SA(0, 1), a2 + hstep, voffA);
;             PG8_WAIT_V(8); PG8_WAIT_L(0); PG8_BAR; PG8_MMA(0, 0, At, B0); PG8_MMA(0, 1, At, B1); PG8_BAR; PG8_SCHED;
;             PG8_LDA(At, 1, 1); PG8_STAGE(PG8_SB(1, 0), b3, voffB); PG8_STAGE(PG8_SB(1, 1), b3 + hstep, voffB); PG8_STAGE(PG8_SA(1, 0), a3, voffA);
;             PG8_WAIT_V(8); PG8_WAIT_L(0); PG8_BAR; PG8_MMA(1, 0, At, B0); PG8_MMA(1, 1, At, B1); PG8_BAR; PG8_SCHED;
;     ...
;         if constexpr (ALIGN_EPI) { if (wr == 0) PG8_BAR; }
	ds_read_b128 v[128:131], v218
	ds_read_b128 v[132:135], v218 offset:1024
	ds_read_b128 v[136:139], v218 offset:2048
	ds_read_b128 v[140:143], v218 offset:3072
	ds_read_b128 v[144:147], v219
	ds_read_b128 v[148:151], v219 offset:1024
	ds_read_b128 v[152:155], v219 offset:2048
	ds_read_b128 v[156:159], v219 offset:3072
	ds_read_b128 v[160:163], v204 offset:32768
	ds_read_b128 v[164:167], v204 offset:33792
	ds_read_b128 v[184:187], v204 offset:34816
	ds_read_b128 v[188:191], v204 offset:35840
	ds_read_b128 v[192:195], v204 offset:36864
	ds_read_b128 v[206:209], v204 offset:37888
	ds_read_b128 v[210:213], v204 offset:38912
	ds_read_b128 v[214:217], v204 offset:39936
	s_add_u32 s98, s64, 0x80000
	s_addc_u32 s99, s65, 0
	s_mov_b32 m0, s5
	s_add_u32 s100, s64, 0x80
	s_addc_u32 s101, s65, 0
	global_load_lds_dwordx4 v168, s[98:99]
	s_mov_b32 m0, s14
	s_nop 0
	global_load_lds_dwordx4 v172, s[98:99]
	s_add_i32 s73, 0, 0x18000
	s_add_i32 s74, 0, 0x1c000
	s_waitcnt vmcnt(8)
	s_waitcnt lgkmcnt(0)
	s_setprio 1
	s_barrier
	v_mfma_f32_16x16x32_bf16 v[124:127], v[128:131], v[160:163], v[124:127]
	v_mfma_f32_16x16x32_bf16 v[120:123], v[136:139], v[160:163], v[120:123]
	v_mfma_f32_16x16x32_bf16 v[116:119], v[128:131], v[184:187], v[116:119]
	v_mfma_f32_16x16x32_bf16 v[108:111], v[136:139], v[184:187], v[108:111]
	v_mfma_f32_16x16x32_bf16 v[92:95], v[128:131], v[192:195], v[92:95]
	v_mfma_f32_16x16x32_bf16 v[88:91], v[136:139], v[192:195], v[88:91]
	v_mfma_f32_16x16x32_bf16 v[76:79], v[128:131], v[210:213], v[76:79]
	v_mfma_f32_16x16x32_bf16 v[72:75], v[136:139], v[210:213], v[72:75]
	v_mfma_f32_16x16x32_bf16 v[124:127], v[132:135], v[164:167], v[124:127]
	v_mfma_f32_16x16x32_bf16 v[120:123], v[140:143], v[164:167], v[120:123]
	v_mfma_f32_16x16x32_bf16 v[116:119], v[132:135], v[188:191], v[116:119]
	v_mfma_f32_16x16x32_bf16 v[108:111], v[140:143], v[188:191], v[108:111]
	v_mfma_f32_16x16x32_bf16 v[92:95], v[132:135], v[206:209], v[92:95]
	v_mfma_f32_16x16x32_bf16 v[88:91], v[140:143], v[206:209], v[88:91]
	v_mfma_f32_16x16x32_bf16 v[76:79], v[132:135], v[214:217], v[76:79]
	v_mfma_f32_16x16x32_bf16 v[72:75], v[140:143], v[214:217], v[72:75]
	v_mfma_f32_16x16x32_bf16 v[112:115], v[144:147], v[160:163], v[112:115]
	v_mfma_f32_16x16x32_bf16 v[104:107], v[152:155], v[160:163], v[104:107]
	v_mfma_f32_16x16x32_bf16 v[100:103], v[144:147], v[184:187], v[100:103]
	v_mfma_f32_16x16x32_bf16 v[96:99], v[152:155], v[184:187], v[96:99]
	v_mfma_f32_16x16x32_bf16 v[84:87], v[144:147], v[192:195], v[84:87]
	v_mfma_f32_16x16x32_bf16 v[80:83], v[152:155], v[192:195], v[80:83]
	v_mfma_f32_16x16x32_bf16 v[68:71], v[144:147], v[210:213], v[68:71]
	v_mfma_f32_16x16x32_bf16 v[64:67], v[152:155], v[210:213], v[64:67]
	v_mfma_f32_16x16x32_bf16 v[112:115], v[148:151], v[164:167], v[112:115]
	v_mfma_f32_16x16x32_bf16 v[104:107], v[156:159], v[164:167], v[104:107]
	v_mfma_f32_16x16x32_bf16 v[100:103], v[148:151], v[188:191], v[100:103]
	v_mfma_f32_16x16x32_bf16 v[96:99], v[156:159], v[188:191], v[96:99]
	v_mfma_f32_16x16x32_bf16 v[84:87], v[148:151], v[206:209], v[84:87]
	v_mfma_f32_16x16x32_bf16 v[80:83], v[156:159], v[206:209], v[80:83]
	v_mfma_f32_16x16x32_bf16 v[68:71], v[148:151], v[214:217], v[68:71]
	v_mfma_f32_16x16x32_bf16 v[64:67], v[156:159], v[214:217], v[64:67]
	s_setprio 0
	s_barrier
	s_add_u32 s98, s62, 0x80
	s_addc_u32 s99, s63, 0
	s_add_i32 s64, s73, s1
	s_mov_b32 m0, s64
	ds_read_b128 v[160:163], v204 offset:49152
	ds_read_b128 v[164:167], v204 offset:50176
	ds_read_b128 v[184:187], v204 offset:51200
	ds_read_b128 v[188:191], v204 offset:52224
	ds_read_b128 v[192:195], v204 offset:53248
	ds_read_b128 v[206:209], v204 offset:54272
	ds_read_b128 v[210:213], v204 offset:55296
	ds_read_b128 v[214:217], v204 offset:56320
	global_load_lds_dwordx4 v170, s[98:99]
	s_add_i32 m0, s64, 0x2000
	s_add_u32 s62, s62, 0x80080
	s_addc_u32 s63, s63, 0
	s_add_i32 s64, s74, s1
	global_load_lds_dwordx4 v174, s[98:99]
	s_mov_b32 m0, s64
	s_nop 0
	global_load_lds_dwordx4 v170, s[62:63]
	s_add_i32 m0, s64, 0x2000
	s_nop 0
	global_load_lds_dwordx4 v174, s[62:63]
	s_mov_b32 m0, s33
	s_nop 0
	global_load_lds_dwordx4 v168, s[100:101]
	s_mov_b32 m0, s35
	s_nop 0
	global_load_lds_dwordx4 v172, s[100:101]
	s_waitcnt vmcnt(8)
	s_waitcnt lgkmcnt(0)
	s_setprio 1
	s_barrier
	v_mfma_f32_16x16x32_bf16 v[60:63], v[128:131], v[160:163], v[60:63]
	v_mfma_f32_16x16x32_bf16 v[56:59], v[136:139], v[160:163], v[56:59]
	v_mfma_f32_16x16x32_bf16 v[44:47], v[128:131], v[184:187], v[44:47]
	v_mfma_f32_16x16x32_bf16 v[40:43], v[136:139], v[184:187], v[40:43]
	v_mfma_f32_16x16x32_bf16 v[28:31], v[128:131], v[192:195], v[28:31]
	v_mfma_f32_16x16x32_bf16 v[24:27], v[136:139], v[192:195], v[24:27]
	v_mfma_f32_16x16x32_bf16 v[12:15], v[128:131], v[210:213], v[12:15]
	v_mfma_f32_16x16x32_bf16 v[8:11], v[136:139], v[210:213], v[8:11]
	v_mfma_f32_16x16x32_bf16 v[60:63], v[132:135], v[164:167], v[60:63]
	v_mfma_f32_16x16x32_bf16 v[56:59], v[140:143], v[164:167], v[56:59]
	v_mfma_f32_16x16x32_bf16 v[44:47], v[132:135], v[188:191], v[44:47]
	v_mfma_f32_16x16x32_bf16 v[40:43], v[140:143], v[188:191], v[40:43]
	v_mfma_f32_16x16x32_bf16 v[28:31], v[132:135], v[206:209], v[28:31]
	v_mfma_f32_16x16x32_bf16 v[24:27], v[140:143], v[206:209], v[24:27]
	v_mfma_f32_16x16x32_bf16 v[12:15], v[132:135], v[214:217], v[12:15]
	v_mfma_f32_16x16x32_bf16 v[8:11], v[140:143], v[214:217], v[8:11]
	v_mfma_f32_16x16x32_bf16 v[52:55], v[144:147], v[160:163], v[52:55]
	v_mfma_f32_16x16x32_bf16 v[48:51], v[152:155], v[160:163], v[48:51]
	v_mfma_f32_16x16x32_bf16 v[36:39], v[144:147], v[184:187], v[36:39]
	v_mfma_f32_16x16x32_bf16 v[32:35], v[152:155], v[184:187], v[32:35]
	v_mfma_f32_16x16x32_bf16 v[20:23], v[144:147], v[192:195], v[20:23]
	v_mfma_f32_16x16x32_bf16 v[16:19], v[152:155], v[192:195], v[16:19]
	v_mfma_f32_16x16x32_bf16 v[4:7], v[144:147], v[210:213], v[4:7]
	v_mfma_f32_16x16x32_bf16 v[0:3], v[152:155], v[210:213], v[0:3]
	v_mfma_f32_16x16x32_bf16 v[52:55], v[148:151], v[164:167], v[52:55]
	v_mfma_f32_16x16x32_bf16 v[48:51], v[156:159], v[164:167], v[48:51]
	v_mfma_f32_16x16x32_bf16 v[36:39], v[148:151], v[188:191], v[36:39]
	v_mfma_f32_16x16x32_bf16 v[32:35], v[156:159], v[188:191], v[32:35]
	v_mfma_f32_16x16x32_bf16 v[20:23], v[148:151], v[206:209], v[20:23]
	v_mfma_f32_16x16x32_bf16 v[16:19], v[156:159], v[206:209], v[16:19]
	v_mfma_f32_16x16x32_bf16 v[4:7], v[148:151], v[214:217], v[4:7]
	v_mfma_f32_16x16x32_bf16 v[0:3], v[156:159], v[214:217], v[0:3]
	s_setprio 0
	s_barrier
	s_add_i32 s72, s72, 2
	s_add_u32 s60, s60, 0x100
	s_addc_u32 s61, s61, 0
	s_add_u32 s70, s70, 0x100
	s_addc_u32 s71, s71, 0
	s_cmp_gt_u32 s72, 29
	s_cbranch_scc0 .LBB0_1053
	s_and_b64 vcc, exec, s[16:17]
	s_cbranch_vccz .LBB0_1056
	s_barrier

; #define PG8_STAGE(bufoff, gbase, voff) do { _Pragma("unroll") for (int _i = 0; _i < 2; ++_i) \
;         __builtin_amdgcn_global_load_lds((const unsigned*)((const char*)(gbase) + (voff)[_i]), (PG8_LAS unsigned*)(lds + (bufoff) + ldsw + _i * 8192), 16, 0, 0); } while (0)
; #define PG8_LDA(dst, b, h) do { _Pragma("unroll") for (int m = 0; m < 4; ++m) _Pragma("unroll") for (int k = 0; k < 2; ++k) dst[m][k] = *(const PG8_LAS bf16x8*)(lds + PG8_SA(b, h) + aoff + m * 2048 + k * 1024); } while (0)
; #define PG8_LDB(dst, b, h) do { _Pragma("unroll") for (int n = 0; n < 2; ++n) _Pragma("unroll") for (int k = 0; k < 2; ++k) dst[n][k] = *(const PG8_LAS bf16x8*)(lds + PG8_SB(b, h) + boff + n * 2048 + k * 1024); } while (0)
; #define PG8_MMA(ai, bj, At, Bt) do { __builtin_amdgcn_s_setprio(1); _Pragma("unroll") for (int m = 0; m < 4; ++m) _Pragma("unroll") for (int n = 0; n < 2; ++n) _Pragma("unroll") for (int k = 0; k < 2; ++k) \
;         acc[ai][bj][m][n] = __builtin_amdgcn_mfma_f32_16x16x32_bf16(Bt[n][k], At[m][k], acc[ai][bj][m][n], 0, 0, 0); __builtin_amdgcn_s_setprio(0); } while (0)
; #define PG8_WAIT_V(n) asm volatile("s_waitcnt vmcnt(" #n ")" ::: "memory")
; #define PG8_WAIT_L(n) asm volatile("s_waitcnt lgkmcnt(" #n ")" ::: "memory")
; #define PG8_BAR __builtin_amdgcn_s_barrier()
; #define PG8_SCHED __builtin_amdgcn_sched_barrier(0)
; template <class Epi, class Sched, bool ALIGN_EPI = false, bool SP2 = false>
; __device__ __forceinline__ void gemm_phase(PG8_LAS unsigned char* lds, const Gemm g, const Sched& S, const Epi& E) {
;     ...
;             const char* a2 = last ? nA : cA + (size_t)(t + 2) * kstep; const char* b2 = last ? nB : cB + (size_t)(t + 2) * kstep;
;             const char* a3 = a2 + kstep; const char* b3 = b2 + kstep;
;             if (last && has_next) S.a_ready(nxt);
;             if constexpr (SP2) {
;             PG8_LDB(B0, 0, 0); PG8_LDB(B1, 0, 1); PG8_SCHED; PG8_LDA(At, 0, 0); PG8_STAGE(PG8_SA(1, 1), a1 + hstep, voffA);
;             PG8_WAIT_V(8); PG8_WAIT_L(0); PG8_BAR; PG8_MMA(0, 0, At, B0); PG8_MMA(0, 1, At, B1); PG8_BAR; PG8_SCHED;
;             PG8_LDA(At, 0, 1); PG8_STAGE(PG8_SB(0, 0), b2, voffB); PG8_STAGE(PG8_SB(0, 1), b2 + hstep, voffB); PG8_STAGE(PG8_SA(0, 0), a2, voffA);
;             PG8_WAIT_V(8); PG8_WAIT_L(0); PG8_BAR; PG8_MMA(1, 0, At, B0); PG8_MMA(1, 1, At, B1); PG8_BAR; PG8_SCHED;
.LBB0_1184:
	ds_read_b128 v[152:155], v149
	ds_read_b128 v[156:159], v149 offset:1024
	ds_read_b128 v[160:163], v149 offset:2048
	ds_read_b128 v[164:167], v149 offset:3072
	ds_read_b128 v[168:171], v150
	ds_read_b128 v[172:175], v150 offset:1024
	ds_read_b128 v[176:179], v150 offset:2048
	ds_read_b128 v[180:183], v150 offset:3072
	s_add_i32 m0, s3, 0xc000
	ds_read_b128 v[184:187], v151
	ds_read_b128 v[188:191], v151 offset:1024
	ds_read_b128 v[192:195], v151 offset:2048
	ds_read_b128 v[196:199], v151 offset:3072
	ds_read_b128 v[200:203], v151 offset:4096
	ds_read_b128 v[204:207], v151 offset:5120
	ds_read_b128 v[208:211], v151 offset:6144
	ds_read_b128 v[212:215], v151 offset:7168
	global_load_lds_dwordx4 v136, s[50:51]
	s_add_i32 m0, s3, 0xe000
	s_nop 0
	global_load_lds_dwordx4 v138, s[50:51]
	s_add_u32 s58, s50, 0xfff80080
	s_addc_u32 s59, s51, -1
	s_cmp_eq_u32 s74, 28
	s_cselect_b32 s61, s25, s59
	s_cselect_b32 s60, s41, s58
	s_cselect_b32 s59, s39, s73
	s_cselect_b32 s58, s71, s72
	s_waitcnt vmcnt(8)
	s_waitcnt lgkmcnt(0)
	s_setprio 1
	s_barrier
	v_mfma_f32_16x16x32_bf16 v[124:127], v[152:155], v[184:187], v[124:127]
	v_mfma_f32_16x16x32_bf16 v[120:123], v[160:163], v[184:187], v[120:123]
	v_mfma_f32_16x16x32_bf16 v[108:111], v[152:155], v[192:195], v[108:111]
	v_mfma_f32_16x16x32_bf16 v[104:107], v[160:163], v[192:195], v[104:107]
	v_mfma_f32_16x16x32_bf16 v[92:95], v[152:155], v[200:203], v[92:95]
	v_mfma_f32_16x16x32_bf16 v[88:91], v[160:163], v[200:203], v[88:91]
	v_mfma_f32_16x16x32_bf16 v[76:79], v[152:155], v[208:211], v[76:79]
	v_mfma_f32_16x16x32_bf16 v[72:75], v[160:163], v[208:211], v[72:75]
	v_mfma_f32_16x16x32_bf16 v[124:127], v[156:159], v[188:191], v[124:127]
	v_mfma_f32_16x16x32_bf16 v[120:123], v[164:167], v[188:191], v[120:123]
	v_mfma_f32_16x16x32_bf16 v[108:111], v[156:159], v[196:199], v[108:111]
	v_mfma_f32_16x16x32_bf16 v[104:107], v[164:167], v[196:199], v[104:107]
	v_mfma_f32_16x16x32_bf16 v[92:95], v[156:159], v[204:207], v[92:95]
	v_mfma_f32_16x16x32_bf16 v[88:91], v[164:167], v[204:207], v[88:91]
	v_mfma_f32_16x16x32_bf16 v[76:79], v[156:159], v[212:215], v[76:79]
	v_mfma_f32_16x16x32_bf16 v[72:75], v[164:167], v[212:215], v[72:75]
	v_mfma_f32_16x16x32_bf16 v[116:119], v[168:171], v[184:187], v[116:119]
	v_mfma_f32_16x16x32_bf16 v[112:115], v[176:179], v[184:187], v[112:115]
	v_mfma_f32_16x16x32_bf16 v[100:103], v[168:171], v[192:195], v[100:103]
	v_mfma_f32_16x16x32_bf16 v[96:99], v[176:179], v[192:195], v[96:99]
	v_mfma_f32_16x16x32_bf16 v[84:87], v[168:171], v[200:203], v[84:87]
	v_mfma_f32_16x16x32_bf16 v[80:83], v[176:179], v[200:203], v[80:83]
	v_mfma_f32_16x16x32_bf16 v[68:71], v[168:171], v[208:211], v[68:71]
	v_mfma_f32_16x16x32_bf16 v[64:67], v[176:179], v[208:211], v[64:67]
	v_mfma_f32_16x16x32_bf16 v[116:119], v[172:175], v[188:191], v[116:119]
	v_mfma_f32_16x16x32_bf16 v[112:115], v[180:183], v[188:191], v[112:115]
	v_mfma_f32_16x16x32_bf16 v[100:103], v[172:175], v[196:199], v[100:103]
	v_mfma_f32_16x16x32_bf16 v[96:99], v[180:183], v[196:199], v[96:99]
	v_mfma_f32_16x16x32_bf16 v[84:87], v[172:175], v[204:207], v[84:87]
	v_mfma_f32_16x16x32_bf16 v[80:83], v[180:183], v[204:207], v[80:83]
	v_mfma_f32_16x16x32_bf16 v[68:71], v[172:175], v[212:215], v[68:71]
	v_mfma_f32_16x16x32_bf16 v[64:67], v[180:183], v[212:215], v[64:67]
	s_setprio 0
	s_barrier
	s_add_i32 s75, s65, s1
	s_mov_b32 m0, s75
	ds_read_b128 v[184:187], v151 offset:16384
	ds_read_b128 v[188:191], v151 offset:17408
	ds_read_b128 v[192:195], v151 offset:18432
	ds_read_b128 v[196:199], v151 offset:19456
	ds_read_b128 v[200:203], v151 offset:20480
	ds_read_b128 v[204:207], v151 offset:21504
	ds_read_b128 v[208:211], v151 offset:22528
	ds_read_b128 v[212:215], v151 offset:23552
	global_load_lds_dwordx4 v130, s[58:59]
	s_add_i32 m0, s75, 0x2000
	s_add_u32 s76, s58, 0x80000
	s_addc_u32 s77, s59, 0
	s_add_i32 s75, s66, s1
	global_load_lds_dwordx4 v134, s[58:59]
	s_mov_b32 m0, s75
	s_nop 0
	global_load_lds_dwordx4 v130, s[76:77]
	s_add_i32 m0, s75, 0x2000
	s_nop 0
	global_load_lds_dwordx4 v134, s[76:77]
	s_mov_b32 m0, s3
	s_nop 0
	global_load_lds_dwordx4 v128, s[60:61]
	s_mov_b32 m0, s14
	s_nop 0
	global_load_lds_dwordx4 v132, s[60:61]
	s_waitcnt vmcnt(8)
	s_waitcnt lgkmcnt(0)
	s_setprio 1
	s_barrier
	v_mfma_f32_16x16x32_bf16 v[60:63], v[152:155], v[184:187], v[60:63]
	v_mfma_f32_16x16x32_bf16 v[56:59], v[160:163], v[184:187], v[56:59]
	v_mfma_f32_16x16x32_bf16 v[44:47], v[152:155], v[192:195], v[44:47]
	v_mfma_f32_16x16x32_bf16 v[40:43], v[160:163], v[192:195], v[40:43]
	v_mfma_f32_16x16x32_bf16 v[28:31], v[152:155], v[200:203], v[28:31]
	v_mfma_f32_16x16x32_bf16 v[24:27], v[160:163], v[200:203], v[24:27]
	v_mfma_f32_16x16x32_bf16 v[12:15], v[152:155], v[208:211], v[12:15]
	v_mfma_f32_16x16x32_bf16 v[8:11], v[160:163], v[208:211], v[8:11]
	v_mfma_f32_16x16x32_bf16 v[60:63], v[156:159], v[188:191], v[60:63]
	v_mfma_f32_16x16x32_bf16 v[56:59], v[164:167], v[188:191], v[56:59]
	v_mfma_f32_16x16x32_bf16 v[44:47], v[156:159], v[196:199], v[44:47]
	v_mfma_f32_16x16x32_bf16 v[40:43], v[164:167], v[196:199], v[40:43]
	v_mfma_f32_16x16x32_bf16 v[28:31], v[156:159], v[204:207], v[28:31]
	v_mfma_f32_16x16x32_bf16 v[24:27], v[164:167], v[204:207], v[24:27]
	v_mfma_f32_16x16x32_bf16 v[12:15], v[156:159], v[212:215], v[12:15]
	v_mfma_f32_16x16x32_bf16 v[8:11], v[164:167], v[212:215], v[8:11]
	v_mfma_f32_16x16x32_bf16 v[52:55], v[168:171], v[184:187], v[52:55]
	v_mfma_f32_16x16x32_bf16 v[48:51], v[176:179], v[184:187], v[48:51]
	v_mfma_f32_16x16x32_bf16 v[36:39], v[168:171], v[192:195], v[36:39]
	v_mfma_f32_16x16x32_bf16 v[32:35], v[176:179], v[192:195], v[32:35]
	v_mfma_f32_16x16x32_bf16 v[20:23], v[168:171], v[200:203], v[20:23]
	v_mfma_f32_16x16x32_bf16 v[16:19], v[176:179], v[200:203], v[16:19]
	v_mfma_f32_16x16x32_bf16 v[4:7], v[168:171], v[208:211], v[4:7]
	v_mfma_f32_16x16x32_bf16 v[0:3], v[176:179], v[208:211], v[0:3]
	v_mfma_f32_16x16x32_bf16 v[52:55], v[172:175], v[188:191], v[52:55]
	v_mfma_f32_16x16x32_bf16 v[48:51], v[180:183], v[188:191], v[48:51]
	v_mfma_f32_16x16x32_bf16 v[36:39], v[172:175], v[196:199], v[36:39]
	v_mfma_f32_16x16x32_bf16 v[32:35], v[180:183], v[196:199], v[32:35]
	v_mfma_f32_16x16x32_bf16 v[20:23], v[172:175], v[204:207], v[20:23]
	v_mfma_f32_16x16x32_bf16 v[16:19], v[180:183], v[204:207], v[16:19]
	v_mfma_f32_16x16x32_bf16 v[4:7], v[172:175], v[212:215], v[4:7]
	v_mfma_f32_16x16x32_bf16 v[0:3], v[180:183], v[212:215], v[0:3]
	s_setprio 0
	s_barrier
; #define PG8_STAGE(bufoff, gbase, voff) do { _Pragma("unroll") for (int _i = 0; _i < 2; ++_i) \
;         __builtin_amdgcn_global_load_lds((const unsigned*)((const char*)(gbase) + (voff)[_i]), (PG8_LAS unsigned*)(lds + (bufoff) + ldsw + _i * 8192), 16, 0, 0); } while (0)
; #define PG8_LDA(dst, b, h) do { _Pragma("unroll") for (int m = 0; m < 4; ++m) _Pragma("unroll") for (int k = 0; k < 2; ++k) dst[m][k] = *(const PG8_LAS bf16x8*)(lds + PG8_SA(b, h) + aoff + m * 2048 + k * 1024); } while (0)
; #define PG8_LDB(dst, b, h) do { _Pragma("unroll") for (int n = 0; n < 2; ++n) _Pragma("unroll") for (int k = 0; k < 2; ++k) dst[n][k] = *(const PG8_LAS bf16x8*)(lds + PG8_SB(b, h) + boff + n * 2048 + k * 1024); } while (0)
; #define PG8_MMA(ai, bj, At, Bt) do { __builtin_amdgcn_s_setprio(1); _Pragma("unroll") for (int m = 0; m < 4; ++m) _Pragma("unroll") for (int n = 0; n < 2; ++n) _Pragma("unroll") for (int k = 0; k < 2; ++k) \
;         acc[ai][bj][m][n] = __builtin_amdgcn_mfma_f32_16x16x32_bf16(Bt[n][k], At[m][k], acc[ai][bj][m][n], 0, 0, 0); __builtin_amdgcn_s_setprio(0); } while (0)
; #define PG8_WAIT_V(n) asm volatile("s_waitcnt vmcnt(" #n ")" ::: "memory")
; #define PG8_WAIT_L(n) asm volatile("s_waitcnt lgkmcnt(" #n ")" ::: "memory")
; #define PG8_BAR __builtin_amdgcn_s_barrier()
; #define PG8_SCHED __builtin_amdgcn_sched_barrier(0)
; template <class Epi, class Sched, bool ALIGN_EPI = false, bool SP2 = false>
; __device__ __forceinline__ void gemm_phase(PG8_LAS unsigned char* lds, const Gemm g, const Sched& S, const Epi& E) {
;     ...
;             PG8_LDB(B0, 1, 0); PG8_LDB(B1, 1, 1); PG8_SCHED; PG8_LDA(At, 1, 0); PG8_STAGE(PG8_SA(0, 1), a2 + hstep, voffA);
;             PG8_WAIT_V(8); PG8_WAIT_L(0); PG8_BAR; PG8_MMA(0, 0, At, B0); PG8_MMA(0, 1, At, B1); PG8_BAR; PG8_SCHED;
;             PG8_LDA(At, 1, 1); PG8_STAGE(PG8_SB(1, 0), b3, voffB); PG8_STAGE(PG8_SB(1, 1), b3 + hstep, voffB); PG8_STAGE(PG8_SA(1, 0), a3, voffA);
;             PG8_WAIT_V(8); PG8_WAIT_L(0); PG8_BAR; PG8_MMA(1, 0, At, B0); PG8_MMA(1, 1, At, B1); PG8_BAR; PG8_SCHED;
;     ...
;         if constexpr (ALIGN_EPI) { if (wr == 0) PG8_BAR; }
	ds_read_b128 v[152:155], v216
	ds_read_b128 v[156:159], v216 offset:1024
	ds_read_b128 v[160:163], v216 offset:2048
	ds_read_b128 v[164:167], v216 offset:3072
	ds_read_b128 v[168:171], v217
	ds_read_b128 v[172:175], v217 offset:1024
	ds_read_b128 v[176:179], v217 offset:2048
	ds_read_b128 v[180:183], v217 offset:3072
	ds_read_b128 v[184:187], v151 offset:32768
	ds_read_b128 v[188:191], v151 offset:33792
	ds_read_b128 v[192:195], v151 offset:34816
	ds_read_b128 v[196:199], v151 offset:35840
	ds_read_b128 v[200:203], v151 offset:36864
	ds_read_b128 v[204:207], v151 offset:37888
	ds_read_b128 v[208:211], v151 offset:38912
	ds_read_b128 v[212:215], v151 offset:39936
	s_add_u32 s98, s60, 0x80000
	s_addc_u32 s99, s61, 0
	s_mov_b32 m0, s15
	s_add_u32 s100, s60, 0x80
	s_addc_u32 s101, s61, 0
	global_load_lds_dwordx4 v128, s[98:99]
	s_mov_b32 m0, s33
	s_nop 0
	global_load_lds_dwordx4 v132, s[98:99]
	s_add_i32 s75, 0, 0x18000
	s_add_i32 s76, 0, 0x1c000
	s_waitcnt vmcnt(8)
	s_waitcnt lgkmcnt(0)
	s_setprio 1
	s_barrier
	v_mfma_f32_16x16x32_bf16 v[124:127], v[152:155], v[184:187], v[124:127]
	v_mfma_f32_16x16x32_bf16 v[120:123], v[160:163], v[184:187], v[120:123]
	v_mfma_f32_16x16x32_bf16 v[108:111], v[152:155], v[192:195], v[108:111]
	v_mfma_f32_16x16x32_bf16 v[104:107], v[160:163], v[192:195], v[104:107]
	v_mfma_f32_16x16x32_bf16 v[92:95], v[152:155], v[200:203], v[92:95]
	v_mfma_f32_16x16x32_bf16 v[88:91], v[160:163], v[200:203], v[88:91]
	v_mfma_f32_16x16x32_bf16 v[76:79], v[152:155], v[208:211], v[76:79]
	v_mfma_f32_16x16x32_bf16 v[72:75], v[160:163], v[208:211], v[72:75]
	v_mfma_f32_16x16x32_bf16 v[124:127], v[156:159], v[188:191], v[124:127]
	v_mfma_f32_16x16x32_bf16 v[120:123], v[164:167], v[188:191], v[120:123]
	v_mfma_f32_16x16x32_bf16 v[108:111], v[156:159], v[196:199], v[108:111]
	v_mfma_f32_16x16x32_bf16 v[104:107], v[164:167], v[196:199], v[104:107]
	v_mfma_f32_16x16x32_bf16 v[92:95], v[156:159], v[204:207], v[92:95]
	v_mfma_f32_16x16x32_bf16 v[88:91], v[164:167], v[204:207], v[88:91]
	v_mfma_f32_16x16x32_bf16 v[76:79], v[156:159], v[212:215], v[76:79]
	v_mfma_f32_16x16x32_bf16 v[72:75], v[164:167], v[212:215], v[72:75]
	v_mfma_f32_16x16x32_bf16 v[116:119], v[168:171], v[184:187], v[116:119]
	v_mfma_f32_16x16x32_bf16 v[112:115], v[176:179], v[184:187], v[112:115]
	v_mfma_f32_16x16x32_bf16 v[100:103], v[168:171], v[192:195], v[100:103]
	v_mfma_f32_16x16x32_bf16 v[96:99], v[176:179], v[192:195], v[96:99]
	v_mfma_f32_16x16x32_bf16 v[84:87], v[168:171], v[200:203], v[84:87]
	v_mfma_f32_16x16x32_bf16 v[80:83], v[176:179], v[200:203], v[80:83]
	v_mfma_f32_16x16x32_bf16 v[68:71], v[168:171], v[208:211], v[68:71]
	v_mfma_f32_16x16x32_bf16 v[64:67], v[176:179], v[208:211], v[64:67]
	v_mfma_f32_16x16x32_bf16 v[116:119], v[172:175], v[188:191], v[116:119]
	v_mfma_f32_16x16x32_bf16 v[112:115], v[180:183], v[188:191], v[112:115]
	v_mfma_f32_16x16x32_bf16 v[100:103], v[172:175], v[196:199], v[100:103]
	v_mfma_f32_16x16x32_bf16 v[96:99], v[180:183], v[196:199], v[96:99]
	v_mfma_f32_16x16x32_bf16 v[84:87], v[172:175], v[204:207], v[84:87]
	v_mfma_f32_16x16x32_bf16 v[80:83], v[180:183], v[204:207], v[80:83]
	v_mfma_f32_16x16x32_bf16 v[68:71], v[172:175], v[212:215], v[68:71]
	v_mfma_f32_16x16x32_bf16 v[64:67], v[180:183], v[212:215], v[64:67]
	s_setprio 0
	s_barrier
	s_add_u32 s98, s58, 0x80
	s_addc_u32 s99, s59, 0
	s_add_i32 s60, s75, s1
	s_mov_b32 m0, s60
	ds_read_b128 v[184:187], v151 offset:49152
	ds_read_b128 v[188:191], v151 offset:50176
	ds_read_b128 v[192:195], v151 offset:51200
	ds_read_b128 v[196:199], v151 offset:52224
	ds_read_b128 v[200:203], v151 offset:53248
	ds_read_b128 v[204:207], v151 offset:54272
	ds_read_b128 v[208:211], v151 offset:55296
	ds_read_b128 v[212:215], v151 offset:56320
	global_load_lds_dwordx4 v130, s[98:99]
	s_add_i32 m0, s60, 0x2000
	s_add_u32 s58, s58, 0x80080
	s_addc_u32 s59, s59, 0
	s_add_i32 s60, s76, s1
	global_load_lds_dwordx4 v134, s[98:99]
	s_mov_b32 m0, s60
	s_nop 0
	global_load_lds_dwordx4 v130, s[58:59]
	s_add_i32 m0, s60, 0x2000
	s_nop 0
	global_load_lds_dwordx4 v134, s[58:59]
	s_mov_b32 m0, s49
	s_nop 0
	global_load_lds_dwordx4 v128, s[100:101]
	s_mov_b32 m0, s62
	s_nop 0
	global_load_lds_dwordx4 v132, s[100:101]
	s_waitcnt vmcnt(8)
	s_waitcnt lgkmcnt(0)
	s_setprio 1
	s_barrier
	v_mfma_f32_16x16x32_bf16 v[60:63], v[152:155], v[184:187], v[60:63]
	v_mfma_f32_16x16x32_bf16 v[56:59], v[160:163], v[184:187], v[56:59]
	v_mfma_f32_16x16x32_bf16 v[44:47], v[152:155], v[192:195], v[44:47]
	v_mfma_f32_16x16x32_bf16 v[40:43], v[160:163], v[192:195], v[40:43]
	v_mfma_f32_16x16x32_bf16 v[28:31], v[152:155], v[200:203], v[28:31]
	v_mfma_f32_16x16x32_bf16 v[24:27], v[160:163], v[200:203], v[24:27]
	v_mfma_f32_16x16x32_bf16 v[12:15], v[152:155], v[208:211], v[12:15]
	v_mfma_f32_16x16x32_bf16 v[8:11], v[160:163], v[208:211], v[8:11]
	v_mfma_f32_16x16x32_bf16 v[60:63], v[156:159], v[188:191], v[60:63]
	v_mfma_f32_16x16x32_bf16 v[56:59], v[164:167], v[188:191], v[56:59]
	v_mfma_f32_16x16x32_bf16 v[44:47], v[156:159], v[196:199], v[44:47]
	v_mfma_f32_16x16x32_bf16 v[40:43], v[164:167], v[196:199], v[40:43]
	v_mfma_f32_16x16x32_bf16 v[28:31], v[156:159], v[204:207], v[28:31]
	v_mfma_f32_16x16x32_bf16 v[24:27], v[164:167], v[204:207], v[24:27]
	v_mfma_f32_16x16x32_bf16 v[12:15], v[156:159], v[212:215], v[12:15]
	v_mfma_f32_16x16x32_bf16 v[8:11], v[164:167], v[212:215], v[8:11]
	v_mfma_f32_16x16x32_bf16 v[52:55], v[168:171], v[184:187], v[52:55]
	v_mfma_f32_16x16x32_bf16 v[48:51], v[176:179], v[184:187], v[48:51]
	v_mfma_f32_16x16x32_bf16 v[36:39], v[168:171], v[192:195], v[36:39]
	v_mfma_f32_16x16x32_bf16 v[32:35], v[176:179], v[192:195], v[32:35]
	v_mfma_f32_16x16x32_bf16 v[20:23], v[168:171], v[200:203], v[20:23]
	v_mfma_f32_16x16x32_bf16 v[16:19], v[176:179], v[200:203], v[16:19]
	v_mfma_f32_16x16x32_bf16 v[4:7], v[168:171], v[208:211], v[4:7]
	v_mfma_f32_16x16x32_bf16 v[0:3], v[176:179], v[208:211], v[0:3]
	v_mfma_f32_16x16x32_bf16 v[52:55], v[172:175], v[188:191], v[52:55]
	v_mfma_f32_16x16x32_bf16 v[48:51], v[180:183], v[188:191], v[48:51]
	v_mfma_f32_16x16x32_bf16 v[36:39], v[172:175], v[196:199], v[36:39]
	v_mfma_f32_16x16x32_bf16 v[32:35], v[180:183], v[196:199], v[32:35]
	v_mfma_f32_16x16x32_bf16 v[20:23], v[172:175], v[204:207], v[20:23]
	v_mfma_f32_16x16x32_bf16 v[16:19], v[180:183], v[204:207], v[16:19]
	v_mfma_f32_16x16x32_bf16 v[4:7], v[172:175], v[212:215], v[4:7]
	v_mfma_f32_16x16x32_bf16 v[0:3], v[180:183], v[212:215], v[0:3]
	s_setprio 0
	s_barrier
	s_add_i32 s74, s74, 2
	s_add_u32 s50, s50, 0x100
	s_addc_u32 s51, s51, 0
	s_add_u32 s72, s72, 0x100
	s_addc_u32 s73, s73, 0
	s_cmp_gt_u32 s74, 29
	s_cbranch_scc0 .LBB0_1184
	s_and_b64 vcc, exec, s[12:13]
	s_cbranch_vccz .LBB0_1187
	s_barrier

; #define PG8_STAGE(bufoff, gbase, voff) do { _Pragma("unroll") for (int _i = 0; _i < 2; ++_i) \
;         __builtin_amdgcn_global_load_lds((const unsigned*)((const char*)(gbase) + (voff)[_i]), (PG8_LAS unsigned*)(lds + (bufoff) + ldsw + _i * 8192), 16, 0, 0); } while (0)
; #define PG8_LDA(dst, b, h) do { _Pragma("unroll") for (int m = 0; m < 4; ++m) _Pragma("unroll") for (int k = 0; k < 2; ++k) dst[m][k] = *(const PG8_LAS bf16x8*)(lds + PG8_SA(b, h) + aoff + m * 2048 + k * 1024); } while (0)
; #define PG8_LDB(dst, b, h) do { _Pragma("unroll") for (int n = 0; n < 2; ++n) _Pragma("unroll") for (int k = 0; k < 2; ++k) dst[n][k] = *(const PG8_LAS bf16x8*)(lds + PG8_SB(b, h) + boff + n * 2048 + k * 1024); } while (0)
; #define PG8_MMA(ai, bj, At, Bt) do { __builtin_amdgcn_s_setprio(1); _Pragma("unroll") for (int m = 0; m < 4; ++m) _Pragma("unroll") for (int n = 0; n < 2; ++n) _Pragma("unroll") for (int k = 0; k < 2; ++k) \
;         acc[ai][bj][m][n] = __builtin_amdgcn_mfma_f32_16x16x32_bf16(Bt[n][k], At[m][k], acc[ai][bj][m][n], 0, 0, 0); __builtin_amdgcn_s_setprio(0); } while (0)
; #define PG8_WAIT_V(n) asm volatile("s_waitcnt vmcnt(" #n ")" ::: "memory")
; #define PG8_WAIT_L(n) asm volatile("s_waitcnt lgkmcnt(" #n ")" ::: "memory")
; #define PG8_BAR __builtin_amdgcn_s_barrier()
; #define PG8_SCHED __builtin_amdgcn_sched_barrier(0)
; template <class Epi, class Sched, bool ALIGN_EPI = false, bool SP2 = false>
; __device__ __forceinline__ void gemm_phase(PG8_LAS unsigned char* lds, const Gemm g, const Sched& S, const Epi& E) {
;     ...
;             const char* a2 = last ? nA : cA + (size_t)(t + 2) * kstep; const char* b2 = last ? nB : cB + (size_t)(t + 2) * kstep;
;             const char* a3 = a2 + kstep; const char* b3 = b2 + kstep;
;             if (last && has_next) S.a_ready(nxt);
;             if constexpr (SP2) {
;             PG8_LDB(B0, 0, 0); PG8_LDB(B1, 0, 1); PG8_SCHED; PG8_LDA(At, 0, 0); PG8_STAGE(PG8_SA(1, 1), a1 + hstep, voffA);
;             PG8_WAIT_V(8); PG8_WAIT_L(0); PG8_BAR; PG8_MMA(0, 0, At, B0); PG8_MMA(0, 1, At, B1); PG8_BAR; PG8_SCHED;
;             PG8_LDA(At, 0, 1); PG8_STAGE(PG8_SB(0, 0), b2, voffB); PG8_STAGE(PG8_SB(0, 1), b2 + hstep, voffB); PG8_STAGE(PG8_SA(0, 0), a2, voffA);
;             PG8_WAIT_V(8); PG8_WAIT_L(0); PG8_BAR; PG8_MMA(1, 0, At, B0); PG8_MMA(1, 1, At, B1); PG8_BAR; PG8_SCHED;
.LBB0_1260:
	ds_read_b128 v[128:131], v202
	ds_read_b128 v[132:135], v202 offset:1024
	ds_read_b128 v[136:139], v202 offset:2048
	ds_read_b128 v[140:143], v202 offset:3072
	ds_read_b128 v[144:147], v203
	ds_read_b128 v[148:151], v203 offset:1024
	ds_read_b128 v[152:155], v203 offset:2048
	ds_read_b128 v[156:159], v203 offset:3072
	s_add_i32 m0, s14, 0xc000
	ds_read_b128 v[160:163], v204
	ds_read_b128 v[164:167], v204 offset:1024
	ds_read_b128 v[184:187], v204 offset:2048
	ds_read_b128 v[188:191], v204 offset:3072
	ds_read_b128 v[192:195], v204 offset:4096
	ds_read_b128 v[206:209], v204 offset:5120
	ds_read_b128 v[210:213], v204 offset:6144
	ds_read_b128 v[214:217], v204 offset:7168
	global_load_lds_dwordx4 v176, s[50:51]
	s_add_i32 m0, s14, 0xe000
	s_nop 0
	global_load_lds_dwordx4 v178, s[50:51]
	s_add_u32 s58, s50, 0xffe00080
	s_addc_u32 s59, s51, -1
	s_cmpk_eq_i32 s72, 0x7c
	s_cselect_b32 s61, s25, s59
	s_cselect_b32 s60, s41, s58
	s_cselect_b32 s59, s39, s71
	s_cselect_b32 s58, s69, s70
	s_waitcnt vmcnt(8)
	s_waitcnt lgkmcnt(0)
	s_setprio 1
	s_barrier
	v_mfma_f32_16x16x32_bf16 v[124:127], v[128:131], v[160:163], v[124:127]
	v_mfma_f32_16x16x32_bf16 v[120:123], v[136:139], v[160:163], v[120:123]
	v_mfma_f32_16x16x32_bf16 v[116:119], v[128:131], v[184:187], v[116:119]
	v_mfma_f32_16x16x32_bf16 v[108:111], v[136:139], v[184:187], v[108:111]
	v_mfma_f32_16x16x32_bf16 v[92:95], v[128:131], v[192:195], v[92:95]
	v_mfma_f32_16x16x32_bf16 v[88:91], v[136:139], v[192:195], v[88:91]
	v_mfma_f32_16x16x32_bf16 v[76:79], v[128:131], v[210:213], v[76:79]
	v_mfma_f32_16x16x32_bf16 v[72:75], v[136:139], v[210:213], v[72:75]
	v_mfma_f32_16x16x32_bf16 v[124:127], v[132:135], v[164:167], v[124:127]
	v_mfma_f32_16x16x32_bf16 v[120:123], v[140:143], v[164:167], v[120:123]
	v_mfma_f32_16x16x32_bf16 v[116:119], v[132:135], v[188:191], v[116:119]
	v_mfma_f32_16x16x32_bf16 v[108:111], v[140:143], v[188:191], v[108:111]
	v_mfma_f32_16x16x32_bf16 v[92:95], v[132:135], v[206:209], v[92:95]
	v_mfma_f32_16x16x32_bf16 v[88:91], v[140:143], v[206:209], v[88:91]
	v_mfma_f32_16x16x32_bf16 v[76:79], v[132:135], v[214:217], v[76:79]
	v_mfma_f32_16x16x32_bf16 v[72:75], v[140:143], v[214:217], v[72:75]
	v_mfma_f32_16x16x32_bf16 v[112:115], v[144:147], v[160:163], v[112:115]
	v_mfma_f32_16x16x32_bf16 v[104:107], v[152:155], v[160:163], v[104:107]
	v_mfma_f32_16x16x32_bf16 v[100:103], v[144:147], v[184:187], v[100:103]
	v_mfma_f32_16x16x32_bf16 v[96:99], v[152:155], v[184:187], v[96:99]
	v_mfma_f32_16x16x32_bf16 v[84:87], v[144:147], v[192:195], v[84:87]
	v_mfma_f32_16x16x32_bf16 v[80:83], v[152:155], v[192:195], v[80:83]
	v_mfma_f32_16x16x32_bf16 v[68:71], v[144:147], v[210:213], v[68:71]
	v_mfma_f32_16x16x32_bf16 v[64:67], v[152:155], v[210:213], v[64:67]
	v_mfma_f32_16x16x32_bf16 v[112:115], v[148:151], v[164:167], v[112:115]
	v_mfma_f32_16x16x32_bf16 v[104:107], v[156:159], v[164:167], v[104:107]
	v_mfma_f32_16x16x32_bf16 v[100:103], v[148:151], v[188:191], v[100:103]
	v_mfma_f32_16x16x32_bf16 v[96:99], v[156:159], v[188:191], v[96:99]
	v_mfma_f32_16x16x32_bf16 v[84:87], v[148:151], v[206:209], v[84:87]
	v_mfma_f32_16x16x32_bf16 v[80:83], v[156:159], v[206:209], v[80:83]
	v_mfma_f32_16x16x32_bf16 v[68:71], v[148:151], v[214:217], v[68:71]
	v_mfma_f32_16x16x32_bf16 v[64:67], v[156:159], v[214:217], v[64:67]
	s_setprio 0
	s_barrier
	s_add_i32 s73, s67, s1
	s_mov_b32 m0, s73
	ds_read_b128 v[160:163], v204 offset:16384
	ds_read_b128 v[164:167], v204 offset:17408
	ds_read_b128 v[184:187], v204 offset:18432
	ds_read_b128 v[188:191], v204 offset:19456
	ds_read_b128 v[192:195], v204 offset:20480
	ds_read_b128 v[206:209], v204 offset:21504
	ds_read_b128 v[210:213], v204 offset:22528
	ds_read_b128 v[214:217], v204 offset:23552
	global_load_lds_dwordx4 v170, s[58:59]
	s_add_i32 m0, s73, 0x2000
	s_add_u32 s74, s58, 0x200000
	s_addc_u32 s75, s59, 0
	s_add_i32 s73, s68, s1
	global_load_lds_dwordx4 v174, s[58:59]
	s_mov_b32 m0, s73
	s_nop 0
	global_load_lds_dwordx4 v170, s[74:75]
	s_add_i32 m0, s73, 0x2000
	s_nop 0
	global_load_lds_dwordx4 v174, s[74:75]
	s_mov_b32 m0, s14
	s_nop 0
	global_load_lds_dwordx4 v168, s[60:61]
	s_mov_b32 m0, s15
	s_nop 0
	global_load_lds_dwordx4 v172, s[60:61]
	s_waitcnt vmcnt(8)
	s_waitcnt lgkmcnt(0)
	s_setprio 1
	s_barrier
	v_mfma_f32_16x16x32_bf16 v[60:63], v[128:131], v[160:163], v[60:63]
	v_mfma_f32_16x16x32_bf16 v[56:59], v[136:139], v[160:163], v[56:59]
	v_mfma_f32_16x16x32_bf16 v[44:47], v[128:131], v[184:187], v[44:47]
	v_mfma_f32_16x16x32_bf16 v[40:43], v[136:139], v[184:187], v[40:43]
	v_mfma_f32_16x16x32_bf16 v[28:31], v[128:131], v[192:195], v[28:31]
	v_mfma_f32_16x16x32_bf16 v[24:27], v[136:139], v[192:195], v[24:27]
	v_mfma_f32_16x16x32_bf16 v[12:15], v[128:131], v[210:213], v[12:15]
	v_mfma_f32_16x16x32_bf16 v[8:11], v[136:139], v[210:213], v[8:11]
	v_mfma_f32_16x16x32_bf16 v[60:63], v[132:135], v[164:167], v[60:63]
	v_mfma_f32_16x16x32_bf16 v[56:59], v[140:143], v[164:167], v[56:59]
	v_mfma_f32_16x16x32_bf16 v[44:47], v[132:135], v[188:191], v[44:47]
	v_mfma_f32_16x16x32_bf16 v[40:43], v[140:143], v[188:191], v[40:43]
	v_mfma_f32_16x16x32_bf16 v[28:31], v[132:135], v[206:209], v[28:31]
	v_mfma_f32_16x16x32_bf16 v[24:27], v[140:143], v[206:209], v[24:27]
	v_mfma_f32_16x16x32_bf16 v[12:15], v[132:135], v[214:217], v[12:15]
	v_mfma_f32_16x16x32_bf16 v[8:11], v[140:143], v[214:217], v[8:11]
	v_mfma_f32_16x16x32_bf16 v[52:55], v[144:147], v[160:163], v[52:55]
	v_mfma_f32_16x16x32_bf16 v[48:51], v[152:155], v[160:163], v[48:51]
	v_mfma_f32_16x16x32_bf16 v[36:39], v[144:147], v[184:187], v[36:39]
	v_mfma_f32_16x16x32_bf16 v[32:35], v[152:155], v[184:187], v[32:35]
	v_mfma_f32_16x16x32_bf16 v[20:23], v[144:147], v[192:195], v[20:23]
	v_mfma_f32_16x16x32_bf16 v[16:19], v[152:155], v[192:195], v[16:19]
	v_mfma_f32_16x16x32_bf16 v[4:7], v[144:147], v[210:213], v[4:7]
	v_mfma_f32_16x16x32_bf16 v[0:3], v[152:155], v[210:213], v[0:3]
	v_mfma_f32_16x16x32_bf16 v[52:55], v[148:151], v[164:167], v[52:55]
	v_mfma_f32_16x16x32_bf16 v[48:51], v[156:159], v[164:167], v[48:51]
	v_mfma_f32_16x16x32_bf16 v[36:39], v[148:151], v[188:191], v[36:39]
	v_mfma_f32_16x16x32_bf16 v[32:35], v[156:159], v[188:191], v[32:35]
	v_mfma_f32_16x16x32_bf16 v[20:23], v[148:151], v[206:209], v[20:23]
	v_mfma_f32_16x16x32_bf16 v[16:19], v[156:159], v[206:209], v[16:19]
	v_mfma_f32_16x16x32_bf16 v[4:7], v[148:151], v[214:217], v[4:7]
	v_mfma_f32_16x16x32_bf16 v[0:3], v[156:159], v[214:217], v[0:3]
	s_setprio 0
	s_barrier
; #define PG8_STAGE(bufoff, gbase, voff) do { _Pragma("unroll") for (int _i = 0; _i < 2; ++_i) \
;         __builtin_amdgcn_global_load_lds((const unsigned*)((const char*)(gbase) + (voff)[_i]), (PG8_LAS unsigned*)(lds + (bufoff) + ldsw + _i * 8192), 16, 0, 0); } while (0)
; #define PG8_LDA(dst, b, h) do { _Pragma("unroll") for (int m = 0; m < 4; ++m) _Pragma("unroll") for (int k = 0; k < 2; ++k) dst[m][k] = *(const PG8_LAS bf16x8*)(lds + PG8_SA(b, h) + aoff + m * 2048 + k * 1024); } while (0)
; #define PG8_LDB(dst, b, h) do { _Pragma("unroll") for (int n = 0; n < 2; ++n) _Pragma("unroll") for (int k = 0; k < 2; ++k) dst[n][k] = *(const PG8_LAS bf16x8*)(lds + PG8_SB(b, h) + boff + n * 2048 + k * 1024); } while (0)
; #define PG8_MMA(ai, bj, At, Bt) do { __builtin_amdgcn_s_setprio(1); _Pragma("unroll") for (int m = 0; m < 4; ++m) _Pragma("unroll") for (int n = 0; n < 2; ++n) _Pragma("unroll") for (int k = 0; k < 2; ++k) \
;         acc[ai][bj][m][n] = __builtin_amdgcn_mfma_f32_16x16x32_bf16(Bt[n][k], At[m][k], acc[ai][bj][m][n], 0, 0, 0); __builtin_amdgcn_s_setprio(0); } while (0)
; #define PG8_WAIT_V(n) asm volatile("s_waitcnt vmcnt(" #n ")" ::: "memory")
; #define PG8_WAIT_L(n) asm volatile("s_waitcnt lgkmcnt(" #n ")" ::: "memory")
; #define PG8_BAR __builtin_amdgcn_s_barrier()
; #define PG8_SCHED __builtin_amdgcn_sched_barrier(0)
; template <class Epi, class Sched, bool ALIGN_EPI = false, bool SP2 = false>
; __device__ __forceinline__ void gemm_phase(PG8_LAS unsigned char* lds, const Gemm g, const Sched& S, const Epi& E) {
;     ...
;             PG8_LDB(B0, 1, 0); PG8_LDB(B1, 1, 1); PG8_SCHED; PG8_LDA(At, 1, 0); PG8_STAGE(PG8_SA(0, 1), a2 + hstep, voffA);
;             PG8_WAIT_V(8); PG8_WAIT_L(0); PG8_BAR; PG8_MMA(0, 0, At, B0); PG8_MMA(0, 1, At, B1); PG8_BAR; PG8_SCHED;
;             PG8_LDA(At, 1, 1); PG8_STAGE(PG8_SB(1, 0), b3, voffB); PG8_STAGE(PG8_SB(1, 1), b3 + hstep, voffB); PG8_STAGE(PG8_SA(1, 0), a3, voffA);
;             PG8_WAIT_V(8); PG8_WAIT_L(0); PG8_BAR; PG8_MMA(1, 0, At, B0); PG8_MMA(1, 1, At, B1); PG8_BAR; PG8_SCHED;
;     ...
;         if constexpr (ALIGN_EPI) { if (wr == 0) PG8_BAR; }
	ds_read_b128 v[128:131], v218
	ds_read_b128 v[132:135], v218 offset:1024
	ds_read_b128 v[136:139], v218 offset:2048
	ds_read_b128 v[140:143], v218 offset:3072
	ds_read_b128 v[144:147], v219
	ds_read_b128 v[148:151], v219 offset:1024
	ds_read_b128 v[152:155], v219 offset:2048
	ds_read_b128 v[156:159], v219 offset:3072
	ds_read_b128 v[160:163], v204 offset:32768
	ds_read_b128 v[164:167], v204 offset:33792
	ds_read_b128 v[184:187], v204 offset:34816
	ds_read_b128 v[188:191], v204 offset:35840
	ds_read_b128 v[192:195], v204 offset:36864
	ds_read_b128 v[206:209], v204 offset:37888
	ds_read_b128 v[210:213], v204 offset:38912
	ds_read_b128 v[214:217], v204 offset:39936
	s_add_u32 s98, s60, 0x200000
	s_addc_u32 s99, s61, 0
	s_mov_b32 m0, s33
	s_add_u32 s100, s60, 0x80
	s_addc_u32 s101, s61, 0
	global_load_lds_dwordx4 v168, s[98:99]
	s_mov_b32 m0, s49
	s_nop 0
	global_load_lds_dwordx4 v172, s[98:99]
	s_add_i32 s73, 0, 0x18000
	s_add_i32 s74, 0, 0x1c000
	s_waitcnt vmcnt(8)
	s_waitcnt lgkmcnt(0)
	s_setprio 1
	s_barrier
	v_mfma_f32_16x16x32_bf16 v[124:127], v[128:131], v[160:163], v[124:127]
	v_mfma_f32_16x16x32_bf16 v[120:123], v[136:139], v[160:163], v[120:123]
	v_mfma_f32_16x16x32_bf16 v[116:119], v[128:131], v[184:187], v[116:119]
	v_mfma_f32_16x16x32_bf16 v[108:111], v[136:139], v[184:187], v[108:111]
	v_mfma_f32_16x16x32_bf16 v[92:95], v[128:131], v[192:195], v[92:95]
	v_mfma_f32_16x16x32_bf16 v[88:91], v[136:139], v[192:195], v[88:91]
	v_mfma_f32_16x16x32_bf16 v[76:79], v[128:131], v[210:213], v[76:79]
	v_mfma_f32_16x16x32_bf16 v[72:75], v[136:139], v[210:213], v[72:75]
	v_mfma_f32_16x16x32_bf16 v[124:127], v[132:135], v[164:167], v[124:127]
	v_mfma_f32_16x16x32_bf16 v[120:123], v[140:143], v[164:167], v[120:123]
	v_mfma_f32_16x16x32_bf16 v[116:119], v[132:135], v[188:191], v[116:119]
	v_mfma_f32_16x16x32_bf16 v[108:111], v[140:143], v[188:191], v[108:111]
	v_mfma_f32_16x16x32_bf16 v[92:95], v[132:135], v[206:209], v[92:95]
	v_mfma_f32_16x16x32_bf16 v[88:91], v[140:143], v[206:209], v[88:91]
	v_mfma_f32_16x16x32_bf16 v[76:79], v[132:135], v[214:217], v[76:79]
	v_mfma_f32_16x16x32_bf16 v[72:75], v[140:143], v[214:217], v[72:75]
	v_mfma_f32_16x16x32_bf16 v[112:115], v[144:147], v[160:163], v[112:115]
	v_mfma_f32_16x16x32_bf16 v[104:107], v[152:155], v[160:163], v[104:107]
	v_mfma_f32_16x16x32_bf16 v[100:103], v[144:147], v[184:187], v[100:103]
	v_mfma_f32_16x16x32_bf16 v[96:99], v[152:155], v[184:187], v[96:99]
	v_mfma_f32_16x16x32_bf16 v[84:87], v[144:147], v[192:195], v[84:87]
	v_mfma_f32_16x16x32_bf16 v[80:83], v[152:155], v[192:195], v[80:83]
	v_mfma_f32_16x16x32_bf16 v[68:71], v[144:147], v[210:213], v[68:71]
	v_mfma_f32_16x16x32_bf16 v[64:67], v[152:155], v[210:213], v[64:67]
	v_mfma_f32_16x16x32_bf16 v[112:115], v[148:151], v[164:167], v[112:115]
	v_mfma_f32_16x16x32_bf16 v[104:107], v[156:159], v[164:167], v[104:107]
	v_mfma_f32_16x16x32_bf16 v[100:103], v[148:151], v[188:191], v[100:103]
	v_mfma_f32_16x16x32_bf16 v[96:99], v[156:159], v[188:191], v[96:99]
	v_mfma_f32_16x16x32_bf16 v[84:87], v[148:151], v[206:209], v[84:87]
	v_mfma_f32_16x16x32_bf16 v[80:83], v[156:159], v[206:209], v[80:83]
	v_mfma_f32_16x16x32_bf16 v[68:71], v[148:151], v[214:217], v[68:71]
	v_mfma_f32_16x16x32_bf16 v[64:67], v[156:159], v[214:217], v[64:67]
	s_setprio 0
	s_barrier
	s_add_u32 s98, s58, 0x80
	s_addc_u32 s99, s59, 0
	s_add_i32 s60, s73, s1
	s_mov_b32 m0, s60
	ds_read_b128 v[160:163], v204 offset:49152
	ds_read_b128 v[164:167], v204 offset:50176
	ds_read_b128 v[184:187], v204 offset:51200
	ds_read_b128 v[188:191], v204 offset:52224
	ds_read_b128 v[192:195], v204 offset:53248
	ds_read_b128 v[206:209], v204 offset:54272
	ds_read_b128 v[210:213], v204 offset:55296
	ds_read_b128 v[214:217], v204 offset:56320
	global_load_lds_dwordx4 v170, s[98:99]
	s_add_i32 m0, s60, 0x2000
	s_add_u32 s58, s58, 0x200080
	s_addc_u32 s59, s59, 0
	s_add_i32 s60, s74, s1
	global_load_lds_dwordx4 v174, s[98:99]
	s_mov_b32 m0, s60
	s_nop 0
	global_load_lds_dwordx4 v170, s[58:59]
	s_add_i32 m0, s60, 0x2000
	s_nop 0
	global_load_lds_dwordx4 v174, s[58:59]
	s_mov_b32 m0, s63
	s_nop 0
	global_load_lds_dwordx4 v168, s[100:101]
	s_mov_b32 m0, s64
	s_nop 0
	global_load_lds_dwordx4 v172, s[100:101]
	s_waitcnt vmcnt(8)
	s_waitcnt lgkmcnt(0)
	s_setprio 1
	s_barrier
	v_mfma_f32_16x16x32_bf16 v[60:63], v[128:131], v[160:163], v[60:63]
	v_mfma_f32_16x16x32_bf16 v[56:59], v[136:139], v[160:163], v[56:59]
	v_mfma_f32_16x16x32_bf16 v[44:47], v[128:131], v[184:187], v[44:47]
	v_mfma_f32_16x16x32_bf16 v[40:43], v[136:139], v[184:187], v[40:43]
	v_mfma_f32_16x16x32_bf16 v[28:31], v[128:131], v[192:195], v[28:31]
	v_mfma_f32_16x16x32_bf16 v[24:27], v[136:139], v[192:195], v[24:27]
	v_mfma_f32_16x16x32_bf16 v[12:15], v[128:131], v[210:213], v[12:15]
	v_mfma_f32_16x16x32_bf16 v[8:11], v[136:139], v[210:213], v[8:11]
	v_mfma_f32_16x16x32_bf16 v[60:63], v[132:135], v[164:167], v[60:63]
	v_mfma_f32_16x16x32_bf16 v[56:59], v[140:143], v[164:167], v[56:59]
	v_mfma_f32_16x16x32_bf16 v[44:47], v[132:135], v[188:191], v[44:47]
	v_mfma_f32_16x16x32_bf16 v[40:43], v[140:143], v[188:191], v[40:43]
	v_mfma_f32_16x16x32_bf16 v[28:31], v[132:135], v[206:209], v[28:31]
	v_mfma_f32_16x16x32_bf16 v[24:27], v[140:143], v[206:209], v[24:27]
	v_mfma_f32_16x16x32_bf16 v[12:15], v[132:135], v[214:217], v[12:15]
	v_mfma_f32_16x16x32_bf16 v[8:11], v[140:143], v[214:217], v[8:11]
	v_mfma_f32_16x16x32_bf16 v[52:55], v[144:147], v[160:163], v[52:55]
	v_mfma_f32_16x16x32_bf16 v[48:51], v[152:155], v[160:163], v[48:51]
	v_mfma_f32_16x16x32_bf16 v[36:39], v[144:147], v[184:187], v[36:39]
	v_mfma_f32_16x16x32_bf16 v[32:35], v[152:155], v[184:187], v[32:35]
	v_mfma_f32_16x16x32_bf16 v[20:23], v[144:147], v[192:195], v[20:23]
	v_mfma_f32_16x16x32_bf16 v[16:19], v[152:155], v[192:195], v[16:19]
	v_mfma_f32_16x16x32_bf16 v[4:7], v[144:147], v[210:213], v[4:7]
	v_mfma_f32_16x16x32_bf16 v[0:3], v[152:155], v[210:213], v[0:3]
	v_mfma_f32_16x16x32_bf16 v[52:55], v[148:151], v[164:167], v[52:55]
	v_mfma_f32_16x16x32_bf16 v[48:51], v[156:159], v[164:167], v[48:51]
	v_mfma_f32_16x16x32_bf16 v[36:39], v[148:151], v[188:191], v[36:39]
	v_mfma_f32_16x16x32_bf16 v[32:35], v[156:159], v[188:191], v[32:35]
	v_mfma_f32_16x16x32_bf16 v[20:23], v[148:151], v[206:209], v[20:23]
	v_mfma_f32_16x16x32_bf16 v[16:19], v[156:159], v[206:209], v[16:19]
	v_mfma_f32_16x16x32_bf16 v[4:7], v[148:151], v[214:217], v[4:7]
	v_mfma_f32_16x16x32_bf16 v[0:3], v[156:159], v[214:217], v[0:3]
	s_setprio 0
	s_barrier
	s_add_i32 s72, s72, 2
	s_add_u32 s50, s50, 0x100
	s_addc_u32 s51, s51, 0
	s_add_u32 s70, s70, 0x100
	s_addc_u32 s71, s71, 0
	s_cmpk_gt_u32 s72, 0x7d
	s_cbranch_scc0 .LBB0_1260
	s_and_b64 vcc, exec, s[12:13]
	s_cbranch_vccz .LBB0_1263
	s_barrier

; #define PG8_STAGE(bufoff, gbase, voff) do { _Pragma("unroll") for (int _i = 0; _i < 2; ++_i) \
;         __builtin_amdgcn_global_load_lds((const unsigned*)((const char*)(gbase) + (voff)[_i]), (PG8_LAS unsigned*)(lds + (bufoff) + ldsw + _i * 8192), 16, 0, 0); } while (0)
; #define PG8_LDA(dst, b, h) do { _Pragma("unroll") for (int m = 0; m < 4; ++m) _Pragma("unroll") for (int k = 0; k < 2; ++k) dst[m][k] = *(const PG8_LAS bf16x8*)(lds + PG8_SA(b, h) + aoff + m * 2048 + k * 1024); } while (0)
; #define PG8_LDB(dst, b, h) do { _Pragma("unroll") for (int n = 0; n < 2; ++n) _Pragma("unroll") for (int k = 0; k < 2; ++k) dst[n][k] = *(const PG8_LAS bf16x8*)(lds + PG8_SB(b, h) + boff + n * 2048 + k * 1024); } while (0)
; #define PG8_MMA(ai, bj, At, Bt) do { __builtin_amdgcn_s_setprio(1); _Pragma("unroll") for (int m = 0; m < 4; ++m) _Pragma("unroll") for (int n = 0; n < 2; ++n) _Pragma("unroll") for (int k = 0; k < 2; ++k) \
;         acc[ai][bj][m][n] = __builtin_amdgcn_mfma_f32_16x16x32_bf16(Bt[n][k], At[m][k], acc[ai][bj][m][n], 0, 0, 0); __builtin_amdgcn_s_setprio(0); } while (0)
; #define PG8_WAIT_V(n) asm volatile("s_waitcnt vmcnt(" #n ")" ::: "memory")
; #define PG8_WAIT_L(n) asm volatile("s_waitcnt lgkmcnt(" #n ")" ::: "memory")
; #define PG8_BAR __builtin_amdgcn_s_barrier()
; #define PG8_SCHED __builtin_amdgcn_sched_barrier(0)
; template <class Epi, class Sched, bool ALIGN_EPI = false, bool SP2 = false>
; __device__ __forceinline__ void gemm_phase(PG8_LAS unsigned char* lds, const Gemm g, const Sched& S, const Epi& E) {
;     ...
;             const char* a2 = last ? nA : cA + (size_t)(t + 2) * kstep; const char* b2 = last ? nB : cB + (size_t)(t + 2) * kstep;
;             const char* a3 = a2 + kstep; const char* b3 = b2 + kstep;
;             if (last && has_next) S.a_ready(nxt);
;             if constexpr (SP2) {
;             PG8_LDB(B0, 0, 0); PG8_LDB(B1, 0, 1); PG8_SCHED; PG8_LDA(At, 0, 0); PG8_STAGE(PG8_SA(1, 1), a1 + hstep, voffA);
;             PG8_WAIT_V(8); PG8_WAIT_L(0); PG8_BAR; PG8_MMA(0, 0, At, B0); PG8_MMA(0, 1, At, B1); PG8_BAR; PG8_SCHED;
;             PG8_LDA(At, 0, 1); PG8_STAGE(PG8_SB(0, 0), b2, voffB); PG8_STAGE(PG8_SB(0, 1), b2 + hstep, voffB); PG8_STAGE(PG8_SA(0, 0), a2, voffA);
;             PG8_WAIT_V(8); PG8_WAIT_L(0); PG8_BAR; PG8_MMA(1, 0, At, B0); PG8_MMA(1, 1, At, B1); PG8_BAR; PG8_SCHED;
.LBB0_1336:
	ds_read_b128 v[152:155], v149
	ds_read_b128 v[156:159], v149 offset:1024
	ds_read_b128 v[160:163], v149 offset:2048
	ds_read_b128 v[164:167], v149 offset:3072
	ds_read_b128 v[168:171], v150
	ds_read_b128 v[172:175], v150 offset:1024
	ds_read_b128 v[176:179], v150 offset:2048
	ds_read_b128 v[180:183], v150 offset:3072
	s_add_i32 m0, s33, 0xc000
	ds_read_b128 v[184:187], v151
	ds_read_b128 v[188:191], v151 offset:1024
	ds_read_b128 v[192:195], v151 offset:2048
	ds_read_b128 v[196:199], v151 offset:3072
	ds_read_b128 v[200:203], v151 offset:4096
	ds_read_b128 v[204:207], v151 offset:5120
	ds_read_b128 v[208:211], v151 offset:6144
	ds_read_b128 v[212:215], v151 offset:7168
	global_load_lds_dwordx4 v136, s[46:47]
	s_add_i32 m0, s33, 0xe000
	s_nop 0
	global_load_lds_dwordx4 v138, s[46:47]
	s_add_u32 s48, s46, 0xfff80080
	s_addc_u32 s49, s47, -1
	s_cmp_eq_u32 s74, 28
	s_cselect_b32 s51, s25, s49
	s_cselect_b32 s50, s29, s48
	s_cselect_b32 s49, s23, s73
	s_cselect_b32 s48, s71, s72
	s_waitcnt vmcnt(8)
	s_waitcnt lgkmcnt(0)
	s_setprio 1
	s_barrier
	v_mfma_f32_16x16x32_bf16 v[124:127], v[152:155], v[184:187], v[124:127]
	v_mfma_f32_16x16x32_bf16 v[120:123], v[160:163], v[184:187], v[120:123]
	v_mfma_f32_16x16x32_bf16 v[108:111], v[152:155], v[192:195], v[108:111]
	v_mfma_f32_16x16x32_bf16 v[104:107], v[160:163], v[192:195], v[104:107]
	v_mfma_f32_16x16x32_bf16 v[92:95], v[152:155], v[200:203], v[92:95]
	v_mfma_f32_16x16x32_bf16 v[88:91], v[160:163], v[200:203], v[88:91]
	v_mfma_f32_16x16x32_bf16 v[76:79], v[152:155], v[208:211], v[76:79]
	v_mfma_f32_16x16x32_bf16 v[72:75], v[160:163], v[208:211], v[72:75]
	v_mfma_f32_16x16x32_bf16 v[124:127], v[156:159], v[188:191], v[124:127]
	v_mfma_f32_16x16x32_bf16 v[120:123], v[164:167], v[188:191], v[120:123]
	v_mfma_f32_16x16x32_bf16 v[108:111], v[156:159], v[196:199], v[108:111]
	v_mfma_f32_16x16x32_bf16 v[104:107], v[164:167], v[196:199], v[104:107]
	v_mfma_f32_16x16x32_bf16 v[92:95], v[156:159], v[204:207], v[92:95]
	v_mfma_f32_16x16x32_bf16 v[88:91], v[164:167], v[204:207], v[88:91]
	v_mfma_f32_16x16x32_bf16 v[76:79], v[156:159], v[212:215], v[76:79]
	v_mfma_f32_16x16x32_bf16 v[72:75], v[164:167], v[212:215], v[72:75]
	v_mfma_f32_16x16x32_bf16 v[116:119], v[168:171], v[184:187], v[116:119]
	v_mfma_f32_16x16x32_bf16 v[112:115], v[176:179], v[184:187], v[112:115]
	v_mfma_f32_16x16x32_bf16 v[100:103], v[168:171], v[192:195], v[100:103]
	v_mfma_f32_16x16x32_bf16 v[96:99], v[176:179], v[192:195], v[96:99]
	v_mfma_f32_16x16x32_bf16 v[84:87], v[168:171], v[200:203], v[84:87]
	v_mfma_f32_16x16x32_bf16 v[80:83], v[176:179], v[200:203], v[80:83]
	v_mfma_f32_16x16x32_bf16 v[68:71], v[168:171], v[208:211], v[68:71]
	v_mfma_f32_16x16x32_bf16 v[64:67], v[176:179], v[208:211], v[64:67]
	v_mfma_f32_16x16x32_bf16 v[116:119], v[172:175], v[188:191], v[116:119]
	v_mfma_f32_16x16x32_bf16 v[112:115], v[180:183], v[188:191], v[112:115]
	v_mfma_f32_16x16x32_bf16 v[100:103], v[172:175], v[196:199], v[100:103]
	v_mfma_f32_16x16x32_bf16 v[96:99], v[180:183], v[196:199], v[96:99]
	v_mfma_f32_16x16x32_bf16 v[84:87], v[172:175], v[204:207], v[84:87]
	v_mfma_f32_16x16x32_bf16 v[80:83], v[180:183], v[204:207], v[80:83]
	v_mfma_f32_16x16x32_bf16 v[68:71], v[172:175], v[212:215], v[68:71]
	v_mfma_f32_16x16x32_bf16 v[64:67], v[180:183], v[212:215], v[64:67]
	s_setprio 0
	s_barrier
	s_add_i32 s75, s65, s1
	s_mov_b32 m0, s75
	ds_read_b128 v[184:187], v151 offset:16384
	ds_read_b128 v[188:191], v151 offset:17408
	ds_read_b128 v[192:195], v151 offset:18432
	ds_read_b128 v[196:199], v151 offset:19456
	ds_read_b128 v[200:203], v151 offset:20480
	ds_read_b128 v[204:207], v151 offset:21504
	ds_read_b128 v[208:211], v151 offset:22528
	ds_read_b128 v[212:215], v151 offset:23552
	global_load_lds_dwordx4 v130, s[48:49]
	s_add_i32 m0, s75, 0x2000
	s_add_u32 s76, s48, 0x80000
	s_addc_u32 s77, s49, 0
	s_add_i32 s75, s66, s1
	global_load_lds_dwordx4 v134, s[48:49]
	s_mov_b32 m0, s75
	s_nop 0
	global_load_lds_dwordx4 v130, s[76:77]
	s_add_i32 m0, s75, 0x2000
	s_nop 0
	global_load_lds_dwordx4 v134, s[76:77]
	s_mov_b32 m0, s33
	s_nop 0
	global_load_lds_dwordx4 v128, s[50:51]
	s_mov_b32 m0, s43
	s_nop 0
	global_load_lds_dwordx4 v132, s[50:51]
	s_waitcnt vmcnt(8)
	s_waitcnt lgkmcnt(0)
	s_setprio 1
	s_barrier
	v_mfma_f32_16x16x32_bf16 v[60:63], v[152:155], v[184:187], v[60:63]
	v_mfma_f32_16x16x32_bf16 v[56:59], v[160:163], v[184:187], v[56:59]
	v_mfma_f32_16x16x32_bf16 v[44:47], v[152:155], v[192:195], v[44:47]
	v_mfma_f32_16x16x32_bf16 v[40:43], v[160:163], v[192:195], v[40:43]
	v_mfma_f32_16x16x32_bf16 v[28:31], v[152:155], v[200:203], v[28:31]
	v_mfma_f32_16x16x32_bf16 v[24:27], v[160:163], v[200:203], v[24:27]
	v_mfma_f32_16x16x32_bf16 v[12:15], v[152:155], v[208:211], v[12:15]
	v_mfma_f32_16x16x32_bf16 v[8:11], v[160:163], v[208:211], v[8:11]
	v_mfma_f32_16x16x32_bf16 v[60:63], v[156:159], v[188:191], v[60:63]
	v_mfma_f32_16x16x32_bf16 v[56:59], v[164:167], v[188:191], v[56:59]
	v_mfma_f32_16x16x32_bf16 v[44:47], v[156:159], v[196:199], v[44:47]
	v_mfma_f32_16x16x32_bf16 v[40:43], v[164:167], v[196:199], v[40:43]
	v_mfma_f32_16x16x32_bf16 v[28:31], v[156:159], v[204:207], v[28:31]
	v_mfma_f32_16x16x32_bf16 v[24:27], v[164:167], v[204:207], v[24:27]
	v_mfma_f32_16x16x32_bf16 v[12:15], v[156:159], v[212:215], v[12:15]
	v_mfma_f32_16x16x32_bf16 v[8:11], v[164:167], v[212:215], v[8:11]
	v_mfma_f32_16x16x32_bf16 v[52:55], v[168:171], v[184:187], v[52:55]
	v_mfma_f32_16x16x32_bf16 v[48:51], v[176:179], v[184:187], v[48:51]
	v_mfma_f32_16x16x32_bf16 v[36:39], v[168:171], v[192:195], v[36:39]
	v_mfma_f32_16x16x32_bf16 v[32:35], v[176:179], v[192:195], v[32:35]
	v_mfma_f32_16x16x32_bf16 v[20:23], v[168:171], v[200:203], v[20:23]
	v_mfma_f32_16x16x32_bf16 v[16:19], v[176:179], v[200:203], v[16:19]
	v_mfma_f32_16x16x32_bf16 v[4:7], v[168:171], v[208:211], v[4:7]
	v_mfma_f32_16x16x32_bf16 v[0:3], v[176:179], v[208:211], v[0:3]
	v_mfma_f32_16x16x32_bf16 v[52:55], v[172:175], v[188:191], v[52:55]
	v_mfma_f32_16x16x32_bf16 v[48:51], v[180:183], v[188:191], v[48:51]
	v_mfma_f32_16x16x32_bf16 v[36:39], v[172:175], v[196:199], v[36:39]
	v_mfma_f32_16x16x32_bf16 v[32:35], v[180:183], v[196:199], v[32:35]
	v_mfma_f32_16x16x32_bf16 v[20:23], v[172:175], v[204:207], v[20:23]
	v_mfma_f32_16x16x32_bf16 v[16:19], v[180:183], v[204:207], v[16:19]
	v_mfma_f32_16x16x32_bf16 v[4:7], v[172:175], v[212:215], v[4:7]
	v_mfma_f32_16x16x32_bf16 v[0:3], v[180:183], v[212:215], v[0:3]
	s_setprio 0
	s_barrier
; #define PG8_STAGE(bufoff, gbase, voff) do { _Pragma("unroll") for (int _i = 0; _i < 2; ++_i) \
;         __builtin_amdgcn_global_load_lds((const unsigned*)((const char*)(gbase) + (voff)[_i]), (PG8_LAS unsigned*)(lds + (bufoff) + ldsw + _i * 8192), 16, 0, 0); } while (0)
; #define PG8_LDA(dst, b, h) do { _Pragma("unroll") for (int m = 0; m < 4; ++m) _Pragma("unroll") for (int k = 0; k < 2; ++k) dst[m][k] = *(const PG8_LAS bf16x8*)(lds + PG8_SA(b, h) + aoff + m * 2048 + k * 1024); } while (0)
; #define PG8_LDB(dst, b, h) do { _Pragma("unroll") for (int n = 0; n < 2; ++n) _Pragma("unroll") for (int k = 0; k < 2; ++k) dst[n][k] = *(const PG8_LAS bf16x8*)(lds + PG8_SB(b, h) + boff + n * 2048 + k * 1024); } while (0)
; #define PG8_MMA(ai, bj, At, Bt) do { __builtin_amdgcn_s_setprio(1); _Pragma("unroll") for (int m = 0; m < 4; ++m) _Pragma("unroll") for (int n = 0; n < 2; ++n) _Pragma("unroll") for (int k = 0; k < 2; ++k) \
;         acc[ai][bj][m][n] = __builtin_amdgcn_mfma_f32_16x16x32_bf16(Bt[n][k], At[m][k], acc[ai][bj][m][n], 0, 0, 0); __builtin_amdgcn_s_setprio(0); } while (0)
; #define PG8_WAIT_V(n) asm volatile("s_waitcnt vmcnt(" #n ")" ::: "memory")
; #define PG8_WAIT_L(n) asm volatile("s_waitcnt lgkmcnt(" #n ")" ::: "memory")
; #define PG8_BAR __builtin_amdgcn_s_barrier()
; #define PG8_SCHED __builtin_amdgcn_sched_barrier(0)
; template <class Epi, class Sched, bool ALIGN_EPI = false, bool SP2 = false>
; __device__ __forceinline__ void gemm_phase(PG8_LAS unsigned char* lds, const Gemm g, const Sched& S, const Epi& E) {
;     ...
;             PG8_LDB(B0, 1, 0); PG8_LDB(B1, 1, 1); PG8_SCHED; PG8_LDA(At, 1, 0); PG8_STAGE(PG8_SA(0, 1), a2 + hstep, voffA);
;             PG8_WAIT_V(8); PG8_WAIT_L(0); PG8_BAR; PG8_MMA(0, 0, At, B0); PG8_MMA(0, 1, At, B1); PG8_BAR; PG8_SCHED;
;             PG8_LDA(At, 1, 1); PG8_STAGE(PG8_SB(1, 0), b3, voffB); PG8_STAGE(PG8_SB(1, 1), b3 + hstep, voffB); PG8_STAGE(PG8_SA(1, 0), a3, voffA);
;             PG8_WAIT_V(8); PG8_WAIT_L(0); PG8_BAR; PG8_MMA(1, 0, At, B0); PG8_MMA(1, 1, At, B1); PG8_BAR; PG8_SCHED;
;     ...
;         if constexpr (ALIGN_EPI) { if (wr == 0) PG8_BAR; }
	ds_read_b128 v[152:155], v216
	ds_read_b128 v[156:159], v216 offset:1024
	ds_read_b128 v[160:163], v216 offset:2048
	ds_read_b128 v[164:167], v216 offset:3072
	ds_read_b128 v[168:171], v217
	ds_read_b128 v[172:175], v217 offset:1024
	ds_read_b128 v[176:179], v217 offset:2048
	ds_read_b128 v[180:183], v217 offset:3072
	ds_read_b128 v[184:187], v151 offset:32768
	ds_read_b128 v[188:191], v151 offset:33792
	ds_read_b128 v[192:195], v151 offset:34816
	ds_read_b128 v[196:199], v151 offset:35840
	ds_read_b128 v[200:203], v151 offset:36864
	ds_read_b128 v[204:207], v151 offset:37888
	ds_read_b128 v[208:211], v151 offset:38912
	ds_read_b128 v[212:215], v151 offset:39936
	s_add_u32 s98, s50, 0x80000
	s_addc_u32 s99, s51, 0
	s_mov_b32 m0, s58
	s_add_u32 s100, s50, 0x80
	s_addc_u32 s101, s51, 0
	global_load_lds_dwordx4 v128, s[98:99]
	s_mov_b32 m0, s59
	s_nop 0
	global_load_lds_dwordx4 v132, s[98:99]
	s_add_i32 s75, 0, 0x18000
	s_add_i32 s76, 0, 0x1c000
	s_waitcnt vmcnt(8)
	s_waitcnt lgkmcnt(0)
	s_setprio 1
	s_barrier
	v_mfma_f32_16x16x32_bf16 v[124:127], v[152:155], v[184:187], v[124:127]
	v_mfma_f32_16x16x32_bf16 v[120:123], v[160:163], v[184:187], v[120:123]
	v_mfma_f32_16x16x32_bf16 v[108:111], v[152:155], v[192:195], v[108:111]
	v_mfma_f32_16x16x32_bf16 v[104:107], v[160:163], v[192:195], v[104:107]
	v_mfma_f32_16x16x32_bf16 v[92:95], v[152:155], v[200:203], v[92:95]
	v_mfma_f32_16x16x32_bf16 v[88:91], v[160:163], v[200:203], v[88:91]
	v_mfma_f32_16x16x32_bf16 v[76:79], v[152:155], v[208:211], v[76:79]
	v_mfma_f32_16x16x32_bf16 v[72:75], v[160:163], v[208:211], v[72:75]
	v_mfma_f32_16x16x32_bf16 v[124:127], v[156:159], v[188:191], v[124:127]
	v_mfma_f32_16x16x32_bf16 v[120:123], v[164:167], v[188:191], v[120:123]
	v_mfma_f32_16x16x32_bf16 v[108:111], v[156:159], v[196:199], v[108:111]
	v_mfma_f32_16x16x32_bf16 v[104:107], v[164:167], v[196:199], v[104:107]
	v_mfma_f32_16x16x32_bf16 v[92:95], v[156:159], v[204:207], v[92:95]
	v_mfma_f32_16x16x32_bf16 v[88:91], v[164:167], v[204:207], v[88:91]
	v_mfma_f32_16x16x32_bf16 v[76:79], v[156:159], v[212:215], v[76:79]
	v_mfma_f32_16x16x32_bf16 v[72:75], v[164:167], v[212:215], v[72:75]
	v_mfma_f32_16x16x32_bf16 v[116:119], v[168:171], v[184:187], v[116:119]
	v_mfma_f32_16x16x32_bf16 v[112:115], v[176:179], v[184:187], v[112:115]
	v_mfma_f32_16x16x32_bf16 v[100:103], v[168:171], v[192:195], v[100:103]
	v_mfma_f32_16x16x32_bf16 v[96:99], v[176:179], v[192:195], v[96:99]
	v_mfma_f32_16x16x32_bf16 v[84:87], v[168:171], v[200:203], v[84:87]
	v_mfma_f32_16x16x32_bf16 v[80:83], v[176:179], v[200:203], v[80:83]
	v_mfma_f32_16x16x32_bf16 v[68:71], v[168:171], v[208:211], v[68:71]
	v_mfma_f32_16x16x32_bf16 v[64:67], v[176:179], v[208:211], v[64:67]
	v_mfma_f32_16x16x32_bf16 v[116:119], v[172:175], v[188:191], v[116:119]
	v_mfma_f32_16x16x32_bf16 v[112:115], v[180:183], v[188:191], v[112:115]
	v_mfma_f32_16x16x32_bf16 v[100:103], v[172:175], v[196:199], v[100:103]
	v_mfma_f32_16x16x32_bf16 v[96:99], v[180:183], v[196:199], v[96:99]
	v_mfma_f32_16x16x32_bf16 v[84:87], v[172:175], v[204:207], v[84:87]
	v_mfma_f32_16x16x32_bf16 v[80:83], v[180:183], v[204:207], v[80:83]
	v_mfma_f32_16x16x32_bf16 v[68:71], v[172:175], v[212:215], v[68:71]
	v_mfma_f32_16x16x32_bf16 v[64:67], v[180:183], v[212:215], v[64:67]
	s_setprio 0
	s_barrier
	s_add_u32 s98, s48, 0x80
	s_addc_u32 s99, s49, 0
	s_add_i32 s50, s75, s1
	s_mov_b32 m0, s50
	ds_read_b128 v[184:187], v151 offset:49152
	ds_read_b128 v[188:191], v151 offset:50176
	ds_read_b128 v[192:195], v151 offset:51200
	ds_read_b128 v[196:199], v151 offset:52224
	ds_read_b128 v[200:203], v151 offset:53248
	ds_read_b128 v[204:207], v151 offset:54272
	ds_read_b128 v[208:211], v151 offset:55296
	ds_read_b128 v[212:215], v151 offset:56320
	global_load_lds_dwordx4 v130, s[98:99]
	s_add_i32 m0, s50, 0x2000
	s_add_u32 s48, s48, 0x80080
	s_addc_u32 s49, s49, 0
	s_add_i32 s50, s76, s1
	global_load_lds_dwordx4 v134, s[98:99]
	s_mov_b32 m0, s50
	s_nop 0
	global_load_lds_dwordx4 v130, s[48:49]
	s_add_i32 m0, s50, 0x2000
	s_nop 0
	global_load_lds_dwordx4 v134, s[48:49]
	s_mov_b32 m0, s61
	s_nop 0
	global_load_lds_dwordx4 v128, s[100:101]
	s_mov_b32 m0, s62
	s_nop 0
	global_load_lds_dwordx4 v132, s[100:101]
	s_waitcnt vmcnt(8)
	s_waitcnt lgkmcnt(0)
	s_setprio 1
	s_barrier
	v_mfma_f32_16x16x32_bf16 v[60:63], v[152:155], v[184:187], v[60:63]
	v_mfma_f32_16x16x32_bf16 v[56:59], v[160:163], v[184:187], v[56:59]
	v_mfma_f32_16x16x32_bf16 v[44:47], v[152:155], v[192:195], v[44:47]
	v_mfma_f32_16x16x32_bf16 v[40:43], v[160:163], v[192:195], v[40:43]
	v_mfma_f32_16x16x32_bf16 v[28:31], v[152:155], v[200:203], v[28:31]
	v_mfma_f32_16x16x32_bf16 v[24:27], v[160:163], v[200:203], v[24:27]
	v_mfma_f32_16x16x32_bf16 v[12:15], v[152:155], v[208:211], v[12:15]
	v_mfma_f32_16x16x32_bf16 v[8:11], v[160:163], v[208:211], v[8:11]
	v_mfma_f32_16x16x32_bf16 v[60:63], v[156:159], v[188:191], v[60:63]
	v_mfma_f32_16x16x32_bf16 v[56:59], v[164:167], v[188:191], v[56:59]
	v_mfma_f32_16x16x32_bf16 v[44:47], v[156:159], v[196:199], v[44:47]
	v_mfma_f32_16x16x32_bf16 v[40:43], v[164:167], v[196:199], v[40:43]
	v_mfma_f32_16x16x32_bf16 v[28:31], v[156:159], v[204:207], v[28:31]
	v_mfma_f32_16x16x32_bf16 v[24:27], v[164:167], v[204:207], v[24:27]
	v_mfma_f32_16x16x32_bf16 v[12:15], v[156:159], v[212:215], v[12:15]
	v_mfma_f32_16x16x32_bf16 v[8:11], v[164:167], v[212:215], v[8:11]
	v_mfma_f32_16x16x32_bf16 v[52:55], v[168:171], v[184:187], v[52:55]
	v_mfma_f32_16x16x32_bf16 v[48:51], v[176:179], v[184:187], v[48:51]
	v_mfma_f32_16x16x32_bf16 v[36:39], v[168:171], v[192:195], v[36:39]
	v_mfma_f32_16x16x32_bf16 v[32:35], v[176:179], v[192:195], v[32:35]
	v_mfma_f32_16x16x32_bf16 v[20:23], v[168:171], v[200:203], v[20:23]
	v_mfma_f32_16x16x32_bf16 v[16:19], v[176:179], v[200:203], v[16:19]
	v_mfma_f32_16x16x32_bf16 v[4:7], v[168:171], v[208:211], v[4:7]
	v_mfma_f32_16x16x32_bf16 v[0:3], v[176:179], v[208:211], v[0:3]
	v_mfma_f32_16x16x32_bf16 v[52:55], v[172:175], v[188:191], v[52:55]
	v_mfma_f32_16x16x32_bf16 v[48:51], v[180:183], v[188:191], v[48:51]
	v_mfma_f32_16x16x32_bf16 v[36:39], v[172:175], v[196:199], v[36:39]
	v_mfma_f32_16x16x32_bf16 v[32:35], v[180:183], v[196:199], v[32:35]
	v_mfma_f32_16x16x32_bf16 v[20:23], v[172:175], v[204:207], v[20:23]
	v_mfma_f32_16x16x32_bf16 v[16:19], v[180:183], v[204:207], v[16:19]
	v_mfma_f32_16x16x32_bf16 v[4:7], v[172:175], v[212:215], v[4:7]
	v_mfma_f32_16x16x32_bf16 v[0:3], v[180:183], v[212:215], v[0:3]
	s_setprio 0
	s_barrier
	s_add_i32 s74, s74, 2
	s_add_u32 s46, s46, 0x100
	s_addc_u32 s47, s47, 0
	s_add_u32 s72, s72, 0x100
	s_addc_u32 s73, s73, 0
	s_cmp_gt_u32 s74, 29
	s_cbranch_scc0 .LBB0_1336
	s_and_b64 vcc, exec, s[12:13]
	s_cbranch_vccz .LBB0_1339
	s_barrier

; #define PG8_STAGE(bufoff, gbase, voff) do { _Pragma("unroll") for (int _i = 0; _i < 2; ++_i) \
;         __builtin_amdgcn_global_load_lds((const unsigned*)((const char*)(gbase) + (voff)[_i]), (PG8_LAS unsigned*)(lds + (bufoff) + ldsw + _i * 8192), 16, 0, 0); } while (0)
; #define PG8_LDA(dst, b, h) do { _Pragma("unroll") for (int m = 0; m < 4; ++m) _Pragma("unroll") for (int k = 0; k < 2; ++k) dst[m][k] = *(const PG8_LAS bf16x8*)(lds + PG8_SA(b, h) + aoff + m * 2048 + k * 1024); } while (0)
; #define PG8_LDB(dst, b, h) do { _Pragma("unroll") for (int n = 0; n < 2; ++n) _Pragma("unroll") for (int k = 0; k < 2; ++k) dst[n][k] = *(const PG8_LAS bf16x8*)(lds + PG8_SB(b, h) + boff + n * 2048 + k * 1024); } while (0)
; #define PG8_MMA(ai, bj, At, Bt) do { __builtin_amdgcn_s_setprio(1); _Pragma("unroll") for (int m = 0; m < 4; ++m) _Pragma("unroll") for (int n = 0; n < 2; ++n) _Pragma("unroll") for (int k = 0; k < 2; ++k) \
;         acc[ai][bj][m][n] = __builtin_amdgcn_mfma_f32_16x16x32_bf16(Bt[n][k], At[m][k], acc[ai][bj][m][n], 0, 0, 0); __builtin_amdgcn_s_setprio(0); } while (0)
; #define PG8_WAIT_V(n) asm volatile("s_waitcnt vmcnt(" #n ")" ::: "memory")
; #define PG8_WAIT_L(n) asm volatile("s_waitcnt lgkmcnt(" #n ")" ::: "memory")
; #define PG8_BAR __builtin_amdgcn_s_barrier()
; #define PG8_SCHED __builtin_amdgcn_sched_barrier(0)
; template <class Epi, class Sched, bool ALIGN_EPI = false, bool SP2 = false>
; __device__ __forceinline__ void gemm_phase(PG8_LAS unsigned char* lds, const Gemm g, const Sched& S, const Epi& E) {
;     ...
;             const char* a2 = last ? nA : cA + (size_t)(t + 2) * kstep; const char* b2 = last ? nB : cB + (size_t)(t + 2) * kstep;
;             const char* a3 = a2 + kstep; const char* b3 = b2 + kstep;
;             if (last && has_next) S.a_ready(nxt);
;             if constexpr (SP2) {
;             PG8_LDB(B0, 0, 0); PG8_LDB(B1, 0, 1); PG8_SCHED; PG8_LDA(At, 0, 0); PG8_STAGE(PG8_SA(1, 1), a1 + hstep, voffA);
;             PG8_WAIT_V(8); PG8_WAIT_L(0); PG8_BAR; PG8_MMA(0, 0, At, B0); PG8_MMA(0, 1, At, B1); PG8_BAR; PG8_SCHED;
;             PG8_LDA(At, 0, 1); PG8_STAGE(PG8_SB(0, 0), b2, voffB); PG8_STAGE(PG8_SB(0, 1), b2 + hstep, voffB); PG8_STAGE(PG8_SA(0, 0), a2, voffA);
;             PG8_WAIT_V(8); PG8_WAIT_L(0); PG8_BAR; PG8_MMA(1, 0, At, B0); PG8_MMA(1, 1, At, B1); PG8_BAR; PG8_SCHED;
.LBB0_1412:
	ds_read_b128 v[128:131], v202
	ds_read_b128 v[132:135], v202 offset:1024
	ds_read_b128 v[136:139], v202 offset:2048
	ds_read_b128 v[140:143], v202 offset:3072
	ds_read_b128 v[144:147], v203
	ds_read_b128 v[148:151], v203 offset:1024
	ds_read_b128 v[152:155], v203 offset:2048
	ds_read_b128 v[156:159], v203 offset:3072
	s_add_i32 m0, s33, 0xc000
	ds_read_b128 v[160:163], v204
	ds_read_b128 v[164:167], v204 offset:1024
	ds_read_b128 v[184:187], v204 offset:2048
	ds_read_b128 v[188:191], v204 offset:3072
	ds_read_b128 v[192:195], v204 offset:4096
	ds_read_b128 v[206:209], v204 offset:5120
	ds_read_b128 v[210:213], v204 offset:6144
	ds_read_b128 v[214:217], v204 offset:7168
	global_load_lds_dwordx4 v176, s[42:43]
	s_add_i32 m0, s33, 0xe000
	s_nop 0
	global_load_lds_dwordx4 v178, s[42:43]
	s_add_u32 s46, s42, 0xffe00080
	s_addc_u32 s47, s43, -1
	s_cmpk_eq_i32 s68, 0x7c
	s_cselect_b32 s49, s23, s47
	s_cselect_b32 s48, s25, s46
	s_cselect_b32 s47, s21, s67
	s_cselect_b32 s46, s65, s66
	s_waitcnt vmcnt(8)
	s_waitcnt lgkmcnt(0)
	s_setprio 1
	s_barrier
	v_mfma_f32_16x16x32_bf16 v[124:127], v[128:131], v[160:163], v[124:127]
	v_mfma_f32_16x16x32_bf16 v[120:123], v[136:139], v[160:163], v[120:123]
	v_mfma_f32_16x16x32_bf16 v[116:119], v[128:131], v[184:187], v[116:119]
	v_mfma_f32_16x16x32_bf16 v[108:111], v[136:139], v[184:187], v[108:111]
	v_mfma_f32_16x16x32_bf16 v[92:95], v[128:131], v[192:195], v[92:95]
	v_mfma_f32_16x16x32_bf16 v[88:91], v[136:139], v[192:195], v[88:91]
	v_mfma_f32_16x16x32_bf16 v[76:79], v[128:131], v[210:213], v[76:79]
	v_mfma_f32_16x16x32_bf16 v[72:75], v[136:139], v[210:213], v[72:75]
	v_mfma_f32_16x16x32_bf16 v[124:127], v[132:135], v[164:167], v[124:127]
	v_mfma_f32_16x16x32_bf16 v[120:123], v[140:143], v[164:167], v[120:123]
	v_mfma_f32_16x16x32_bf16 v[116:119], v[132:135], v[188:191], v[116:119]
	v_mfma_f32_16x16x32_bf16 v[108:111], v[140:143], v[188:191], v[108:111]
	v_mfma_f32_16x16x32_bf16 v[92:95], v[132:135], v[206:209], v[92:95]
	v_mfma_f32_16x16x32_bf16 v[88:91], v[140:143], v[206:209], v[88:91]
	v_mfma_f32_16x16x32_bf16 v[76:79], v[132:135], v[214:217], v[76:79]
	v_mfma_f32_16x16x32_bf16 v[72:75], v[140:143], v[214:217], v[72:75]
	v_mfma_f32_16x16x32_bf16 v[112:115], v[144:147], v[160:163], v[112:115]
	v_mfma_f32_16x16x32_bf16 v[104:107], v[152:155], v[160:163], v[104:107]
	v_mfma_f32_16x16x32_bf16 v[100:103], v[144:147], v[184:187], v[100:103]
	v_mfma_f32_16x16x32_bf16 v[96:99], v[152:155], v[184:187], v[96:99]
	v_mfma_f32_16x16x32_bf16 v[84:87], v[144:147], v[192:195], v[84:87]
	v_mfma_f32_16x16x32_bf16 v[80:83], v[152:155], v[192:195], v[80:83]
	v_mfma_f32_16x16x32_bf16 v[68:71], v[144:147], v[210:213], v[68:71]
	v_mfma_f32_16x16x32_bf16 v[64:67], v[152:155], v[210:213], v[64:67]
	v_mfma_f32_16x16x32_bf16 v[112:115], v[148:151], v[164:167], v[112:115]
	v_mfma_f32_16x16x32_bf16 v[104:107], v[156:159], v[164:167], v[104:107]
	v_mfma_f32_16x16x32_bf16 v[100:103], v[148:151], v[188:191], v[100:103]
	v_mfma_f32_16x16x32_bf16 v[96:99], v[156:159], v[188:191], v[96:99]
	v_mfma_f32_16x16x32_bf16 v[84:87], v[148:151], v[206:209], v[84:87]
	v_mfma_f32_16x16x32_bf16 v[80:83], v[156:159], v[206:209], v[80:83]
	v_mfma_f32_16x16x32_bf16 v[68:71], v[148:151], v[214:217], v[68:71]
	v_mfma_f32_16x16x32_bf16 v[64:67], v[156:159], v[214:217], v[64:67]
	s_setprio 0
	s_barrier
	s_add_i32 s69, s63, s1
	s_mov_b32 m0, s69
	ds_read_b128 v[160:163], v204 offset:16384
	ds_read_b128 v[164:167], v204 offset:17408
	ds_read_b128 v[184:187], v204 offset:18432
	ds_read_b128 v[188:191], v204 offset:19456
	ds_read_b128 v[192:195], v204 offset:20480
	ds_read_b128 v[206:209], v204 offset:21504
	ds_read_b128 v[210:213], v204 offset:22528
	ds_read_b128 v[214:217], v204 offset:23552
	global_load_lds_dwordx4 v170, s[46:47]
	s_add_i32 m0, s69, 0x2000
	s_add_u32 s70, s46, 0x200000
	s_addc_u32 s71, s47, 0
	s_add_i32 s69, s64, s1
	global_load_lds_dwordx4 v174, s[46:47]
	s_mov_b32 m0, s69
	s_nop 0
	global_load_lds_dwordx4 v170, s[70:71]
	s_add_i32 m0, s69, 0x2000
	s_nop 0
	global_load_lds_dwordx4 v174, s[70:71]
	s_mov_b32 m0, s33
	s_nop 0
	global_load_lds_dwordx4 v168, s[48:49]
	s_mov_b32 m0, s41
	s_nop 0
	global_load_lds_dwordx4 v172, s[48:49]
	s_waitcnt vmcnt(8)
	s_waitcnt lgkmcnt(0)
	s_setprio 1
	s_barrier
	v_mfma_f32_16x16x32_bf16 v[60:63], v[128:131], v[160:163], v[60:63]
	v_mfma_f32_16x16x32_bf16 v[56:59], v[136:139], v[160:163], v[56:59]
	v_mfma_f32_16x16x32_bf16 v[44:47], v[128:131], v[184:187], v[44:47]
	v_mfma_f32_16x16x32_bf16 v[40:43], v[136:139], v[184:187], v[40:43]
	v_mfma_f32_16x16x32_bf16 v[28:31], v[128:131], v[192:195], v[28:31]
	v_mfma_f32_16x16x32_bf16 v[24:27], v[136:139], v[192:195], v[24:27]
	v_mfma_f32_16x16x32_bf16 v[12:15], v[128:131], v[210:213], v[12:15]
	v_mfma_f32_16x16x32_bf16 v[8:11], v[136:139], v[210:213], v[8:11]
	v_mfma_f32_16x16x32_bf16 v[60:63], v[132:135], v[164:167], v[60:63]
	v_mfma_f32_16x16x32_bf16 v[56:59], v[140:143], v[164:167], v[56:59]
	v_mfma_f32_16x16x32_bf16 v[44:47], v[132:135], v[188:191], v[44:47]
	v_mfma_f32_16x16x32_bf16 v[40:43], v[140:143], v[188:191], v[40:43]
	v_mfma_f32_16x16x32_bf16 v[28:31], v[132:135], v[206:209], v[28:31]
	v_mfma_f32_16x16x32_bf16 v[24:27], v[140:143], v[206:209], v[24:27]
	v_mfma_f32_16x16x32_bf16 v[12:15], v[132:135], v[214:217], v[12:15]
	v_mfma_f32_16x16x32_bf16 v[8:11], v[140:143], v[214:217], v[8:11]
	v_mfma_f32_16x16x32_bf16 v[52:55], v[144:147], v[160:163], v[52:55]
	v_mfma_f32_16x16x32_bf16 v[48:51], v[152:155], v[160:163], v[48:51]
	v_mfma_f32_16x16x32_bf16 v[36:39], v[144:147], v[184:187], v[36:39]
	v_mfma_f32_16x16x32_bf16 v[32:35], v[152:155], v[184:187], v[32:35]
	v_mfma_f32_16x16x32_bf16 v[20:23], v[144:147], v[192:195], v[20:23]
	v_mfma_f32_16x16x32_bf16 v[16:19], v[152:155], v[192:195], v[16:19]
	v_mfma_f32_16x16x32_bf16 v[4:7], v[144:147], v[210:213], v[4:7]
	v_mfma_f32_16x16x32_bf16 v[0:3], v[152:155], v[210:213], v[0:3]
	v_mfma_f32_16x16x32_bf16 v[52:55], v[148:151], v[164:167], v[52:55]
	v_mfma_f32_16x16x32_bf16 v[48:51], v[156:159], v[164:167], v[48:51]
	v_mfma_f32_16x16x32_bf16 v[36:39], v[148:151], v[188:191], v[36:39]
	v_mfma_f32_16x16x32_bf16 v[32:35], v[156:159], v[188:191], v[32:35]
	v_mfma_f32_16x16x32_bf16 v[20:23], v[148:151], v[206:209], v[20:23]
	v_mfma_f32_16x16x32_bf16 v[16:19], v[156:159], v[206:209], v[16:19]
	v_mfma_f32_16x16x32_bf16 v[4:7], v[148:151], v[214:217], v[4:7]
	v_mfma_f32_16x16x32_bf16 v[0:3], v[156:159], v[214:217], v[0:3]
	s_setprio 0
	s_barrier
; #define PG8_STAGE(bufoff, gbase, voff) do { _Pragma("unroll") for (int _i = 0; _i < 2; ++_i) \
;         __builtin_amdgcn_global_load_lds((const unsigned*)((const char*)(gbase) + (voff)[_i]), (PG8_LAS unsigned*)(lds + (bufoff) + ldsw + _i * 8192), 16, 0, 0); } while (0)
; #define PG8_LDA(dst, b, h) do { _Pragma("unroll") for (int m = 0; m < 4; ++m) _Pragma("unroll") for (int k = 0; k < 2; ++k) dst[m][k] = *(const PG8_LAS bf16x8*)(lds + PG8_SA(b, h) + aoff + m * 2048 + k * 1024); } while (0)
; #define PG8_LDB(dst, b, h) do { _Pragma("unroll") for (int n = 0; n < 2; ++n) _Pragma("unroll") for (int k = 0; k < 2; ++k) dst[n][k] = *(const PG8_LAS bf16x8*)(lds + PG8_SB(b, h) + boff + n * 2048 + k * 1024); } while (0)
; #define PG8_MMA(ai, bj, At, Bt) do { __builtin_amdgcn_s_setprio(1); _Pragma("unroll") for (int m = 0; m < 4; ++m) _Pragma("unroll") for (int n = 0; n < 2; ++n) _Pragma("unroll") for (int k = 0; k < 2; ++k) \
;         acc[ai][bj][m][n] = __builtin_amdgcn_mfma_f32_16x16x32_bf16(Bt[n][k], At[m][k], acc[ai][bj][m][n], 0, 0, 0); __builtin_amdgcn_s_setprio(0); } while (0)
; #define PG8_WAIT_V(n) asm volatile("s_waitcnt vmcnt(" #n ")" ::: "memory")
; #define PG8_WAIT_L(n) asm volatile("s_waitcnt lgkmcnt(" #n ")" ::: "memory")
; #define PG8_BAR __builtin_amdgcn_s_barrier()
; #define PG8_SCHED __builtin_amdgcn_sched_barrier(0)
; template <class Epi, class Sched, bool ALIGN_EPI = false, bool SP2 = false>
; __device__ __forceinline__ void gemm_phase(PG8_LAS unsigned char* lds, const Gemm g, const Sched& S, const Epi& E) {
;     ...
;             PG8_LDB(B0, 1, 0); PG8_LDB(B1, 1, 1); PG8_SCHED; PG8_LDA(At, 1, 0); PG8_STAGE(PG8_SA(0, 1), a2 + hstep, voffA);
;             PG8_WAIT_V(8); PG8_WAIT_L(0); PG8_BAR; PG8_MMA(0, 0, At, B0); PG8_MMA(0, 1, At, B1); PG8_BAR; PG8_SCHED;
;             PG8_LDA(At, 1, 1); PG8_STAGE(PG8_SB(1, 0), b3, voffB); PG8_STAGE(PG8_SB(1, 1), b3 + hstep, voffB); PG8_STAGE(PG8_SA(1, 0), a3, voffA);
;             PG8_WAIT_V(8); PG8_WAIT_L(0); PG8_BAR; PG8_MMA(1, 0, At, B0); PG8_MMA(1, 1, At, B1); PG8_BAR; PG8_SCHED;
;     ...
;         if constexpr (ALIGN_EPI) { if (wr == 0) PG8_BAR; }
	ds_read_b128 v[128:131], v218
	ds_read_b128 v[132:135], v218 offset:1024
	ds_read_b128 v[136:139], v218 offset:2048
	ds_read_b128 v[140:143], v218 offset:3072
	ds_read_b128 v[144:147], v219
	ds_read_b128 v[148:151], v219 offset:1024
	ds_read_b128 v[152:155], v219 offset:2048
	ds_read_b128 v[156:159], v219 offset:3072
	ds_read_b128 v[160:163], v204 offset:32768
	ds_read_b128 v[164:167], v204 offset:33792
	ds_read_b128 v[184:187], v204 offset:34816
	ds_read_b128 v[188:191], v204 offset:35840
	ds_read_b128 v[192:195], v204 offset:36864
	ds_read_b128 v[206:209], v204 offset:37888
	ds_read_b128 v[210:213], v204 offset:38912
	ds_read_b128 v[214:217], v204 offset:39936
	s_add_u32 s98, s48, 0x200000
	s_addc_u32 s99, s49, 0
	s_mov_b32 m0, s50
	s_add_u32 s100, s48, 0x80
	s_addc_u32 s101, s49, 0
	global_load_lds_dwordx4 v168, s[98:99]
	s_mov_b32 m0, s51
	s_nop 0
	global_load_lds_dwordx4 v172, s[98:99]
	s_add_i32 s69, 0, 0x18000
	s_add_i32 s70, 0, 0x1c000
	s_waitcnt vmcnt(8)
	s_waitcnt lgkmcnt(0)
	s_setprio 1
	s_barrier
	v_mfma_f32_16x16x32_bf16 v[124:127], v[128:131], v[160:163], v[124:127]
	v_mfma_f32_16x16x32_bf16 v[120:123], v[136:139], v[160:163], v[120:123]
	v_mfma_f32_16x16x32_bf16 v[116:119], v[128:131], v[184:187], v[116:119]
	v_mfma_f32_16x16x32_bf16 v[108:111], v[136:139], v[184:187], v[108:111]
	v_mfma_f32_16x16x32_bf16 v[92:95], v[128:131], v[192:195], v[92:95]
	v_mfma_f32_16x16x32_bf16 v[88:91], v[136:139], v[192:195], v[88:91]
	v_mfma_f32_16x16x32_bf16 v[76:79], v[128:131], v[210:213], v[76:79]
	v_mfma_f32_16x16x32_bf16 v[72:75], v[136:139], v[210:213], v[72:75]
	v_mfma_f32_16x16x32_bf16 v[124:127], v[132:135], v[164:167], v[124:127]
	v_mfma_f32_16x16x32_bf16 v[120:123], v[140:143], v[164:167], v[120:123]
	v_mfma_f32_16x16x32_bf16 v[116:119], v[132:135], v[188:191], v[116:119]
	v_mfma_f32_16x16x32_bf16 v[108:111], v[140:143], v[188:191], v[108:111]
	v_mfma_f32_16x16x32_bf16 v[92:95], v[132:135], v[206:209], v[92:95]
	v_mfma_f32_16x16x32_bf16 v[88:91], v[140:143], v[206:209], v[88:91]
	v_mfma_f32_16x16x32_bf16 v[76:79], v[132:135], v[214:217], v[76:79]
	v_mfma_f32_16x16x32_bf16 v[72:75], v[140:143], v[214:217], v[72:75]
	v_mfma_f32_16x16x32_bf16 v[112:115], v[144:147], v[160:163], v[112:115]
	v_mfma_f32_16x16x32_bf16 v[104:107], v[152:155], v[160:163], v[104:107]
	v_mfma_f32_16x16x32_bf16 v[100:103], v[144:147], v[184:187], v[100:103]
	v_mfma_f32_16x16x32_bf16 v[96:99], v[152:155], v[184:187], v[96:99]
	v_mfma_f32_16x16x32_bf16 v[84:87], v[144:147], v[192:195], v[84:87]
	v_mfma_f32_16x16x32_bf16 v[80:83], v[152:155], v[192:195], v[80:83]
	v_mfma_f32_16x16x32_bf16 v[68:71], v[144:147], v[210:213], v[68:71]
	v_mfma_f32_16x16x32_bf16 v[64:67], v[152:155], v[210:213], v[64:67]
	v_mfma_f32_16x16x32_bf16 v[112:115], v[148:151], v[164:167], v[112:115]
	v_mfma_f32_16x16x32_bf16 v[104:107], v[156:159], v[164:167], v[104:107]
	v_mfma_f32_16x16x32_bf16 v[100:103], v[148:151], v[188:191], v[100:103]
	v_mfma_f32_16x16x32_bf16 v[96:99], v[156:159], v[188:191], v[96:99]
	v_mfma_f32_16x16x32_bf16 v[84:87], v[148:151], v[206:209], v[84:87]
	v_mfma_f32_16x16x32_bf16 v[80:83], v[156:159], v[206:209], v[80:83]
	v_mfma_f32_16x16x32_bf16 v[68:71], v[148:151], v[214:217], v[68:71]
	v_mfma_f32_16x16x32_bf16 v[64:67], v[156:159], v[214:217], v[64:67]
	s_setprio 0
	s_barrier
	s_add_u32 s98, s46, 0x80
	s_addc_u32 s99, s47, 0
	s_add_i32 s48, s69, s1
	s_mov_b32 m0, s48
	ds_read_b128 v[160:163], v204 offset:49152
	ds_read_b128 v[164:167], v204 offset:50176
	ds_read_b128 v[184:187], v204 offset:51200
	ds_read_b128 v[188:191], v204 offset:52224
	ds_read_b128 v[192:195], v204 offset:53248
	ds_read_b128 v[206:209], v204 offset:54272
	ds_read_b128 v[210:213], v204 offset:55296
	ds_read_b128 v[214:217], v204 offset:56320
	global_load_lds_dwordx4 v170, s[98:99]
	s_add_i32 m0, s48, 0x2000
	s_add_u32 s46, s46, 0x200080
	s_addc_u32 s47, s47, 0
	s_add_i32 s48, s70, s1
	global_load_lds_dwordx4 v174, s[98:99]
	s_mov_b32 m0, s48
	s_nop 0
	global_load_lds_dwordx4 v170, s[46:47]
	s_add_i32 m0, s48, 0x2000
	s_nop 0
	global_load_lds_dwordx4 v174, s[46:47]
	s_mov_b32 m0, s59
	s_nop 0
	global_load_lds_dwordx4 v168, s[100:101]
	s_mov_b32 m0, s60
	s_nop 0
	global_load_lds_dwordx4 v172, s[100:101]
	s_waitcnt vmcnt(8)
	s_waitcnt lgkmcnt(0)
	s_setprio 1
	s_barrier
	v_mfma_f32_16x16x32_bf16 v[60:63], v[128:131], v[160:163], v[60:63]
	v_mfma_f32_16x16x32_bf16 v[56:59], v[136:139], v[160:163], v[56:59]
	v_mfma_f32_16x16x32_bf16 v[44:47], v[128:131], v[184:187], v[44:47]
	v_mfma_f32_16x16x32_bf16 v[40:43], v[136:139], v[184:187], v[40:43]
	v_mfma_f32_16x16x32_bf16 v[28:31], v[128:131], v[192:195], v[28:31]
	v_mfma_f32_16x16x32_bf16 v[24:27], v[136:139], v[192:195], v[24:27]
	v_mfma_f32_16x16x32_bf16 v[12:15], v[128:131], v[210:213], v[12:15]
	v_mfma_f32_16x16x32_bf16 v[8:11], v[136:139], v[210:213], v[8:11]
	v_mfma_f32_16x16x32_bf16 v[60:63], v[132:135], v[164:167], v[60:63]
	v_mfma_f32_16x16x32_bf16 v[56:59], v[140:143], v[164:167], v[56:59]
	v_mfma_f32_16x16x32_bf16 v[44:47], v[132:135], v[188:191], v[44:47]
	v_mfma_f32_16x16x32_bf16 v[40:43], v[140:143], v[188:191], v[40:43]
	v_mfma_f32_16x16x32_bf16 v[28:31], v[132:135], v[206:209], v[28:31]
	v_mfma_f32_16x16x32_bf16 v[24:27], v[140:143], v[206:209], v[24:27]
	v_mfma_f32_16x16x32_bf16 v[12:15], v[132:135], v[214:217], v[12:15]
	v_mfma_f32_16x16x32_bf16 v[8:11], v[140:143], v[214:217], v[8:11]
	v_mfma_f32_16x16x32_bf16 v[52:55], v[144:147], v[160:163], v[52:55]
	v_mfma_f32_16x16x32_bf16 v[48:51], v[152:155], v[160:163], v[48:51]
	v_mfma_f32_16x16x32_bf16 v[36:39], v[144:147], v[184:187], v[36:39]
	v_mfma_f32_16x16x32_bf16 v[32:35], v[152:155], v[184:187], v[32:35]
	v_mfma_f32_16x16x32_bf16 v[20:23], v[144:147], v[192:195], v[20:23]
	v_mfma_f32_16x16x32_bf16 v[16:19], v[152:155], v[192:195], v[16:19]
	v_mfma_f32_16x16x32_bf16 v[4:7], v[144:147], v[210:213], v[4:7]
	v_mfma_f32_16x16x32_bf16 v[0:3], v[152:155], v[210:213], v[0:3]
	v_mfma_f32_16x16x32_bf16 v[52:55], v[148:151], v[164:167], v[52:55]
	v_mfma_f32_16x16x32_bf16 v[48:51], v[156:159], v[164:167], v[48:51]
	v_mfma_f32_16x16x32_bf16 v[36:39], v[148:151], v[188:191], v[36:39]
	v_mfma_f32_16x16x32_bf16 v[32:35], v[156:159], v[188:191], v[32:35]
	v_mfma_f32_16x16x32_bf16 v[20:23], v[148:151], v[206:209], v[20:23]
	v_mfma_f32_16x16x32_bf16 v[16:19], v[156:159], v[206:209], v[16:19]
	v_mfma_f32_16x16x32_bf16 v[4:7], v[148:151], v[214:217], v[4:7]
	v_mfma_f32_16x16x32_bf16 v[0:3], v[156:159], v[214:217], v[0:3]
	s_setprio 0
	s_barrier
	s_add_i32 s68, s68, 2
	s_add_u32 s42, s42, 0x100
	s_addc_u32 s43, s43, 0
	s_add_u32 s66, s66, 0x100
	s_addc_u32 s67, s67, 0
	s_cmpk_gt_u32 s68, 0x7d
	s_cbranch_scc0 .LBB0_1412
	s_and_b64 vcc, exec, s[10:11]
	s_cbranch_vccz .LBB0_1415
	s_barrier
